# hand-written final RMSNorm row loop (gains hoisted, whole row in flight, next row prefetched) + peeled first K-loop iteration with C=0 instead of accumulator zeroing + no pre-K-loop drain
# speedup vs baseline: 1.0027x; 1.0027x over previous
; #define PG8_STAGE(bufoff, gbase, voff) do { _Pragma("unroll") for (int _i = 0; _i < 2; ++_i) \
;         __builtin_amdgcn_global_load_lds((const unsigned*)((const char*)(gbase) + (voff)[_i]), (PG8_LAS unsigned*)(lds + (bufoff) + ldsw + _i * 8192), 16, 0, 0); } while (0)
; #define PG8_LDA(dst, b, h) do { _Pragma("unroll") for (int m = 0; m < 4; ++m) _Pragma("unroll") for (int k = 0; k < 2; ++k) dst[m][k] = *(const PG8_LAS bf16x8*)(lds + PG8_SA(b, h) + aoff + m * 2048 + k * 1024); } while (0)
; #define PG8_LDB(dst, b, h) do { _Pragma("unroll") for (int n = 0; n < 2; ++n) _Pragma("unroll") for (int k = 0; k < 2; ++k) dst[n][k] = *(const PG8_LAS bf16x8*)(lds + PG8_SB(b, h) + boff + n * 2048 + k * 1024); } while (0)
; #define PG8_MMA(ai, bj, At, Bt) do { __builtin_amdgcn_s_setprio(1); _Pragma("unroll") for (int m = 0; m < 4; ++m) _Pragma("unroll") for (int n = 0; n < 2; ++n) _Pragma("unroll") for (int k = 0; k < 2; ++k) \
;         acc[ai][bj][m][n] = __builtin_amdgcn_mfma_f32_16x16x32_bf16(Bt[n][k], At[m][k], acc[ai][bj][m][n], 0, 0, 0); __builtin_amdgcn_s_setprio(0); } while (0)
; #define PG8_WAIT_V(n) asm volatile("s_waitcnt vmcnt(" #n ")" ::: "memory")
; template <class Epi, class Sched, bool ALIGN_EPI = false, bool SP2 = false>
; __device__ __forceinline__ void gemm_phase(PG8_LAS unsigned char* lds, const Gemm g, const Sched& S, const Epi& E, const int tid_in) {
;     ...
;         const char* nA = has_next ? (const char*)g.A + (size_t)nxt.pm * tstep : cA; const char* nB = has_next ? (const char*)g.Bt + (size_t)nxt.pn * tstep : cB;
;         for (int t = 0; t < nt; t += 2) {
;             const bool last = (t == nt - 2);
;             const char* a1 = cA + (size_t)(t + 1) * kstep;
;             const char* a2 = last ? nA : cA + (size_t)(t + 2) * kstep; const char* b2 = last ? nB : cB + (size_t)(t + 2) * kstep;
;             const char* a3 = a2 + kstep; const char* b3 = b2 + kstep;
;             if (last && has_next) S.a_ready(nxt);
;             if constexpr (SP2) {
;             PG8_LDB(B0, 0, 0); PG8_LDB(B1, 0, 1); PG8_SCHED; PG8_LDA(At, 0, 0); PG8_STAGE(PG8_SA(1, 1), a1 + hstep, voffA);
;             PG8_WAIT_V(8); PG8_WAIT_L(0); PG8_BAR; PG8_MMA(0, 0, At, B0); PG8_MMA(0, 1, At, B1); PG8_BAR; PG8_SCHED;
;             PG8_LDA(At, 0, 1); PG8_STAGE(PG8_SB(0, 0), b2, voffB); PG8_STAGE(PG8_SB(0, 1), b2 + hstep, voffB); PG8_STAGE(PG8_SA(0, 0), a2, voffA);
.LBB0_485:
	s_ashr_i32 s55, s54, 31
	s_lshl_b64 s[76:77], s[54:55], 19
	s_add_u32 s78, s36, s76
	s_addc_u32 s79, s37, s77
	s_and_b64 s[76:77], s[4:5], exec
	s_cselect_b32 s7, s79, s75
	s_cselect_b32 s18, s78, s74
	s_ashr_i32 s53, s52, 31
	s_lshl_b64 s[76:77], s[52:53], 19
	s_add_u32 s80, s34, s76
	s_addc_u32 s81, s35, s77
	s_and_b64 s[76:77], s[4:5], exec
	s_cselect_b32 s53, s81, s1
	s_cselect_b32 s55, s80, s0
	s_add_u32 s82, s74, 0x40080
	s_addc_u32 s83, s75, 0
	s_add_u32 s73, s0, 0x100
	v_mov_b32_e32 v0, 0
	s_addc_u32 s76, s1, 0
	s_mov_b32 s77, -2
	ds_read_b128 v[128:131], v174
	ds_read_b128 v[132:135], v174 offset:1024
	ds_read_b128 v[136:139], v174 offset:2048
	ds_read_b128 v[140:143], v174 offset:3072
	ds_read_b128 v[160:163], v175
	ds_read_b128 v[180:183], v175 offset:1024
	ds_read_b128 v[184:187], v175 offset:2048
	ds_read_b128 v[188:191], v175 offset:3072
	s_add_u32 s0, s82, 0xfffc0080
	s_addc_u32 s1, s83, -1
	s_cmp_eq_u32 s77, 12
	s_cselect_b32 s75, s7, s1
	s_cselect_b32 s74, s18, s0
	s_cselect_b32 s1, s53, s76
	s_cselect_b32 s0, s55, s73
	v_lshl_add_u64 v[164:165], s[82:83], 0, v[152:153]
	s_add_i32 m0, s17, 0xc000
	ds_read_b128 v[192:195], v176
	ds_read_b128 v[196:199], v176 offset:1024
	ds_read_b128 v[200:203], v176 offset:2048
	ds_read_b128 v[204:207], v176 offset:3072
	ds_read_b128 v[208:211], v176 offset:4096
	ds_read_b128 v[212:215], v176 offset:5120
	ds_read_b128 v[216:219], v176 offset:6144
	ds_read_b128 v[220:223], v176 offset:7168
	global_load_lds_dwordx4 v[164:165], off
	v_lshl_add_u64 v[164:165], s[82:83], 0, v[154:155]
	s_add_i32 m0, s17, 0xe000
	s_nop 0
	global_load_lds_dwordx4 v[164:165], off
	s_waitcnt vmcnt(8)
	s_waitcnt lgkmcnt(0)
	s_barrier
	s_setprio 1
	s_waitcnt lgkmcnt(0)
	v_mfma_f32_16x16x32_bf16 v[124:127], v[128:131], v[192:195], 0
	v_mfma_f32_16x16x32_bf16 v[120:123], v[136:139], v[192:195], 0
	v_mfma_f32_16x16x32_bf16 v[108:111], v[128:131], v[200:203], 0
	v_mfma_f32_16x16x32_bf16 v[104:107], v[136:139], v[200:203], 0
	v_mfma_f32_16x16x32_bf16 v[92:95], v[128:131], v[208:211], 0
	v_mfma_f32_16x16x32_bf16 v[88:91], v[136:139], v[208:211], 0
	v_mfma_f32_16x16x32_bf16 v[76:79], v[128:131], v[216:219], 0
	v_mfma_f32_16x16x32_bf16 v[72:75], v[136:139], v[216:219], 0
	v_mfma_f32_16x16x32_bf16 v[124:127], v[132:135], v[196:199], v[124:127]
	v_mfma_f32_16x16x32_bf16 v[120:123], v[140:143], v[196:199], v[120:123]
	v_mfma_f32_16x16x32_bf16 v[108:111], v[132:135], v[204:207], v[108:111]
	v_mfma_f32_16x16x32_bf16 v[104:107], v[140:143], v[204:207], v[104:107]
	v_mfma_f32_16x16x32_bf16 v[92:95], v[132:135], v[212:215], v[92:95]
	v_mfma_f32_16x16x32_bf16 v[88:91], v[140:143], v[212:215], v[88:91]
	v_mfma_f32_16x16x32_bf16 v[76:79], v[132:135], v[220:223], v[76:79]
	v_mfma_f32_16x16x32_bf16 v[72:75], v[140:143], v[220:223], v[72:75]
	s_setprio 0
	s_setprio 1
	v_mfma_f32_16x16x32_bf16 v[116:119], v[160:163], v[192:195], 0
	v_mfma_f32_16x16x32_bf16 v[112:115], v[184:187], v[192:195], 0
	v_mfma_f32_16x16x32_bf16 v[100:103], v[160:163], v[200:203], 0
	v_mfma_f32_16x16x32_bf16 v[96:99], v[184:187], v[200:203], 0
	v_mfma_f32_16x16x32_bf16 v[84:87], v[160:163], v[208:211], 0
	v_mfma_f32_16x16x32_bf16 v[80:83], v[184:187], v[208:211], 0
	v_mfma_f32_16x16x32_bf16 v[68:71], v[160:163], v[216:219], 0
	v_mfma_f32_16x16x32_bf16 v[64:67], v[184:187], v[216:219], 0
	v_mfma_f32_16x16x32_bf16 v[116:119], v[180:183], v[196:199], v[116:119]
	v_mfma_f32_16x16x32_bf16 v[112:115], v[188:191], v[196:199], v[112:115]
	v_mfma_f32_16x16x32_bf16 v[100:103], v[180:183], v[204:207], v[100:103]
	v_mfma_f32_16x16x32_bf16 v[96:99], v[188:191], v[204:207], v[96:99]
	v_mfma_f32_16x16x32_bf16 v[84:87], v[180:183], v[212:215], v[84:87]
	v_mfma_f32_16x16x32_bf16 v[80:83], v[188:191], v[212:215], v[80:83]
	v_mfma_f32_16x16x32_bf16 v[68:71], v[180:183], v[220:223], v[68:71]
	v_mfma_f32_16x16x32_bf16 v[64:67], v[188:191], v[220:223], v[64:67]
	s_setprio 0
	s_barrier
	s_add_i32 s84, s47, s2
	v_lshl_add_u64 v[164:165], s[0:1], 0, v[146:147]
	s_mov_b32 m0, s84
	ds_read_b128 v[192:195], v176 offset:16384
	ds_read_b128 v[196:199], v176 offset:17408
	ds_read_b128 v[200:203], v176 offset:18432
	ds_read_b128 v[204:207], v176 offset:19456
	ds_read_b128 v[208:211], v176 offset:20480
	ds_read_b128 v[212:215], v176 offset:21504
	ds_read_b128 v[216:219], v176 offset:22528
	ds_read_b128 v[220:223], v176 offset:23552
	global_load_lds_dwordx4 v[164:165], off
	s_add_i32 m0, s84, 0x2000
	s_add_u32 s84, s0, 0x40000
	v_lshl_add_u64 v[224:225], s[0:1], 0, v[150:151]
	s_addc_u32 s85, s1, 0
	s_add_i32 s86, s48, s2
	global_load_lds_dwordx4 v[224:225], off
	v_lshl_add_u64 v[226:227], s[84:85], 0, v[146:147]
	s_mov_b32 m0, s86
	v_lshl_add_u64 v[228:229], s[74:75], 0, v[148:149]
	global_load_lds_dwordx4 v[226:227], off
	v_lshl_add_u64 v[226:227], s[84:85], 0, v[150:151]
	s_add_i32 m0, s86, 0x2000
	s_nop 0
	global_load_lds_dwordx4 v[226:227], off
	v_lshl_add_u64 v[226:227], s[74:75], 0, v[144:145]
	s_mov_b32 m0, s17
	s_nop 0
	global_load_lds_dwordx4 v[226:227], off
	s_mov_b32 m0, s38
	s_nop 0
	global_load_lds_dwordx4 v[228:229], off
	s_waitcnt vmcnt(8)
	s_waitcnt lgkmcnt(0)
	s_barrier
; #define PG8_STAGE(bufoff, gbase, voff) do { _Pragma("unroll") for (int _i = 0; _i < 2; ++_i) \
;         __builtin_amdgcn_global_load_lds((const unsigned*)((const char*)(gbase) + (voff)[_i]), (PG8_LAS unsigned*)(lds + (bufoff) + ldsw + _i * 8192), 16, 0, 0); } while (0)
; #define PG8_LDA(dst, b, h) do { _Pragma("unroll") for (int m = 0; m < 4; ++m) _Pragma("unroll") for (int k = 0; k < 2; ++k) dst[m][k] = *(const PG8_LAS bf16x8*)(lds + PG8_SA(b, h) + aoff + m * 2048 + k * 1024); } while (0)
; #define PG8_LDB(dst, b, h) do { _Pragma("unroll") for (int n = 0; n < 2; ++n) _Pragma("unroll") for (int k = 0; k < 2; ++k) dst[n][k] = *(const PG8_LAS bf16x8*)(lds + PG8_SB(b, h) + boff + n * 2048 + k * 1024); } while (0)
; #define PG8_MMA(ai, bj, At, Bt) do { __builtin_amdgcn_s_setprio(1); _Pragma("unroll") for (int m = 0; m < 4; ++m) _Pragma("unroll") for (int n = 0; n < 2; ++n) _Pragma("unroll") for (int k = 0; k < 2; ++k) \
;         acc[ai][bj][m][n] = __builtin_amdgcn_mfma_f32_16x16x32_bf16(Bt[n][k], At[m][k], acc[ai][bj][m][n], 0, 0, 0); __builtin_amdgcn_s_setprio(0); } while (0)
; #define PG8_WAIT_V(n) asm volatile("s_waitcnt vmcnt(" #n ")" ::: "memory")
; #define PG8_WAIT_L(n) asm volatile("s_waitcnt lgkmcnt(" #n ")" ::: "memory")
; #define PG8_BAR __builtin_amdgcn_s_barrier()
; #define PG8_SCHED __builtin_amdgcn_sched_barrier(0)
; template <class Epi, class Sched, bool ALIGN_EPI = false, bool SP2 = false>
; __device__ __forceinline__ void gemm_phase(PG8_LAS unsigned char* lds, const Gemm g, const Sched& S, const Epi& E, const int tid_in) {
;     ...
;             PG8_WAIT_V(8); PG8_WAIT_L(0); PG8_BAR; PG8_MMA(1, 0, At, B0); PG8_MMA(1, 1, At, B1); PG8_BAR; PG8_SCHED;
;             PG8_LDB(B0, 1, 0); PG8_LDB(B1, 1, 1); PG8_SCHED; PG8_LDA(At, 1, 0); PG8_STAGE(PG8_SA(0, 1), a2 + hstep, voffA);
;             PG8_WAIT_V(8); PG8_WAIT_L(0); PG8_BAR; PG8_MMA(0, 0, At, B0); PG8_MMA(0, 1, At, B1); PG8_BAR; PG8_SCHED;
	s_setprio 1
	s_waitcnt lgkmcnt(0)
	v_mfma_f32_16x16x32_bf16 v[60:63], v[128:131], v[192:195], 0
	v_mfma_f32_16x16x32_bf16 v[56:59], v[136:139], v[192:195], 0
	v_mfma_f32_16x16x32_bf16 v[44:47], v[128:131], v[200:203], 0
	v_mfma_f32_16x16x32_bf16 v[40:43], v[136:139], v[200:203], 0
	v_mfma_f32_16x16x32_bf16 v[28:31], v[128:131], v[208:211], 0
	v_mfma_f32_16x16x32_bf16 v[24:27], v[136:139], v[208:211], 0
	v_mfma_f32_16x16x32_bf16 v[12:15], v[128:131], v[216:219], 0
	v_mfma_f32_16x16x32_bf16 v[8:11], v[136:139], v[216:219], 0
	v_mfma_f32_16x16x32_bf16 v[60:63], v[132:135], v[196:199], v[60:63]
	v_mfma_f32_16x16x32_bf16 v[56:59], v[140:143], v[196:199], v[56:59]
	v_mfma_f32_16x16x32_bf16 v[44:47], v[132:135], v[204:207], v[44:47]
	v_mfma_f32_16x16x32_bf16 v[40:43], v[140:143], v[204:207], v[40:43]
	v_mfma_f32_16x16x32_bf16 v[28:31], v[132:135], v[212:215], v[28:31]
	v_mfma_f32_16x16x32_bf16 v[24:27], v[140:143], v[212:215], v[24:27]
	v_mfma_f32_16x16x32_bf16 v[12:15], v[132:135], v[220:223], v[12:15]
	v_mfma_f32_16x16x32_bf16 v[8:11], v[140:143], v[220:223], v[8:11]
	s_setprio 0
	s_setprio 1
	v_mfma_f32_16x16x32_bf16 v[52:55], v[160:163], v[192:195], 0
	v_mfma_f32_16x16x32_bf16 v[48:51], v[184:187], v[192:195], 0
	v_mfma_f32_16x16x32_bf16 v[36:39], v[160:163], v[200:203], 0
	v_mfma_f32_16x16x32_bf16 v[32:35], v[184:187], v[200:203], 0
	v_mfma_f32_16x16x32_bf16 v[20:23], v[160:163], v[208:211], 0
	v_mfma_f32_16x16x32_bf16 v[16:19], v[184:187], v[208:211], 0
	v_mfma_f32_16x16x32_bf16 v[4:7], v[160:163], v[216:219], 0
	v_mfma_f32_16x16x32_bf16 v[0:3], v[184:187], v[216:219], 0
	v_mfma_f32_16x16x32_bf16 v[52:55], v[180:183], v[196:199], v[52:55]
	v_mfma_f32_16x16x32_bf16 v[48:51], v[188:191], v[196:199], v[48:51]
	v_mfma_f32_16x16x32_bf16 v[36:39], v[180:183], v[204:207], v[36:39]
	v_mfma_f32_16x16x32_bf16 v[32:35], v[188:191], v[204:207], v[32:35]
	v_mfma_f32_16x16x32_bf16 v[20:23], v[180:183], v[212:215], v[20:23]
	v_mfma_f32_16x16x32_bf16 v[16:19], v[188:191], v[212:215], v[16:19]
	v_mfma_f32_16x16x32_bf16 v[4:7], v[180:183], v[220:223], v[4:7]
	v_mfma_f32_16x16x32_bf16 v[0:3], v[188:191], v[220:223], v[0:3]
	s_setprio 0
	s_barrier
	s_add_i32 s84, 0, 0x18000
	s_add_i32 s85, 0, 0x1c000
	v_add_u32_e32 v140, s84, v168
	v_add_u32_e32 v179, s85, v168
	ds_read_b128 v[128:131], v140
	ds_read_b128 v[132:135], v140 offset:1024
	ds_read_b128 v[136:139], v140 offset:2048
	ds_read_b128 v[140:143], v140 offset:3072
	ds_read_b128 v[160:163], v179
	ds_read_b128 v[180:183], v179 offset:1024
	ds_read_b128 v[184:187], v179 offset:2048
	ds_read_b128 v[188:191], v179 offset:3072
	s_add_u32 s74, s74, 0x40000
	s_addc_u32 s75, s75, 0
	s_mov_b32 m0, s39
	v_lshl_add_u64 v[230:231], s[74:75], 0, v[144:145]
	ds_read_b128 v[192:195], v176 offset:32768
	ds_read_b128 v[196:199], v176 offset:33792
	ds_read_b128 v[200:203], v176 offset:34816
	ds_read_b128 v[204:207], v176 offset:35840
	ds_read_b128 v[208:211], v176 offset:36864
	ds_read_b128 v[212:215], v176 offset:37888
	ds_read_b128 v[216:219], v176 offset:38912
	ds_read_b128 v[220:223], v176 offset:39936
	global_load_lds_dwordx4 v[230:231], off
	v_lshl_add_u64 v[230:231], s[74:75], 0, v[148:149]
	s_mov_b32 m0, s40
	s_nop 0
	global_load_lds_dwordx4 v[230:231], off
	s_waitcnt vmcnt(8)
	s_waitcnt lgkmcnt(0)
	s_barrier
	s_setprio 1
	s_waitcnt lgkmcnt(0)
	v_mfma_f32_16x16x32_bf16 v[124:127], v[128:131], v[192:195], v[124:127]
	v_mfma_f32_16x16x32_bf16 v[120:123], v[136:139], v[192:195], v[120:123]
	v_mfma_f32_16x16x32_bf16 v[108:111], v[128:131], v[200:203], v[108:111]
	v_mfma_f32_16x16x32_bf16 v[104:107], v[136:139], v[200:203], v[104:107]
	v_mfma_f32_16x16x32_bf16 v[92:95], v[128:131], v[208:211], v[92:95]
	v_mfma_f32_16x16x32_bf16 v[88:91], v[136:139], v[208:211], v[88:91]
	v_mfma_f32_16x16x32_bf16 v[76:79], v[128:131], v[216:219], v[76:79]
	v_mfma_f32_16x16x32_bf16 v[72:75], v[136:139], v[216:219], v[72:75]
	v_mfma_f32_16x16x32_bf16 v[124:127], v[132:135], v[196:199], v[124:127]
	v_mfma_f32_16x16x32_bf16 v[120:123], v[140:143], v[196:199], v[120:123]
	v_mfma_f32_16x16x32_bf16 v[108:111], v[132:135], v[204:207], v[108:111]
	v_mfma_f32_16x16x32_bf16 v[104:107], v[140:143], v[204:207], v[104:107]
	v_mfma_f32_16x16x32_bf16 v[92:95], v[132:135], v[212:215], v[92:95]
	v_mfma_f32_16x16x32_bf16 v[88:91], v[140:143], v[212:215], v[88:91]
	v_mfma_f32_16x16x32_bf16 v[76:79], v[132:135], v[220:223], v[76:79]
	v_mfma_f32_16x16x32_bf16 v[72:75], v[140:143], v[220:223], v[72:75]
	s_setprio 0
	s_setprio 1
	v_mfma_f32_16x16x32_bf16 v[116:119], v[160:163], v[192:195], v[116:119]
	v_mfma_f32_16x16x32_bf16 v[112:115], v[184:187], v[192:195], v[112:115]
	v_mfma_f32_16x16x32_bf16 v[100:103], v[160:163], v[200:203], v[100:103]
	v_mfma_f32_16x16x32_bf16 v[96:99], v[184:187], v[200:203], v[96:99]
	v_mfma_f32_16x16x32_bf16 v[84:87], v[160:163], v[208:211], v[84:87]
	v_mfma_f32_16x16x32_bf16 v[80:83], v[184:187], v[208:211], v[80:83]
	v_mfma_f32_16x16x32_bf16 v[68:71], v[160:163], v[216:219], v[68:71]
	v_mfma_f32_16x16x32_bf16 v[64:67], v[184:187], v[216:219], v[64:67]
	v_mfma_f32_16x16x32_bf16 v[116:119], v[180:183], v[196:199], v[116:119]
	v_mfma_f32_16x16x32_bf16 v[112:115], v[188:191], v[196:199], v[112:115]
	v_mfma_f32_16x16x32_bf16 v[100:103], v[180:183], v[204:207], v[100:103]
	v_mfma_f32_16x16x32_bf16 v[96:99], v[188:191], v[204:207], v[96:99]
	v_mfma_f32_16x16x32_bf16 v[84:87], v[180:183], v[212:215], v[84:87]
	v_mfma_f32_16x16x32_bf16 v[80:83], v[188:191], v[212:215], v[80:83]
	v_mfma_f32_16x16x32_bf16 v[68:71], v[180:183], v[220:223], v[68:71]
	v_mfma_f32_16x16x32_bf16 v[64:67], v[188:191], v[220:223], v[64:67]
	s_setprio 0
	s_barrier
; #define PG8_STAGE(bufoff, gbase, voff) do { _Pragma("unroll") for (int _i = 0; _i < 2; ++_i) \
;         __builtin_amdgcn_global_load_lds((const unsigned*)((const char*)(gbase) + (voff)[_i]), (PG8_LAS unsigned*)(lds + (bufoff) + ldsw + _i * 8192), 16, 0, 0); } while (0)
; #define PG8_LDA(dst, b, h) do { _Pragma("unroll") for (int m = 0; m < 4; ++m) _Pragma("unroll") for (int k = 0; k < 2; ++k) dst[m][k] = *(const PG8_LAS bf16x8*)(lds + PG8_SA(b, h) + aoff + m * 2048 + k * 1024); } while (0)
; #define PG8_MMA(ai, bj, At, Bt) do { __builtin_amdgcn_s_setprio(1); _Pragma("unroll") for (int m = 0; m < 4; ++m) _Pragma("unroll") for (int n = 0; n < 2; ++n) _Pragma("unroll") for (int k = 0; k < 2; ++k) \
;         acc[ai][bj][m][n] = __builtin_amdgcn_mfma_f32_16x16x32_bf16(Bt[n][k], At[m][k], acc[ai][bj][m][n], 0, 0, 0); __builtin_amdgcn_s_setprio(0); } while (0)
; #define PG8_WAIT_V(n) asm volatile("s_waitcnt vmcnt(" #n ")" ::: "memory")
; #define PG8_WAIT_L(n) asm volatile("s_waitcnt lgkmcnt(" #n ")" ::: "memory")
; #define PG8_BAR __builtin_amdgcn_s_barrier()
; #define PG8_SCHED __builtin_amdgcn_sched_barrier(0)
; template <class Epi, class Sched, bool ALIGN_EPI = false, bool SP2 = false>
; __device__ __forceinline__ void gemm_phase(PG8_LAS unsigned char* lds, const Gemm g, const Sched& S, const Epi& E, const int tid_in) {
;     ...
;             PG8_LDA(At, 1, 1); PG8_STAGE(PG8_SB(1, 0), b3, voffB); PG8_STAGE(PG8_SB(1, 1), b3 + hstep, voffB); PG8_STAGE(PG8_SA(1, 0), a3, voffA);
;             PG8_WAIT_V(8); PG8_WAIT_L(0); PG8_BAR; PG8_MMA(1, 0, At, B0); PG8_MMA(1, 1, At, B1); PG8_BAR; PG8_SCHED;
	s_add_i32 s74, s84, s2
	v_lshl_add_u64 v[164:165], v[164:165], 0, s[28:29]
	s_mov_b32 m0, s74
	ds_read_b128 v[192:195], v176 offset:49152
	ds_read_b128 v[196:199], v176 offset:50176
	ds_read_b128 v[200:203], v176 offset:51200
	ds_read_b128 v[204:207], v176 offset:52224
	ds_read_b128 v[208:211], v176 offset:53248
	ds_read_b128 v[212:215], v176 offset:54272
	ds_read_b128 v[216:219], v176 offset:55296
	ds_read_b128 v[220:223], v176 offset:56320
	global_load_lds_dwordx4 v[164:165], off
	s_add_i32 m0, s74, 0x2000
	s_add_u32 s0, s0, 0x40080
	v_lshl_add_u64 v[164:165], v[224:225], 0, s[28:29]
	s_addc_u32 s1, s1, 0
	s_add_i32 s74, s85, s2
	global_load_lds_dwordx4 v[164:165], off
	v_lshl_add_u64 v[164:165], s[0:1], 0, v[146:147]
	s_mov_b32 m0, s74
	s_nop 0
	global_load_lds_dwordx4 v[164:165], off
	v_lshl_add_u64 v[164:165], s[0:1], 0, v[150:151]
	s_add_i32 m0, s74, 0x2000
	s_nop 0
	global_load_lds_dwordx4 v[164:165], off
	v_lshl_add_u64 v[164:165], v[226:227], 0, s[28:29]
	s_mov_b32 m0, s43
	s_nop 0
	global_load_lds_dwordx4 v[164:165], off
	v_lshl_add_u64 v[164:165], v[228:229], 0, s[28:29]
	s_mov_b32 m0, s44
	s_nop 0
	global_load_lds_dwordx4 v[164:165], off
	s_waitcnt vmcnt(8)
	s_waitcnt lgkmcnt(0)
	s_barrier
	s_setprio 1
	s_waitcnt lgkmcnt(0)
	v_mfma_f32_16x16x32_bf16 v[60:63], v[128:131], v[192:195], v[60:63]
	v_mfma_f32_16x16x32_bf16 v[56:59], v[136:139], v[192:195], v[56:59]
	v_mfma_f32_16x16x32_bf16 v[44:47], v[128:131], v[200:203], v[44:47]
	v_mfma_f32_16x16x32_bf16 v[40:43], v[136:139], v[200:203], v[40:43]
	v_mfma_f32_16x16x32_bf16 v[28:31], v[128:131], v[208:211], v[28:31]
	v_mfma_f32_16x16x32_bf16 v[24:27], v[136:139], v[208:211], v[24:27]
	v_mfma_f32_16x16x32_bf16 v[12:15], v[128:131], v[216:219], v[12:15]
	v_mfma_f32_16x16x32_bf16 v[8:11], v[136:139], v[216:219], v[8:11]
	v_mfma_f32_16x16x32_bf16 v[60:63], v[132:135], v[196:199], v[60:63]
	v_mfma_f32_16x16x32_bf16 v[56:59], v[140:143], v[196:199], v[56:59]
	v_mfma_f32_16x16x32_bf16 v[44:47], v[132:135], v[204:207], v[44:47]
	v_mfma_f32_16x16x32_bf16 v[40:43], v[140:143], v[204:207], v[40:43]
	v_mfma_f32_16x16x32_bf16 v[28:31], v[132:135], v[212:215], v[28:31]
	v_mfma_f32_16x16x32_bf16 v[24:27], v[140:143], v[212:215], v[24:27]
	v_mfma_f32_16x16x32_bf16 v[12:15], v[132:135], v[220:223], v[12:15]
	v_mfma_f32_16x16x32_bf16 v[8:11], v[140:143], v[220:223], v[8:11]
	s_setprio 0
	s_setprio 1
	v_mfma_f32_16x16x32_bf16 v[52:55], v[160:163], v[192:195], v[52:55]
	v_mfma_f32_16x16x32_bf16 v[48:51], v[184:187], v[192:195], v[48:51]
	v_mfma_f32_16x16x32_bf16 v[36:39], v[160:163], v[200:203], v[36:39]
	v_mfma_f32_16x16x32_bf16 v[32:35], v[184:187], v[200:203], v[32:35]
	v_mfma_f32_16x16x32_bf16 v[20:23], v[160:163], v[208:211], v[20:23]
	v_mfma_f32_16x16x32_bf16 v[16:19], v[184:187], v[208:211], v[16:19]
	v_mfma_f32_16x16x32_bf16 v[4:7], v[160:163], v[216:219], v[4:7]
	v_mfma_f32_16x16x32_bf16 v[0:3], v[184:187], v[216:219], v[0:3]
	v_mfma_f32_16x16x32_bf16 v[52:55], v[180:183], v[196:199], v[52:55]
	v_mfma_f32_16x16x32_bf16 v[48:51], v[188:191], v[196:199], v[48:51]
	v_mfma_f32_16x16x32_bf16 v[36:39], v[180:183], v[204:207], v[36:39]
	v_mfma_f32_16x16x32_bf16 v[32:35], v[188:191], v[204:207], v[32:35]
	v_mfma_f32_16x16x32_bf16 v[20:23], v[180:183], v[212:215], v[20:23]
	v_mfma_f32_16x16x32_bf16 v[16:19], v[188:191], v[212:215], v[16:19]
	v_mfma_f32_16x16x32_bf16 v[4:7], v[180:183], v[220:223], v[4:7]
	v_mfma_f32_16x16x32_bf16 v[0:3], v[188:191], v[220:223], v[0:3]
	s_setprio 0
	s_barrier
	s_add_i32 s77, s77, 2
	s_add_u32 s82, s82, 0x100
	s_addc_u32 s83, s83, 0
	s_add_u32 s73, s73, 0x100
	s_addc_u32 s76, s76, 0
	s_cmp_gt_u32 s77, 13
	s_cbranch_scc0 .LBB0_486
	s_branch .Lmy_kdone_1

; #define PG8_BAR __builtin_amdgcn_s_barrier()
; template <class Epi, class Sched, bool ALIGN_EPI = false, bool SP2 = false>
; __device__ __forceinline__ void gemm_phase(PG8_LAS unsigned char* lds, const Gemm g, const Sched& S, const Epi& E, const int tid_in) {
;     ...
;         if constexpr (ALIGN_EPI) { if (wr == 0) PG8_BAR; }
.Lmy_kdone_1:
	s_and_b64 vcc, exec, s[30:31]
	s_cbranch_vccz .LBB0_489
	s_barrier

; #define PG8_STAGE(bufoff, gbase, voff) do { _Pragma("unroll") for (int _i = 0; _i < 2; ++_i) \
;         __builtin_amdgcn_global_load_lds((const unsigned*)((const char*)(gbase) + (voff)[_i]), (PG8_LAS unsigned*)(lds + (bufoff) + ldsw + _i * 8192), 16, 0, 0); } while (0)
; #define PG8_LDA(dst, b, h) do { _Pragma("unroll") for (int m = 0; m < 4; ++m) _Pragma("unroll") for (int k = 0; k < 2; ++k) dst[m][k] = *(const PG8_LAS bf16x8*)(lds + PG8_SA(b, h) + aoff + m * 2048 + k * 1024); } while (0)
; #define PG8_LDB(dst, b, h) do { _Pragma("unroll") for (int n = 0; n < 2; ++n) _Pragma("unroll") for (int k = 0; k < 2; ++k) dst[n][k] = *(const PG8_LAS bf16x8*)(lds + PG8_SB(b, h) + boff + n * 2048 + k * 1024); } while (0)
; #define PG8_MMA(ai, bj, At, Bt) do { __builtin_amdgcn_s_setprio(1); _Pragma("unroll") for (int m = 0; m < 4; ++m) _Pragma("unroll") for (int n = 0; n < 2; ++n) _Pragma("unroll") for (int k = 0; k < 2; ++k) \
;         acc[ai][bj][m][n] = __builtin_amdgcn_mfma_f32_16x16x32_bf16(Bt[n][k], At[m][k], acc[ai][bj][m][n], 0, 0, 0); __builtin_amdgcn_s_setprio(0); } while (0)
; #define PG8_WAIT_V(n) asm volatile("s_waitcnt vmcnt(" #n ")" ::: "memory")
; template <class Epi, class Sched, bool ALIGN_EPI = false, bool SP2 = false>
; __device__ __forceinline__ void gemm_phase(PG8_LAS unsigned char* lds, const Gemm g, const Sched& S, const Epi& E, const int tid_in) {
;     ...
;         const char* nA = has_next ? (const char*)g.A + (size_t)nxt.pm * tstep : cA; const char* nB = has_next ? (const char*)g.Bt + (size_t)nxt.pn * tstep : cB;
;         for (int t = 0; t < nt; t += 2) {
;             const bool last = (t == nt - 2);
;             const char* a1 = cA + (size_t)(t + 1) * kstep;
;             const char* a2 = last ? nA : cA + (size_t)(t + 2) * kstep; const char* b2 = last ? nB : cB + (size_t)(t + 2) * kstep;
;             const char* a3 = a2 + kstep; const char* b3 = b2 + kstep;
;             if (last && has_next) S.a_ready(nxt);
;             if constexpr (SP2) {
;             PG8_LDB(B0, 0, 0); PG8_LDB(B1, 0, 1); PG8_SCHED; PG8_LDA(At, 0, 0); PG8_STAGE(PG8_SA(1, 1), a1 + hstep, voffA);
;             PG8_WAIT_V(8); PG8_WAIT_L(0); PG8_BAR; PG8_MMA(0, 0, At, B0); PG8_MMA(0, 1, At, B1); PG8_BAR; PG8_SCHED;
;             PG8_LDA(At, 0, 1); PG8_STAGE(PG8_SB(0, 0), b2, voffB); PG8_STAGE(PG8_SB(0, 1), b2 + hstep, voffB); PG8_STAGE(PG8_SA(0, 0), a2, voffA);
.LBB0_688:
	s_ashr_i32 s43, s42, 31
	s_lshl_b64 s[44:45], s[42:43], 19
	s_add_u32 s44, s22, s44
	s_addc_u32 s45, s23, s45
	s_and_b64 s[46:47], s[6:7], exec
	s_cselect_b32 s43, s45, s1
	s_cselect_b32 s53, s44, s0
	s_ashr_i32 s41, s40, 31
	s_lshl_b64 s[46:47], s[40:41], 19
	s_add_u32 s46, s8, s46
	s_addc_u32 s47, s9, s47
	s_and_b64 s[54:55], s[6:7], exec
	s_cselect_b32 s41, s47, s57
	s_cselect_b32 s73, s46, s56
	s_add_u32 s54, s0, 0x40080
	s_addc_u32 s55, s1, 0
	s_add_u32 s74, s56, 0x100
	v_mov_b32_e32 v0, 0
	s_addc_u32 s75, s57, 0
	s_mov_b32 s76, -2
	ds_read_b128 v[92:95], v207
	ds_read_b128 v[100:103], v207 offset:1024
	ds_read_b128 v[112:115], v207 offset:2048
	ds_read_b128 v[124:127], v207 offset:3072
	ds_read_b128 v[136:139], v208
	ds_read_b128 v[148:151], v208 offset:1024
	ds_read_b128 v[152:155], v208 offset:2048
	ds_read_b128 v[156:159], v208 offset:3072
	s_add_u32 s0, s54, 0xfffc0080
	s_addc_u32 s1, s55, -1
	s_cmp_eq_u32 s76, 12
	s_cselect_b32 s57, s43, s1
	s_cselect_b32 s56, s53, s0
	s_cselect_b32 s1, s41, s75
	s_cselect_b32 s0, s73, s74
	v_lshl_add_u64 v[214:215], s[54:55], 0, v[192:193]
	s_add_i32 m0, s30, 0xc000
	ds_read_b128 v[160:163], v209
	ds_read_b128 v[164:167], v209 offset:1024
	ds_read_b128 v[168:171], v209 offset:2048
	ds_read_b128 v[172:175], v209 offset:3072
	ds_read_b128 v[176:179], v209 offset:4096
	ds_read_b128 v[180:183], v209 offset:5120
	ds_read_b128 v[200:203], v209 offset:6144
	ds_read_b128 v[210:213], v209 offset:7168
	global_load_lds_dwordx4 v[214:215], off
	v_lshl_add_u64 v[214:215], s[54:55], 0, v[194:195]
	s_add_i32 m0, s30, 0xe000
	s_nop 0
	global_load_lds_dwordx4 v[214:215], off
	s_waitcnt vmcnt(8)
	s_waitcnt lgkmcnt(0)
	s_barrier
	s_setprio 1
	s_waitcnt lgkmcnt(0)
	v_mfma_f32_16x16x32_bf16 v[144:147], v[92:95], v[160:163], 0
	v_mfma_f32_16x16x32_bf16 v[140:143], v[112:115], v[160:163], 0
	v_mfma_f32_16x16x32_bf16 v[120:123], v[92:95], v[168:171], 0
	v_mfma_f32_16x16x32_bf16 v[116:119], v[112:115], v[168:171], 0
	v_mfma_f32_16x16x32_bf16 v[96:99], v[92:95], v[176:179], 0
	v_mfma_f32_16x16x32_bf16 v[88:91], v[112:115], v[176:179], 0
	v_mfma_f32_16x16x32_bf16 v[76:79], v[92:95], v[200:203], 0
	v_mfma_f32_16x16x32_bf16 v[72:75], v[112:115], v[200:203], 0
	v_mfma_f32_16x16x32_bf16 v[144:147], v[100:103], v[164:167], v[144:147]
	v_mfma_f32_16x16x32_bf16 v[140:143], v[124:127], v[164:167], v[140:143]
	v_mfma_f32_16x16x32_bf16 v[120:123], v[100:103], v[172:175], v[120:123]
	v_mfma_f32_16x16x32_bf16 v[116:119], v[124:127], v[172:175], v[116:119]
	v_mfma_f32_16x16x32_bf16 v[96:99], v[100:103], v[180:183], v[96:99]
	v_mfma_f32_16x16x32_bf16 v[88:91], v[124:127], v[180:183], v[88:91]
	v_mfma_f32_16x16x32_bf16 v[76:79], v[100:103], v[210:213], v[76:79]
	v_mfma_f32_16x16x32_bf16 v[72:75], v[124:127], v[210:213], v[72:75]
	s_setprio 0
	s_setprio 1
	v_mfma_f32_16x16x32_bf16 v[132:135], v[136:139], v[160:163], 0
	v_mfma_f32_16x16x32_bf16 v[128:131], v[152:155], v[160:163], 0
	v_mfma_f32_16x16x32_bf16 v[108:111], v[136:139], v[168:171], 0
	v_mfma_f32_16x16x32_bf16 v[104:107], v[152:155], v[168:171], 0
	v_mfma_f32_16x16x32_bf16 v[84:87], v[136:139], v[176:179], 0
	v_mfma_f32_16x16x32_bf16 v[80:83], v[152:155], v[176:179], 0
	v_mfma_f32_16x16x32_bf16 v[68:71], v[136:139], v[200:203], 0
	v_mfma_f32_16x16x32_bf16 v[64:67], v[152:155], v[200:203], 0
	v_mfma_f32_16x16x32_bf16 v[132:135], v[148:151], v[164:167], v[132:135]
	v_mfma_f32_16x16x32_bf16 v[128:131], v[156:159], v[164:167], v[128:131]
	v_mfma_f32_16x16x32_bf16 v[108:111], v[148:151], v[172:175], v[108:111]
	v_mfma_f32_16x16x32_bf16 v[104:107], v[156:159], v[172:175], v[104:107]
	v_mfma_f32_16x16x32_bf16 v[84:87], v[148:151], v[180:183], v[84:87]
	v_mfma_f32_16x16x32_bf16 v[80:83], v[156:159], v[180:183], v[80:83]
	v_mfma_f32_16x16x32_bf16 v[68:71], v[148:151], v[210:213], v[68:71]
	v_mfma_f32_16x16x32_bf16 v[64:67], v[156:159], v[210:213], v[64:67]
	s_setprio 0
	s_barrier
	s_add_i32 s77, s49, s2
	v_lshl_add_u64 v[214:215], s[0:1], 0, v[186:187]
	s_mov_b32 m0, s77
	ds_read_b128 v[160:163], v209 offset:16384
	ds_read_b128 v[164:167], v209 offset:17408
	ds_read_b128 v[168:171], v209 offset:18432
	ds_read_b128 v[172:175], v209 offset:19456
	ds_read_b128 v[176:179], v209 offset:20480
	ds_read_b128 v[180:183], v209 offset:21504
	ds_read_b128 v[200:203], v209 offset:22528
	ds_read_b128 v[210:213], v209 offset:23552
	global_load_lds_dwordx4 v[214:215], off
	s_add_i32 m0, s77, 0x2000
	s_add_u32 s78, s0, 0x40000
	v_lshl_add_u64 v[216:217], s[0:1], 0, v[190:191]
	s_addc_u32 s79, s1, 0
	s_add_i32 s77, s50, s2
	global_load_lds_dwordx4 v[216:217], off
	v_lshl_add_u64 v[218:219], s[78:79], 0, v[186:187]
	s_mov_b32 m0, s77
	v_lshl_add_u64 v[220:221], s[56:57], 0, v[188:189]
	global_load_lds_dwordx4 v[218:219], off
	v_lshl_add_u64 v[218:219], s[78:79], 0, v[190:191]
	s_add_i32 m0, s77, 0x2000
	s_nop 0
	global_load_lds_dwordx4 v[218:219], off
	v_lshl_add_u64 v[218:219], s[56:57], 0, v[184:185]
	s_mov_b32 m0, s30
	s_nop 0
	global_load_lds_dwordx4 v[218:219], off
	s_mov_b32 m0, s31
	s_nop 0
	global_load_lds_dwordx4 v[220:221], off
	s_waitcnt vmcnt(8)
	s_waitcnt lgkmcnt(0)
	s_barrier
; #define PG8_STAGE(bufoff, gbase, voff) do { _Pragma("unroll") for (int _i = 0; _i < 2; ++_i) \
;         __builtin_amdgcn_global_load_lds((const unsigned*)((const char*)(gbase) + (voff)[_i]), (PG8_LAS unsigned*)(lds + (bufoff) + ldsw + _i * 8192), 16, 0, 0); } while (0)
; #define PG8_LDA(dst, b, h) do { _Pragma("unroll") for (int m = 0; m < 4; ++m) _Pragma("unroll") for (int k = 0; k < 2; ++k) dst[m][k] = *(const PG8_LAS bf16x8*)(lds + PG8_SA(b, h) + aoff + m * 2048 + k * 1024); } while (0)
; #define PG8_LDB(dst, b, h) do { _Pragma("unroll") for (int n = 0; n < 2; ++n) _Pragma("unroll") for (int k = 0; k < 2; ++k) dst[n][k] = *(const PG8_LAS bf16x8*)(lds + PG8_SB(b, h) + boff + n * 2048 + k * 1024); } while (0)
; #define PG8_MMA(ai, bj, At, Bt) do { __builtin_amdgcn_s_setprio(1); _Pragma("unroll") for (int m = 0; m < 4; ++m) _Pragma("unroll") for (int n = 0; n < 2; ++n) _Pragma("unroll") for (int k = 0; k < 2; ++k) \
;         acc[ai][bj][m][n] = __builtin_amdgcn_mfma_f32_16x16x32_bf16(Bt[n][k], At[m][k], acc[ai][bj][m][n], 0, 0, 0); __builtin_amdgcn_s_setprio(0); } while (0)
; #define PG8_WAIT_V(n) asm volatile("s_waitcnt vmcnt(" #n ")" ::: "memory")
; #define PG8_WAIT_L(n) asm volatile("s_waitcnt lgkmcnt(" #n ")" ::: "memory")
; #define PG8_BAR __builtin_amdgcn_s_barrier()
; #define PG8_SCHED __builtin_amdgcn_sched_barrier(0)
; template <class Epi, class Sched, bool ALIGN_EPI = false, bool SP2 = false>
; __device__ __forceinline__ void gemm_phase(PG8_LAS unsigned char* lds, const Gemm g, const Sched& S, const Epi& E, const int tid_in) {
;     ...
;             PG8_WAIT_V(8); PG8_WAIT_L(0); PG8_BAR; PG8_MMA(1, 0, At, B0); PG8_MMA(1, 1, At, B1); PG8_BAR; PG8_SCHED;
;             PG8_LDB(B0, 1, 0); PG8_LDB(B1, 1, 1); PG8_SCHED; PG8_LDA(At, 1, 0); PG8_STAGE(PG8_SA(0, 1), a2 + hstep, voffA);
;             PG8_WAIT_V(8); PG8_WAIT_L(0); PG8_BAR; PG8_MMA(0, 0, At, B0); PG8_MMA(0, 1, At, B1); PG8_BAR; PG8_SCHED;
	s_setprio 1
	s_waitcnt lgkmcnt(0)
	v_mfma_f32_16x16x32_bf16 v[60:63], v[92:95], v[160:163], 0
	v_mfma_f32_16x16x32_bf16 v[56:59], v[112:115], v[160:163], 0
	v_mfma_f32_16x16x32_bf16 v[44:47], v[92:95], v[168:171], 0
	v_mfma_f32_16x16x32_bf16 v[40:43], v[112:115], v[168:171], 0
	v_mfma_f32_16x16x32_bf16 v[28:31], v[92:95], v[176:179], 0
	v_mfma_f32_16x16x32_bf16 v[24:27], v[112:115], v[176:179], 0
	v_mfma_f32_16x16x32_bf16 v[12:15], v[92:95], v[200:203], 0
	v_mfma_f32_16x16x32_bf16 v[8:11], v[112:115], v[200:203], 0
	v_mfma_f32_16x16x32_bf16 v[60:63], v[100:103], v[164:167], v[60:63]
	v_mfma_f32_16x16x32_bf16 v[56:59], v[124:127], v[164:167], v[56:59]
	v_mfma_f32_16x16x32_bf16 v[44:47], v[100:103], v[172:175], v[44:47]
	v_mfma_f32_16x16x32_bf16 v[40:43], v[124:127], v[172:175], v[40:43]
	v_mfma_f32_16x16x32_bf16 v[28:31], v[100:103], v[180:183], v[28:31]
	v_mfma_f32_16x16x32_bf16 v[24:27], v[124:127], v[180:183], v[24:27]
	v_mfma_f32_16x16x32_bf16 v[12:15], v[100:103], v[210:213], v[12:15]
	v_mfma_f32_16x16x32_bf16 v[8:11], v[124:127], v[210:213], v[8:11]
	s_setprio 0
	s_setprio 1
	v_mfma_f32_16x16x32_bf16 v[52:55], v[136:139], v[160:163], 0
	v_mfma_f32_16x16x32_bf16 v[48:51], v[152:155], v[160:163], 0
	v_mfma_f32_16x16x32_bf16 v[36:39], v[136:139], v[168:171], 0
	v_mfma_f32_16x16x32_bf16 v[32:35], v[152:155], v[168:171], 0
	v_mfma_f32_16x16x32_bf16 v[20:23], v[136:139], v[176:179], 0
	v_mfma_f32_16x16x32_bf16 v[16:19], v[152:155], v[176:179], 0
	v_mfma_f32_16x16x32_bf16 v[4:7], v[136:139], v[200:203], 0
	v_mfma_f32_16x16x32_bf16 v[0:3], v[152:155], v[200:203], 0
	v_mfma_f32_16x16x32_bf16 v[52:55], v[148:151], v[164:167], v[52:55]
	v_mfma_f32_16x16x32_bf16 v[48:51], v[156:159], v[164:167], v[48:51]
	v_mfma_f32_16x16x32_bf16 v[36:39], v[148:151], v[172:175], v[36:39]
	v_mfma_f32_16x16x32_bf16 v[32:35], v[156:159], v[172:175], v[32:35]
	v_mfma_f32_16x16x32_bf16 v[20:23], v[148:151], v[180:183], v[20:23]
	v_mfma_f32_16x16x32_bf16 v[16:19], v[156:159], v[180:183], v[16:19]
	v_mfma_f32_16x16x32_bf16 v[4:7], v[148:151], v[210:213], v[4:7]
	v_mfma_f32_16x16x32_bf16 v[0:3], v[156:159], v[210:213], v[0:3]
	s_setprio 0
	s_barrier
	s_add_i32 s77, 0, 0x18000
	s_add_i32 s78, 0, 0x1c000
	v_add_u32_e32 v124, s77, v205
	v_add_u32_e32 v156, s78, v205
	ds_read_b128 v[92:95], v124
	ds_read_b128 v[100:103], v124 offset:1024
	ds_read_b128 v[112:115], v124 offset:2048
	ds_read_b128 v[124:127], v124 offset:3072
	ds_read_b128 v[136:139], v156
	ds_read_b128 v[148:151], v156 offset:1024
	ds_read_b128 v[152:155], v156 offset:2048
	ds_read_b128 v[156:159], v156 offset:3072
	s_add_u32 s56, s56, 0x40000
	s_addc_u32 s57, s57, 0
	s_mov_b32 m0, s34
	v_lshl_add_u64 v[222:223], s[56:57], 0, v[184:185]
	ds_read_b128 v[160:163], v209 offset:32768
	ds_read_b128 v[164:167], v209 offset:33792
	ds_read_b128 v[168:171], v209 offset:34816
	ds_read_b128 v[172:175], v209 offset:35840
	ds_read_b128 v[176:179], v209 offset:36864
	ds_read_b128 v[180:183], v209 offset:37888
	ds_read_b128 v[200:203], v209 offset:38912
	ds_read_b128 v[210:213], v209 offset:39936
	global_load_lds_dwordx4 v[222:223], off
	v_lshl_add_u64 v[222:223], s[56:57], 0, v[188:189]
	s_mov_b32 m0, s35
	s_nop 0
	global_load_lds_dwordx4 v[222:223], off
	s_waitcnt vmcnt(8)
	s_waitcnt lgkmcnt(0)
	s_barrier
	s_setprio 1
	s_waitcnt lgkmcnt(0)
	v_mfma_f32_16x16x32_bf16 v[144:147], v[92:95], v[160:163], v[144:147]
	v_mfma_f32_16x16x32_bf16 v[140:143], v[112:115], v[160:163], v[140:143]
	v_mfma_f32_16x16x32_bf16 v[120:123], v[92:95], v[168:171], v[120:123]
	v_mfma_f32_16x16x32_bf16 v[116:119], v[112:115], v[168:171], v[116:119]
	v_mfma_f32_16x16x32_bf16 v[96:99], v[92:95], v[176:179], v[96:99]
	v_mfma_f32_16x16x32_bf16 v[88:91], v[112:115], v[176:179], v[88:91]
	v_mfma_f32_16x16x32_bf16 v[76:79], v[92:95], v[200:203], v[76:79]
	v_mfma_f32_16x16x32_bf16 v[72:75], v[112:115], v[200:203], v[72:75]
	v_mfma_f32_16x16x32_bf16 v[144:147], v[100:103], v[164:167], v[144:147]
	v_mfma_f32_16x16x32_bf16 v[140:143], v[124:127], v[164:167], v[140:143]
	v_mfma_f32_16x16x32_bf16 v[120:123], v[100:103], v[172:175], v[120:123]
	v_mfma_f32_16x16x32_bf16 v[116:119], v[124:127], v[172:175], v[116:119]
	v_mfma_f32_16x16x32_bf16 v[96:99], v[100:103], v[180:183], v[96:99]
	v_mfma_f32_16x16x32_bf16 v[88:91], v[124:127], v[180:183], v[88:91]
	v_mfma_f32_16x16x32_bf16 v[76:79], v[100:103], v[210:213], v[76:79]
	v_mfma_f32_16x16x32_bf16 v[72:75], v[124:127], v[210:213], v[72:75]
	s_setprio 0
	s_setprio 1
	v_mfma_f32_16x16x32_bf16 v[132:135], v[136:139], v[160:163], v[132:135]
	v_mfma_f32_16x16x32_bf16 v[128:131], v[152:155], v[160:163], v[128:131]
	v_mfma_f32_16x16x32_bf16 v[108:111], v[136:139], v[168:171], v[108:111]
	v_mfma_f32_16x16x32_bf16 v[104:107], v[152:155], v[168:171], v[104:107]
	v_mfma_f32_16x16x32_bf16 v[84:87], v[136:139], v[176:179], v[84:87]
	v_mfma_f32_16x16x32_bf16 v[80:83], v[152:155], v[176:179], v[80:83]
	v_mfma_f32_16x16x32_bf16 v[68:71], v[136:139], v[200:203], v[68:71]
	v_mfma_f32_16x16x32_bf16 v[64:67], v[152:155], v[200:203], v[64:67]
	v_mfma_f32_16x16x32_bf16 v[132:135], v[148:151], v[164:167], v[132:135]
	v_mfma_f32_16x16x32_bf16 v[128:131], v[156:159], v[164:167], v[128:131]
	v_mfma_f32_16x16x32_bf16 v[108:111], v[148:151], v[172:175], v[108:111]
	v_mfma_f32_16x16x32_bf16 v[104:107], v[156:159], v[172:175], v[104:107]
	v_mfma_f32_16x16x32_bf16 v[84:87], v[148:151], v[180:183], v[84:87]
	v_mfma_f32_16x16x32_bf16 v[80:83], v[156:159], v[180:183], v[80:83]
	v_mfma_f32_16x16x32_bf16 v[68:71], v[148:151], v[210:213], v[68:71]
	v_mfma_f32_16x16x32_bf16 v[64:67], v[156:159], v[210:213], v[64:67]
	s_setprio 0
	s_barrier
; #define PG8_STAGE(bufoff, gbase, voff) do { _Pragma("unroll") for (int _i = 0; _i < 2; ++_i) \
;         __builtin_amdgcn_global_load_lds((const unsigned*)((const char*)(gbase) + (voff)[_i]), (PG8_LAS unsigned*)(lds + (bufoff) + ldsw + _i * 8192), 16, 0, 0); } while (0)
; #define PG8_LDA(dst, b, h) do { _Pragma("unroll") for (int m = 0; m < 4; ++m) _Pragma("unroll") for (int k = 0; k < 2; ++k) dst[m][k] = *(const PG8_LAS bf16x8*)(lds + PG8_SA(b, h) + aoff + m * 2048 + k * 1024); } while (0)
; #define PG8_MMA(ai, bj, At, Bt) do { __builtin_amdgcn_s_setprio(1); _Pragma("unroll") for (int m = 0; m < 4; ++m) _Pragma("unroll") for (int n = 0; n < 2; ++n) _Pragma("unroll") for (int k = 0; k < 2; ++k) \
;         acc[ai][bj][m][n] = __builtin_amdgcn_mfma_f32_16x16x32_bf16(Bt[n][k], At[m][k], acc[ai][bj][m][n], 0, 0, 0); __builtin_amdgcn_s_setprio(0); } while (0)
; #define PG8_WAIT_V(n) asm volatile("s_waitcnt vmcnt(" #n ")" ::: "memory")
; #define PG8_WAIT_L(n) asm volatile("s_waitcnt lgkmcnt(" #n ")" ::: "memory")
; #define PG8_BAR __builtin_amdgcn_s_barrier()
; #define PG8_SCHED __builtin_amdgcn_sched_barrier(0)
; template <class Epi, class Sched, bool ALIGN_EPI = false, bool SP2 = false>
; __device__ __forceinline__ void gemm_phase(PG8_LAS unsigned char* lds, const Gemm g, const Sched& S, const Epi& E, const int tid_in) {
;     ...
;             PG8_LDA(At, 1, 1); PG8_STAGE(PG8_SB(1, 0), b3, voffB); PG8_STAGE(PG8_SB(1, 1), b3 + hstep, voffB); PG8_STAGE(PG8_SA(1, 0), a3, voffA);
;             PG8_WAIT_V(8); PG8_WAIT_L(0); PG8_BAR; PG8_MMA(1, 0, At, B0); PG8_MMA(1, 1, At, B1); PG8_BAR; PG8_SCHED;
	s_add_i32 s56, s77, s2
	v_lshl_add_u64 v[214:215], v[214:215], 0, s[26:27]
	s_mov_b32 m0, s56
	ds_read_b128 v[160:163], v209 offset:49152
	ds_read_b128 v[164:167], v209 offset:50176
	ds_read_b128 v[168:171], v209 offset:51200
	ds_read_b128 v[172:175], v209 offset:52224
	ds_read_b128 v[176:179], v209 offset:53248
	ds_read_b128 v[180:183], v209 offset:54272
	ds_read_b128 v[200:203], v209 offset:55296
	ds_read_b128 v[210:213], v209 offset:56320
	global_load_lds_dwordx4 v[214:215], off
	s_add_i32 m0, s56, 0x2000
	s_add_u32 s0, s0, 0x40080
	v_lshl_add_u64 v[214:215], v[216:217], 0, s[26:27]
	s_addc_u32 s1, s1, 0
	s_add_i32 s56, s78, s2
	global_load_lds_dwordx4 v[214:215], off
	v_lshl_add_u64 v[214:215], s[0:1], 0, v[186:187]
	s_mov_b32 m0, s56
	s_nop 0
	global_load_lds_dwordx4 v[214:215], off
	v_lshl_add_u64 v[214:215], s[0:1], 0, v[190:191]
	s_add_i32 m0, s56, 0x2000
	s_nop 0
	global_load_lds_dwordx4 v[214:215], off
	v_lshl_add_u64 v[214:215], v[218:219], 0, s[26:27]
	s_mov_b32 m0, s37
	s_nop 0
	global_load_lds_dwordx4 v[214:215], off
	v_lshl_add_u64 v[214:215], v[220:221], 0, s[26:27]
	s_mov_b32 m0, s38
	s_nop 0
	global_load_lds_dwordx4 v[214:215], off
	s_waitcnt vmcnt(8)
	s_waitcnt lgkmcnt(0)
	s_barrier
	s_setprio 1
	s_waitcnt lgkmcnt(0)
	v_mfma_f32_16x16x32_bf16 v[60:63], v[92:95], v[160:163], v[60:63]
	v_mfma_f32_16x16x32_bf16 v[56:59], v[112:115], v[160:163], v[56:59]
	v_mfma_f32_16x16x32_bf16 v[44:47], v[92:95], v[168:171], v[44:47]
	v_mfma_f32_16x16x32_bf16 v[40:43], v[112:115], v[168:171], v[40:43]
	v_mfma_f32_16x16x32_bf16 v[28:31], v[92:95], v[176:179], v[28:31]
	v_mfma_f32_16x16x32_bf16 v[24:27], v[112:115], v[176:179], v[24:27]
	v_mfma_f32_16x16x32_bf16 v[12:15], v[92:95], v[200:203], v[12:15]
	v_mfma_f32_16x16x32_bf16 v[8:11], v[112:115], v[200:203], v[8:11]
	v_mfma_f32_16x16x32_bf16 v[60:63], v[100:103], v[164:167], v[60:63]
	v_mfma_f32_16x16x32_bf16 v[56:59], v[124:127], v[164:167], v[56:59]
	v_mfma_f32_16x16x32_bf16 v[44:47], v[100:103], v[172:175], v[44:47]
	v_mfma_f32_16x16x32_bf16 v[40:43], v[124:127], v[172:175], v[40:43]
	v_mfma_f32_16x16x32_bf16 v[28:31], v[100:103], v[180:183], v[28:31]
	v_mfma_f32_16x16x32_bf16 v[24:27], v[124:127], v[180:183], v[24:27]
	v_mfma_f32_16x16x32_bf16 v[12:15], v[100:103], v[210:213], v[12:15]
	v_mfma_f32_16x16x32_bf16 v[8:11], v[124:127], v[210:213], v[8:11]
	s_setprio 0
	s_setprio 1
	v_mfma_f32_16x16x32_bf16 v[52:55], v[136:139], v[160:163], v[52:55]
	v_mfma_f32_16x16x32_bf16 v[48:51], v[152:155], v[160:163], v[48:51]
	v_mfma_f32_16x16x32_bf16 v[36:39], v[136:139], v[168:171], v[36:39]
	v_mfma_f32_16x16x32_bf16 v[32:35], v[152:155], v[168:171], v[32:35]
	v_mfma_f32_16x16x32_bf16 v[20:23], v[136:139], v[176:179], v[20:23]
	v_mfma_f32_16x16x32_bf16 v[16:19], v[152:155], v[176:179], v[16:19]
	v_mfma_f32_16x16x32_bf16 v[4:7], v[136:139], v[200:203], v[4:7]
	v_mfma_f32_16x16x32_bf16 v[0:3], v[152:155], v[200:203], v[0:3]
	v_mfma_f32_16x16x32_bf16 v[52:55], v[148:151], v[164:167], v[52:55]
	v_mfma_f32_16x16x32_bf16 v[48:51], v[156:159], v[164:167], v[48:51]
	v_mfma_f32_16x16x32_bf16 v[36:39], v[148:151], v[172:175], v[36:39]
	v_mfma_f32_16x16x32_bf16 v[32:35], v[156:159], v[172:175], v[32:35]
	v_mfma_f32_16x16x32_bf16 v[20:23], v[148:151], v[180:183], v[20:23]
	v_mfma_f32_16x16x32_bf16 v[16:19], v[156:159], v[180:183], v[16:19]
	v_mfma_f32_16x16x32_bf16 v[4:7], v[148:151], v[210:213], v[4:7]
	v_mfma_f32_16x16x32_bf16 v[0:3], v[156:159], v[210:213], v[0:3]
	s_setprio 0
	s_barrier
	s_add_i32 s76, s76, 2
	s_add_u32 s54, s54, 0x100
	s_addc_u32 s55, s55, 0
	s_add_u32 s74, s74, 0x100
	s_addc_u32 s75, s75, 0
	s_cmp_gt_u32 s76, 13
	s_cbranch_scc0 .LBB0_689
	s_branch .Lmy_kdone_2

; #define PG8_BAR __builtin_amdgcn_s_barrier()
; template <class Epi, class Sched, bool ALIGN_EPI = false, bool SP2 = false>
; __device__ __forceinline__ void gemm_phase(PG8_LAS unsigned char* lds, const Gemm g, const Sched& S, const Epi& E, const int tid_in) {
;     ...
;         if constexpr (ALIGN_EPI) { if (wr == 0) PG8_BAR; }
.Lmy_kdone_2:
	s_and_b64 vcc, exec, s[28:29]
	s_cbranch_vccz .LBB0_692
	s_barrier

; #define PG8_STAGE(bufoff, gbase, voff) do { _Pragma("unroll") for (int _i = 0; _i < 2; ++_i) \
;         __builtin_amdgcn_global_load_lds((const unsigned*)((const char*)(gbase) + (voff)[_i]), (PG8_LAS unsigned*)(lds + (bufoff) + ldsw + _i * 8192), 16, 0, 0); } while (0)
; #define PG8_LDA(dst, b, h) do { _Pragma("unroll") for (int m = 0; m < 4; ++m) _Pragma("unroll") for (int k = 0; k < 2; ++k) dst[m][k] = *(const PG8_LAS bf16x8*)(lds + PG8_SA(b, h) + aoff + m * 2048 + k * 1024); } while (0)
; #define PG8_LDB(dst, b, h) do { _Pragma("unroll") for (int n = 0; n < 2; ++n) _Pragma("unroll") for (int k = 0; k < 2; ++k) dst[n][k] = *(const PG8_LAS bf16x8*)(lds + PG8_SB(b, h) + boff + n * 2048 + k * 1024); } while (0)
; #define PG8_MMA(ai, bj, At, Bt) do { __builtin_amdgcn_s_setprio(1); _Pragma("unroll") for (int m = 0; m < 4; ++m) _Pragma("unroll") for (int n = 0; n < 2; ++n) _Pragma("unroll") for (int k = 0; k < 2; ++k) \
;         acc[ai][bj][m][n] = __builtin_amdgcn_mfma_f32_16x16x32_bf16(Bt[n][k], At[m][k], acc[ai][bj][m][n], 0, 0, 0); __builtin_amdgcn_s_setprio(0); } while (0)
; #define PG8_WAIT_V(n) asm volatile("s_waitcnt vmcnt(" #n ")" ::: "memory")
; template <class Epi, class Sched, bool ALIGN_EPI = false, bool SP2 = false>
; __device__ __forceinline__ void gemm_phase(PG8_LAS unsigned char* lds, const Gemm g, const Sched& S, const Epi& E, const int tid_in) {
;     ...
;         const char* nA = has_next ? (const char*)g.A + (size_t)nxt.pm * tstep : cA; const char* nB = has_next ? (const char*)g.Bt + (size_t)nxt.pn * tstep : cB;
;         for (int t = 0; t < nt; t += 2) {
;             const bool last = (t == nt - 2);
;             const char* a1 = cA + (size_t)(t + 1) * kstep;
;             const char* a2 = last ? nA : cA + (size_t)(t + 2) * kstep; const char* b2 = last ? nB : cB + (size_t)(t + 2) * kstep;
;             const char* a3 = a2 + kstep; const char* b3 = b2 + kstep;
;             if (last && has_next) S.a_ready(nxt);
;             if constexpr (SP2) {
;             PG8_LDB(B0, 0, 0); PG8_LDB(B1, 0, 1); PG8_SCHED; PG8_LDA(At, 0, 0); PG8_STAGE(PG8_SA(1, 1), a1 + hstep, voffA);
;             PG8_WAIT_V(8); PG8_WAIT_L(0); PG8_BAR; PG8_MMA(0, 0, At, B0); PG8_MMA(0, 1, At, B1); PG8_BAR; PG8_SCHED;
;             PG8_LDA(At, 0, 1); PG8_STAGE(PG8_SB(0, 0), b2, voffB); PG8_STAGE(PG8_SB(0, 1), b2 + hstep, voffB); PG8_STAGE(PG8_SA(0, 0), a2, voffA);
.LBB0_1199:
	s_ashr_i32 s45, s44, 31
	s_lshl_b64 s[8:9], s[44:45], 19
	s_add_u32 s46, s36, s8
	s_addc_u32 s47, s37, s9
	s_and_b64 s[8:9], s[4:5], exec
	s_cselect_b32 s45, s47, s55
	s_cselect_b32 s76, s46, s54
	s_ashr_i32 s43, s42, 31
	s_lshl_b64 s[8:9], s[42:43], 19
	s_add_u32 s52, s34, s8
	s_addc_u32 s53, s35, s9
	s_and_b64 s[8:9], s[4:5], exec
	s_cselect_b32 s43, s53, s1
	s_cselect_b32 s77, s52, s0
	s_add_u32 s8, s54, 0x40080
	s_addc_u32 s9, s55, 0
	s_add_u32 s78, s0, 0x100
	v_mov_b32_e32 v0, 0
	s_addc_u32 s79, s1, 0
	s_mov_b32 s80, -2
	ds_read_b128 v[160:163], v154
	ds_read_b128 v[164:167], v154 offset:1024
	ds_read_b128 v[168:171], v154 offset:2048
	ds_read_b128 v[172:175], v154 offset:3072
	ds_read_b128 v[176:179], v155
	ds_read_b128 v[180:183], v155 offset:1024
	ds_read_b128 v[184:187], v155 offset:2048
	ds_read_b128 v[188:191], v155 offset:3072
	s_add_u32 s0, s8, 0xfffc0080
	s_addc_u32 s1, s9, -1
	s_cmp_eq_u32 s80, 12
	s_cselect_b32 s55, s45, s1
	s_cselect_b32 s54, s76, s0
	s_cselect_b32 s1, s43, s79
	s_cselect_b32 s0, s77, s78
	v_lshl_add_u64 v[144:145], s[8:9], 0, v[136:137]
	s_add_i32 m0, s38, 0xc000
	ds_read_b128 v[192:195], v156
	ds_read_b128 v[196:199], v156 offset:1024
	ds_read_b128 v[200:203], v156 offset:2048
	ds_read_b128 v[204:207], v156 offset:3072
	ds_read_b128 v[208:211], v156 offset:4096
	ds_read_b128 v[212:215], v156 offset:5120
	ds_read_b128 v[216:219], v156 offset:6144
	ds_read_b128 v[220:223], v156 offset:7168
	global_load_lds_dwordx4 v[144:145], off
	v_lshl_add_u64 v[144:145], s[8:9], 0, v[138:139]
	s_add_i32 m0, s38, 0xe000
	s_nop 0
	global_load_lds_dwordx4 v[144:145], off
	s_waitcnt vmcnt(8)
	s_waitcnt lgkmcnt(0)
	s_barrier
	s_setprio 1
	s_waitcnt lgkmcnt(0)
	v_mfma_f32_16x16x32_bf16 v[124:127], v[160:163], v[192:195], 0
	v_mfma_f32_16x16x32_bf16 v[116:119], v[168:171], v[192:195], 0
	v_mfma_f32_16x16x32_bf16 v[108:111], v[160:163], v[200:203], 0
	v_mfma_f32_16x16x32_bf16 v[100:103], v[168:171], v[200:203], 0
	v_mfma_f32_16x16x32_bf16 v[92:95], v[160:163], v[208:211], 0
	v_mfma_f32_16x16x32_bf16 v[84:87], v[168:171], v[208:211], 0
	v_mfma_f32_16x16x32_bf16 v[76:79], v[160:163], v[216:219], 0
	v_mfma_f32_16x16x32_bf16 v[68:71], v[168:171], v[216:219], 0
	v_mfma_f32_16x16x32_bf16 v[124:127], v[164:167], v[196:199], v[124:127]
	v_mfma_f32_16x16x32_bf16 v[116:119], v[172:175], v[196:199], v[116:119]
	v_mfma_f32_16x16x32_bf16 v[108:111], v[164:167], v[204:207], v[108:111]
	v_mfma_f32_16x16x32_bf16 v[100:103], v[172:175], v[204:207], v[100:103]
	v_mfma_f32_16x16x32_bf16 v[92:95], v[164:167], v[212:215], v[92:95]
	v_mfma_f32_16x16x32_bf16 v[84:87], v[172:175], v[212:215], v[84:87]
	v_mfma_f32_16x16x32_bf16 v[76:79], v[164:167], v[220:223], v[76:79]
	v_mfma_f32_16x16x32_bf16 v[68:71], v[172:175], v[220:223], v[68:71]
	s_setprio 0
	s_setprio 1
	v_mfma_f32_16x16x32_bf16 v[120:123], v[176:179], v[192:195], 0
	v_mfma_f32_16x16x32_bf16 v[112:115], v[184:187], v[192:195], 0
	v_mfma_f32_16x16x32_bf16 v[104:107], v[176:179], v[200:203], 0
	v_mfma_f32_16x16x32_bf16 v[96:99], v[184:187], v[200:203], 0
	v_mfma_f32_16x16x32_bf16 v[88:91], v[176:179], v[208:211], 0
	v_mfma_f32_16x16x32_bf16 v[80:83], v[184:187], v[208:211], 0
	v_mfma_f32_16x16x32_bf16 v[72:75], v[176:179], v[216:219], 0
	v_mfma_f32_16x16x32_bf16 v[64:67], v[184:187], v[216:219], 0
	v_mfma_f32_16x16x32_bf16 v[120:123], v[180:183], v[196:199], v[120:123]
	v_mfma_f32_16x16x32_bf16 v[112:115], v[188:191], v[196:199], v[112:115]
	v_mfma_f32_16x16x32_bf16 v[104:107], v[180:183], v[204:207], v[104:107]
	v_mfma_f32_16x16x32_bf16 v[96:99], v[188:191], v[204:207], v[96:99]
	v_mfma_f32_16x16x32_bf16 v[88:91], v[180:183], v[212:215], v[88:91]
	v_mfma_f32_16x16x32_bf16 v[80:83], v[188:191], v[212:215], v[80:83]
	v_mfma_f32_16x16x32_bf16 v[72:75], v[180:183], v[220:223], v[72:75]
	v_mfma_f32_16x16x32_bf16 v[64:67], v[188:191], v[220:223], v[64:67]
	s_setprio 0
	s_barrier
	s_add_i32 s81, s57, s31
	v_lshl_add_u64 v[144:145], s[0:1], 0, v[130:131]
	s_mov_b32 m0, s81
	ds_read_b128 v[192:195], v156 offset:16384
	ds_read_b128 v[196:199], v156 offset:17408
	ds_read_b128 v[200:203], v156 offset:18432
	ds_read_b128 v[204:207], v156 offset:19456
	ds_read_b128 v[208:211], v156 offset:20480
	ds_read_b128 v[212:215], v156 offset:21504
	ds_read_b128 v[216:219], v156 offset:22528
	ds_read_b128 v[220:223], v156 offset:23552
	global_load_lds_dwordx4 v[144:145], off
	s_add_i32 m0, s81, 0x2000
	s_add_u32 s82, s0, 0x40000
	v_lshl_add_u64 v[224:225], s[0:1], 0, v[134:135]
	s_addc_u32 s83, s1, 0
	s_add_i32 s81, s73, s31
	global_load_lds_dwordx4 v[224:225], off
	v_lshl_add_u64 v[226:227], s[82:83], 0, v[130:131]
	s_mov_b32 m0, s81
	v_lshl_add_u64 v[228:229], s[54:55], 0, v[132:133]
	global_load_lds_dwordx4 v[226:227], off
	v_lshl_add_u64 v[226:227], s[82:83], 0, v[134:135]
	s_add_i32 m0, s81, 0x2000
	s_nop 0
	global_load_lds_dwordx4 v[226:227], off
	v_lshl_add_u64 v[226:227], s[54:55], 0, v[128:129]
	s_mov_b32 m0, s38
	s_nop 0
	global_load_lds_dwordx4 v[226:227], off
	s_mov_b32 m0, s39
	s_nop 0
	global_load_lds_dwordx4 v[228:229], off
	s_waitcnt vmcnt(8)
	s_waitcnt lgkmcnt(0)
	s_barrier
; #define PG8_STAGE(bufoff, gbase, voff) do { _Pragma("unroll") for (int _i = 0; _i < 2; ++_i) \
;         __builtin_amdgcn_global_load_lds((const unsigned*)((const char*)(gbase) + (voff)[_i]), (PG8_LAS unsigned*)(lds + (bufoff) + ldsw + _i * 8192), 16, 0, 0); } while (0)
; #define PG8_LDA(dst, b, h) do { _Pragma("unroll") for (int m = 0; m < 4; ++m) _Pragma("unroll") for (int k = 0; k < 2; ++k) dst[m][k] = *(const PG8_LAS bf16x8*)(lds + PG8_SA(b, h) + aoff + m * 2048 + k * 1024); } while (0)
; #define PG8_LDB(dst, b, h) do { _Pragma("unroll") for (int n = 0; n < 2; ++n) _Pragma("unroll") for (int k = 0; k < 2; ++k) dst[n][k] = *(const PG8_LAS bf16x8*)(lds + PG8_SB(b, h) + boff + n * 2048 + k * 1024); } while (0)
; #define PG8_MMA(ai, bj, At, Bt) do { __builtin_amdgcn_s_setprio(1); _Pragma("unroll") for (int m = 0; m < 4; ++m) _Pragma("unroll") for (int n = 0; n < 2; ++n) _Pragma("unroll") for (int k = 0; k < 2; ++k) \
;         acc[ai][bj][m][n] = __builtin_amdgcn_mfma_f32_16x16x32_bf16(Bt[n][k], At[m][k], acc[ai][bj][m][n], 0, 0, 0); __builtin_amdgcn_s_setprio(0); } while (0)
; #define PG8_WAIT_V(n) asm volatile("s_waitcnt vmcnt(" #n ")" ::: "memory")
; #define PG8_WAIT_L(n) asm volatile("s_waitcnt lgkmcnt(" #n ")" ::: "memory")
; #define PG8_BAR __builtin_amdgcn_s_barrier()
; #define PG8_SCHED __builtin_amdgcn_sched_barrier(0)
; template <class Epi, class Sched, bool ALIGN_EPI = false, bool SP2 = false>
; __device__ __forceinline__ void gemm_phase(PG8_LAS unsigned char* lds, const Gemm g, const Sched& S, const Epi& E, const int tid_in) {
;     ...
;             PG8_WAIT_V(8); PG8_WAIT_L(0); PG8_BAR; PG8_MMA(1, 0, At, B0); PG8_MMA(1, 1, At, B1); PG8_BAR; PG8_SCHED;
;             PG8_LDB(B0, 1, 0); PG8_LDB(B1, 1, 1); PG8_SCHED; PG8_LDA(At, 1, 0); PG8_STAGE(PG8_SA(0, 1), a2 + hstep, voffA);
;             PG8_WAIT_V(8); PG8_WAIT_L(0); PG8_BAR; PG8_MMA(0, 0, At, B0); PG8_MMA(0, 1, At, B1); PG8_BAR; PG8_SCHED;
	s_setprio 1
	s_waitcnt lgkmcnt(0)
	v_mfma_f32_16x16x32_bf16 v[60:63], v[160:163], v[192:195], 0
	v_mfma_f32_16x16x32_bf16 v[52:55], v[168:171], v[192:195], 0
	v_mfma_f32_16x16x32_bf16 v[44:47], v[160:163], v[200:203], 0
	v_mfma_f32_16x16x32_bf16 v[36:39], v[168:171], v[200:203], 0
	v_mfma_f32_16x16x32_bf16 v[28:31], v[160:163], v[208:211], 0
	v_mfma_f32_16x16x32_bf16 v[20:23], v[168:171], v[208:211], 0
	v_mfma_f32_16x16x32_bf16 v[12:15], v[160:163], v[216:219], 0
	v_mfma_f32_16x16x32_bf16 v[4:7], v[168:171], v[216:219], 0
	v_mfma_f32_16x16x32_bf16 v[60:63], v[164:167], v[196:199], v[60:63]
	v_mfma_f32_16x16x32_bf16 v[52:55], v[172:175], v[196:199], v[52:55]
	v_mfma_f32_16x16x32_bf16 v[44:47], v[164:167], v[204:207], v[44:47]
	v_mfma_f32_16x16x32_bf16 v[36:39], v[172:175], v[204:207], v[36:39]
	v_mfma_f32_16x16x32_bf16 v[28:31], v[164:167], v[212:215], v[28:31]
	v_mfma_f32_16x16x32_bf16 v[20:23], v[172:175], v[212:215], v[20:23]
	v_mfma_f32_16x16x32_bf16 v[12:15], v[164:167], v[220:223], v[12:15]
	v_mfma_f32_16x16x32_bf16 v[4:7], v[172:175], v[220:223], v[4:7]
	s_setprio 0
	s_setprio 1
	v_mfma_f32_16x16x32_bf16 v[56:59], v[176:179], v[192:195], 0
	v_mfma_f32_16x16x32_bf16 v[48:51], v[184:187], v[192:195], 0
	v_mfma_f32_16x16x32_bf16 v[40:43], v[176:179], v[200:203], 0
	v_mfma_f32_16x16x32_bf16 v[32:35], v[184:187], v[200:203], 0
	v_mfma_f32_16x16x32_bf16 v[24:27], v[176:179], v[208:211], 0
	v_mfma_f32_16x16x32_bf16 v[16:19], v[184:187], v[208:211], 0
	v_mfma_f32_16x16x32_bf16 v[8:11], v[176:179], v[216:219], 0
	v_mfma_f32_16x16x32_bf16 v[0:3], v[184:187], v[216:219], 0
	v_mfma_f32_16x16x32_bf16 v[56:59], v[180:183], v[196:199], v[56:59]
	v_mfma_f32_16x16x32_bf16 v[48:51], v[188:191], v[196:199], v[48:51]
	v_mfma_f32_16x16x32_bf16 v[40:43], v[180:183], v[204:207], v[40:43]
	v_mfma_f32_16x16x32_bf16 v[32:35], v[188:191], v[204:207], v[32:35]
	v_mfma_f32_16x16x32_bf16 v[24:27], v[180:183], v[212:215], v[24:27]
	v_mfma_f32_16x16x32_bf16 v[16:19], v[188:191], v[212:215], v[16:19]
	v_mfma_f32_16x16x32_bf16 v[8:11], v[180:183], v[220:223], v[8:11]
	v_mfma_f32_16x16x32_bf16 v[0:3], v[188:191], v[220:223], v[0:3]
	s_setprio 0
	s_barrier
	s_add_i32 s81, 0, 0x18000
	v_add_u32_e32 v159, s81, v148
	s_add_i32 s82, 0, 0x1c000
	ds_read_b128 v[160:163], v159
	ds_read_b128 v[164:167], v159 offset:1024
	ds_read_b128 v[168:171], v159 offset:2048
	ds_read_b128 v[172:175], v159 offset:3072
	v_add_u32_e32 v159, s82, v148
	ds_read_b128 v[176:179], v159
	ds_read_b128 v[180:183], v159 offset:1024
	ds_read_b128 v[184:187], v159 offset:2048
	ds_read_b128 v[188:191], v159 offset:3072
	s_add_u32 s54, s54, 0x40000
	s_addc_u32 s55, s55, 0
	s_mov_b32 m0, s40
	v_lshl_add_u64 v[230:231], s[54:55], 0, v[128:129]
	ds_read_b128 v[192:195], v156 offset:32768
	ds_read_b128 v[196:199], v156 offset:33792
	ds_read_b128 v[200:203], v156 offset:34816
	ds_read_b128 v[204:207], v156 offset:35840
	ds_read_b128 v[208:211], v156 offset:36864
	ds_read_b128 v[212:215], v156 offset:37888
	ds_read_b128 v[216:219], v156 offset:38912
	ds_read_b128 v[220:223], v156 offset:39936
	global_load_lds_dwordx4 v[230:231], off
	v_lshl_add_u64 v[230:231], s[54:55], 0, v[132:133]
	s_mov_b32 m0, s41
	s_nop 0
	global_load_lds_dwordx4 v[230:231], off
	s_waitcnt vmcnt(8)
	s_waitcnt lgkmcnt(0)
	s_barrier
	s_setprio 1
	s_waitcnt lgkmcnt(0)
	v_mfma_f32_16x16x32_bf16 v[124:127], v[160:163], v[192:195], v[124:127]
	v_mfma_f32_16x16x32_bf16 v[116:119], v[168:171], v[192:195], v[116:119]
	v_mfma_f32_16x16x32_bf16 v[108:111], v[160:163], v[200:203], v[108:111]
	v_mfma_f32_16x16x32_bf16 v[100:103], v[168:171], v[200:203], v[100:103]
	v_mfma_f32_16x16x32_bf16 v[92:95], v[160:163], v[208:211], v[92:95]
	v_mfma_f32_16x16x32_bf16 v[84:87], v[168:171], v[208:211], v[84:87]
	v_mfma_f32_16x16x32_bf16 v[76:79], v[160:163], v[216:219], v[76:79]
	v_mfma_f32_16x16x32_bf16 v[68:71], v[168:171], v[216:219], v[68:71]
	v_mfma_f32_16x16x32_bf16 v[124:127], v[164:167], v[196:199], v[124:127]
	v_mfma_f32_16x16x32_bf16 v[116:119], v[172:175], v[196:199], v[116:119]
	v_mfma_f32_16x16x32_bf16 v[108:111], v[164:167], v[204:207], v[108:111]
	v_mfma_f32_16x16x32_bf16 v[100:103], v[172:175], v[204:207], v[100:103]
	v_mfma_f32_16x16x32_bf16 v[92:95], v[164:167], v[212:215], v[92:95]
	v_mfma_f32_16x16x32_bf16 v[84:87], v[172:175], v[212:215], v[84:87]
	v_mfma_f32_16x16x32_bf16 v[76:79], v[164:167], v[220:223], v[76:79]
	v_mfma_f32_16x16x32_bf16 v[68:71], v[172:175], v[220:223], v[68:71]
	s_setprio 0
	s_setprio 1
	v_mfma_f32_16x16x32_bf16 v[120:123], v[176:179], v[192:195], v[120:123]
	v_mfma_f32_16x16x32_bf16 v[112:115], v[184:187], v[192:195], v[112:115]
	v_mfma_f32_16x16x32_bf16 v[104:107], v[176:179], v[200:203], v[104:107]
	v_mfma_f32_16x16x32_bf16 v[96:99], v[184:187], v[200:203], v[96:99]
	v_mfma_f32_16x16x32_bf16 v[88:91], v[176:179], v[208:211], v[88:91]
	v_mfma_f32_16x16x32_bf16 v[80:83], v[184:187], v[208:211], v[80:83]
	v_mfma_f32_16x16x32_bf16 v[72:75], v[176:179], v[216:219], v[72:75]
	v_mfma_f32_16x16x32_bf16 v[64:67], v[184:187], v[216:219], v[64:67]
	v_mfma_f32_16x16x32_bf16 v[120:123], v[180:183], v[196:199], v[120:123]
	v_mfma_f32_16x16x32_bf16 v[112:115], v[188:191], v[196:199], v[112:115]
	v_mfma_f32_16x16x32_bf16 v[104:107], v[180:183], v[204:207], v[104:107]
	v_mfma_f32_16x16x32_bf16 v[96:99], v[188:191], v[204:207], v[96:99]
	v_mfma_f32_16x16x32_bf16 v[88:91], v[180:183], v[212:215], v[88:91]
	v_mfma_f32_16x16x32_bf16 v[80:83], v[188:191], v[212:215], v[80:83]
	v_mfma_f32_16x16x32_bf16 v[72:75], v[180:183], v[220:223], v[72:75]
	v_mfma_f32_16x16x32_bf16 v[64:67], v[188:191], v[220:223], v[64:67]
	s_setprio 0
	s_barrier
; #define PG8_STAGE(bufoff, gbase, voff) do { _Pragma("unroll") for (int _i = 0; _i < 2; ++_i) \
;         __builtin_amdgcn_global_load_lds((const unsigned*)((const char*)(gbase) + (voff)[_i]), (PG8_LAS unsigned*)(lds + (bufoff) + ldsw + _i * 8192), 16, 0, 0); } while (0)
; #define PG8_LDA(dst, b, h) do { _Pragma("unroll") for (int m = 0; m < 4; ++m) _Pragma("unroll") for (int k = 0; k < 2; ++k) dst[m][k] = *(const PG8_LAS bf16x8*)(lds + PG8_SA(b, h) + aoff + m * 2048 + k * 1024); } while (0)
; #define PG8_MMA(ai, bj, At, Bt) do { __builtin_amdgcn_s_setprio(1); _Pragma("unroll") for (int m = 0; m < 4; ++m) _Pragma("unroll") for (int n = 0; n < 2; ++n) _Pragma("unroll") for (int k = 0; k < 2; ++k) \
;         acc[ai][bj][m][n] = __builtin_amdgcn_mfma_f32_16x16x32_bf16(Bt[n][k], At[m][k], acc[ai][bj][m][n], 0, 0, 0); __builtin_amdgcn_s_setprio(0); } while (0)
; #define PG8_WAIT_V(n) asm volatile("s_waitcnt vmcnt(" #n ")" ::: "memory")
; #define PG8_WAIT_L(n) asm volatile("s_waitcnt lgkmcnt(" #n ")" ::: "memory")
; #define PG8_BAR __builtin_amdgcn_s_barrier()
; #define PG8_SCHED __builtin_amdgcn_sched_barrier(0)
; template <class Epi, class Sched, bool ALIGN_EPI = false, bool SP2 = false>
; __device__ __forceinline__ void gemm_phase(PG8_LAS unsigned char* lds, const Gemm g, const Sched& S, const Epi& E, const int tid_in) {
;     ...
;             PG8_LDA(At, 1, 1); PG8_STAGE(PG8_SB(1, 0), b3, voffB); PG8_STAGE(PG8_SB(1, 1), b3 + hstep, voffB); PG8_STAGE(PG8_SA(1, 0), a3, voffA);
;             PG8_WAIT_V(8); PG8_WAIT_L(0); PG8_BAR; PG8_MMA(1, 0, At, B0); PG8_MMA(1, 1, At, B1); PG8_BAR; PG8_SCHED;
	s_add_i32 s54, s81, s31
	v_lshl_add_u64 v[144:145], v[144:145], 0, s[26:27]
	s_mov_b32 m0, s54
	ds_read_b128 v[192:195], v156 offset:49152
	ds_read_b128 v[196:199], v156 offset:50176
	ds_read_b128 v[200:203], v156 offset:51200
	ds_read_b128 v[204:207], v156 offset:52224
	ds_read_b128 v[208:211], v156 offset:53248
	ds_read_b128 v[212:215], v156 offset:54272
	ds_read_b128 v[216:219], v156 offset:55296
	ds_read_b128 v[220:223], v156 offset:56320
	global_load_lds_dwordx4 v[144:145], off
	s_add_i32 m0, s54, 0x2000
	s_add_u32 s0, s0, 0x40080
	v_lshl_add_u64 v[144:145], v[224:225], 0, s[26:27]
	s_addc_u32 s1, s1, 0
	s_add_i32 s54, s82, s31
	global_load_lds_dwordx4 v[144:145], off
	v_lshl_add_u64 v[144:145], s[0:1], 0, v[130:131]
	s_mov_b32 m0, s54
	s_nop 0
	global_load_lds_dwordx4 v[144:145], off
	v_lshl_add_u64 v[144:145], s[0:1], 0, v[134:135]
	s_add_i32 m0, s54, 0x2000
	s_nop 0
	global_load_lds_dwordx4 v[144:145], off
	v_lshl_add_u64 v[144:145], v[226:227], 0, s[26:27]
	s_mov_b32 m0, s50
	s_nop 0
	global_load_lds_dwordx4 v[144:145], off
	v_lshl_add_u64 v[144:145], v[228:229], 0, s[26:27]
	s_mov_b32 m0, s51
	s_nop 0
	global_load_lds_dwordx4 v[144:145], off
	s_waitcnt vmcnt(8)
	s_waitcnt lgkmcnt(0)
	s_barrier
	s_setprio 1
	s_waitcnt lgkmcnt(0)
	v_mfma_f32_16x16x32_bf16 v[60:63], v[160:163], v[192:195], v[60:63]
	v_mfma_f32_16x16x32_bf16 v[52:55], v[168:171], v[192:195], v[52:55]
	v_mfma_f32_16x16x32_bf16 v[44:47], v[160:163], v[200:203], v[44:47]
	v_mfma_f32_16x16x32_bf16 v[36:39], v[168:171], v[200:203], v[36:39]
	v_mfma_f32_16x16x32_bf16 v[28:31], v[160:163], v[208:211], v[28:31]
	v_mfma_f32_16x16x32_bf16 v[20:23], v[168:171], v[208:211], v[20:23]
	v_mfma_f32_16x16x32_bf16 v[12:15], v[160:163], v[216:219], v[12:15]
	v_mfma_f32_16x16x32_bf16 v[4:7], v[168:171], v[216:219], v[4:7]
	v_mfma_f32_16x16x32_bf16 v[60:63], v[164:167], v[196:199], v[60:63]
	v_mfma_f32_16x16x32_bf16 v[52:55], v[172:175], v[196:199], v[52:55]
	v_mfma_f32_16x16x32_bf16 v[44:47], v[164:167], v[204:207], v[44:47]
	v_mfma_f32_16x16x32_bf16 v[36:39], v[172:175], v[204:207], v[36:39]
	v_mfma_f32_16x16x32_bf16 v[28:31], v[164:167], v[212:215], v[28:31]
	v_mfma_f32_16x16x32_bf16 v[20:23], v[172:175], v[212:215], v[20:23]
	v_mfma_f32_16x16x32_bf16 v[12:15], v[164:167], v[220:223], v[12:15]
	v_mfma_f32_16x16x32_bf16 v[4:7], v[172:175], v[220:223], v[4:7]
	s_setprio 0
	s_setprio 1
	v_mfma_f32_16x16x32_bf16 v[56:59], v[176:179], v[192:195], v[56:59]
	v_mfma_f32_16x16x32_bf16 v[48:51], v[184:187], v[192:195], v[48:51]
	v_mfma_f32_16x16x32_bf16 v[40:43], v[176:179], v[200:203], v[40:43]
	v_mfma_f32_16x16x32_bf16 v[32:35], v[184:187], v[200:203], v[32:35]
	v_mfma_f32_16x16x32_bf16 v[24:27], v[176:179], v[208:211], v[24:27]
	v_mfma_f32_16x16x32_bf16 v[16:19], v[184:187], v[208:211], v[16:19]
	v_mfma_f32_16x16x32_bf16 v[8:11], v[176:179], v[216:219], v[8:11]
	v_mfma_f32_16x16x32_bf16 v[0:3], v[184:187], v[216:219], v[0:3]
	v_mfma_f32_16x16x32_bf16 v[56:59], v[180:183], v[196:199], v[56:59]
	v_mfma_f32_16x16x32_bf16 v[48:51], v[188:191], v[196:199], v[48:51]
	v_mfma_f32_16x16x32_bf16 v[40:43], v[180:183], v[204:207], v[40:43]
	v_mfma_f32_16x16x32_bf16 v[32:35], v[188:191], v[204:207], v[32:35]
	v_mfma_f32_16x16x32_bf16 v[24:27], v[180:183], v[212:215], v[24:27]
	v_mfma_f32_16x16x32_bf16 v[16:19], v[188:191], v[212:215], v[16:19]
	v_mfma_f32_16x16x32_bf16 v[8:11], v[180:183], v[220:223], v[8:11]
	v_mfma_f32_16x16x32_bf16 v[0:3], v[188:191], v[220:223], v[0:3]
	s_setprio 0
	s_barrier
	s_add_i32 s80, s80, 2
	s_add_u32 s8, s8, 0x100
	s_addc_u32 s9, s9, 0
	s_add_u32 s78, s78, 0x100
	s_addc_u32 s79, s79, 0
	s_cmp_gt_u32 s80, 13
	s_cbranch_scc0 .LBB0_1200
	s_branch .Lmy_kdone_3

; #define PG8_STAGE(bufoff, gbase, voff) do { _Pragma("unroll") for (int _i = 0; _i < 2; ++_i) \
;         __builtin_amdgcn_global_load_lds((const unsigned*)((const char*)(gbase) + (voff)[_i]), (PG8_LAS unsigned*)(lds + (bufoff) + ldsw + _i * 8192), 16, 0, 0); } while (0)
; #define PG8_LDA(dst, b, h) do { _Pragma("unroll") for (int m = 0; m < 4; ++m) _Pragma("unroll") for (int k = 0; k < 2; ++k) dst[m][k] = *(const PG8_LAS bf16x8*)(lds + PG8_SA(b, h) + aoff + m * 2048 + k * 1024); } while (0)
; #define PG8_LDB(dst, b, h) do { _Pragma("unroll") for (int n = 0; n < 2; ++n) _Pragma("unroll") for (int k = 0; k < 2; ++k) dst[n][k] = *(const PG8_LAS bf16x8*)(lds + PG8_SB(b, h) + boff + n * 2048 + k * 1024); } while (0)
; #define PG8_MMA(ai, bj, At, Bt) do { __builtin_amdgcn_s_setprio(1); _Pragma("unroll") for (int m = 0; m < 4; ++m) _Pragma("unroll") for (int n = 0; n < 2; ++n) _Pragma("unroll") for (int k = 0; k < 2; ++k) \
;         acc[ai][bj][m][n] = __builtin_amdgcn_mfma_f32_16x16x32_bf16(Bt[n][k], At[m][k], acc[ai][bj][m][n], 0, 0, 0); __builtin_amdgcn_s_setprio(0); } while (0)
; #define PG8_WAIT_V(n) asm volatile("s_waitcnt vmcnt(" #n ")" ::: "memory")
; #define PG8_WAIT_L(n) asm volatile("s_waitcnt lgkmcnt(" #n ")" ::: "memory")
; #define PG8_BAR __builtin_amdgcn_s_barrier()
; template <class Epi, class Sched, bool ALIGN_EPI = false, bool SP2 = false>
; __device__ __forceinline__ void gemm_phase(PG8_LAS unsigned char* lds, const Gemm g, const Sched& S, const Epi& E, const int tid_in) {
;     ...
;         for (int t = 0; t < nt; t += 2) {
;             const bool last = (t == nt - 2);
;             const char* a1 = cA + (size_t)(t + 1) * kstep;
;             const char* a2 = last ? nA : cA + (size_t)(t + 2) * kstep; const char* b2 = last ? nB : cB + (size_t)(t + 2) * kstep;
;             const char* a3 = a2 + kstep; const char* b3 = b2 + kstep;
;             if (last && has_next) S.a_ready(nxt);
;             if constexpr (SP2) {
;             PG8_LDB(B0, 0, 0); PG8_LDB(B1, 0, 1); PG8_SCHED; PG8_LDA(At, 0, 0); PG8_STAGE(PG8_SA(1, 1), a1 + hstep, voffA);
;             PG8_WAIT_V(8); PG8_WAIT_L(0); PG8_BAR; PG8_MMA(0, 0, At, B0); PG8_MMA(0, 1, At, B1); PG8_BAR; PG8_SCHED;
;             PG8_LDA(At, 0, 1); PG8_STAGE(PG8_SB(0, 0), b2, voffB); PG8_STAGE(PG8_SB(0, 1), b2 + hstep, voffB); PG8_STAGE(PG8_SA(0, 0), a2, voffA);
.LBB0_1281:
	s_add_u32 s76, s76, 0x100
	v_mov_b32_e32 v0, 0
	s_addc_u32 s77, s77, 0
	s_mov_b32 s81, -2
	ds_read_b128 v[92:95], v207
	ds_read_b128 v[100:103], v207 offset:1024
	ds_read_b128 v[112:115], v207 offset:2048
	ds_read_b128 v[124:127], v207 offset:3072
	ds_read_b128 v[136:139], v208
	ds_read_b128 v[148:151], v208 offset:1024
	ds_read_b128 v[152:155], v208 offset:2048
	ds_read_b128 v[156:159], v208 offset:3072
	s_add_u32 s78, s56, 0x100
	s_addc_u32 s79, s57, 0
	s_cmp_eq_u32 s81, 40
	s_cselect_b32 s75, s9, s79
	s_cselect_b32 s74, s8, s78
	s_cselect_b32 s1, s55, s77
	s_cselect_b32 s0, s54, s76
	v_lshl_add_u64 v[214:215], s[56:57], 0, v[192:193]
	s_add_i32 m0, s31, 0xc000
	ds_read_b128 v[160:163], v209
	ds_read_b128 v[164:167], v209 offset:1024
	ds_read_b128 v[168:171], v209 offset:2048
	ds_read_b128 v[172:175], v209 offset:3072
	ds_read_b128 v[176:179], v209 offset:4096
	ds_read_b128 v[180:183], v209 offset:5120
	ds_read_b128 v[200:203], v209 offset:6144
	ds_read_b128 v[210:213], v209 offset:7168
	global_load_lds_dwordx4 v[214:215], off
	v_lshl_add_u64 v[214:215], s[56:57], 0, v[194:195]
	s_add_i32 m0, s31, 0xe000
	s_nop 0
	global_load_lds_dwordx4 v[214:215], off
	s_waitcnt vmcnt(8)
	s_waitcnt lgkmcnt(0)
	s_barrier
	s_setprio 1
	s_waitcnt lgkmcnt(0)
	v_mfma_f32_16x16x32_bf16 v[144:147], v[92:95], v[160:163], 0
	v_mfma_f32_16x16x32_bf16 v[140:143], v[112:115], v[160:163], 0
	v_mfma_f32_16x16x32_bf16 v[120:123], v[92:95], v[168:171], 0
	v_mfma_f32_16x16x32_bf16 v[116:119], v[112:115], v[168:171], 0
	v_mfma_f32_16x16x32_bf16 v[96:99], v[92:95], v[176:179], 0
	v_mfma_f32_16x16x32_bf16 v[88:91], v[112:115], v[176:179], 0
	v_mfma_f32_16x16x32_bf16 v[76:79], v[92:95], v[200:203], 0
	v_mfma_f32_16x16x32_bf16 v[72:75], v[112:115], v[200:203], 0
	v_mfma_f32_16x16x32_bf16 v[144:147], v[100:103], v[164:167], v[144:147]
	v_mfma_f32_16x16x32_bf16 v[140:143], v[124:127], v[164:167], v[140:143]
	v_mfma_f32_16x16x32_bf16 v[120:123], v[100:103], v[172:175], v[120:123]
	v_mfma_f32_16x16x32_bf16 v[116:119], v[124:127], v[172:175], v[116:119]
	v_mfma_f32_16x16x32_bf16 v[96:99], v[100:103], v[180:183], v[96:99]
	v_mfma_f32_16x16x32_bf16 v[88:91], v[124:127], v[180:183], v[88:91]
	v_mfma_f32_16x16x32_bf16 v[76:79], v[100:103], v[210:213], v[76:79]
	v_mfma_f32_16x16x32_bf16 v[72:75], v[124:127], v[210:213], v[72:75]
	s_setprio 0
	s_setprio 1
	v_mfma_f32_16x16x32_bf16 v[132:135], v[136:139], v[160:163], 0
	v_mfma_f32_16x16x32_bf16 v[128:131], v[152:155], v[160:163], 0
	v_mfma_f32_16x16x32_bf16 v[108:111], v[136:139], v[168:171], 0
	v_mfma_f32_16x16x32_bf16 v[104:107], v[152:155], v[168:171], 0
	v_mfma_f32_16x16x32_bf16 v[84:87], v[136:139], v[176:179], 0
	v_mfma_f32_16x16x32_bf16 v[80:83], v[152:155], v[176:179], 0
	v_mfma_f32_16x16x32_bf16 v[68:71], v[136:139], v[200:203], 0
	v_mfma_f32_16x16x32_bf16 v[64:67], v[152:155], v[200:203], 0
	v_mfma_f32_16x16x32_bf16 v[132:135], v[148:151], v[164:167], v[132:135]
	v_mfma_f32_16x16x32_bf16 v[128:131], v[156:159], v[164:167], v[128:131]
	v_mfma_f32_16x16x32_bf16 v[108:111], v[148:151], v[172:175], v[108:111]
	v_mfma_f32_16x16x32_bf16 v[104:107], v[156:159], v[172:175], v[104:107]
	v_mfma_f32_16x16x32_bf16 v[84:87], v[148:151], v[180:183], v[84:87]
	v_mfma_f32_16x16x32_bf16 v[80:83], v[156:159], v[180:183], v[80:83]
	v_mfma_f32_16x16x32_bf16 v[68:71], v[148:151], v[210:213], v[68:71]
	v_mfma_f32_16x16x32_bf16 v[64:67], v[156:159], v[210:213], v[64:67]
	s_setprio 0
	s_barrier
	s_add_i32 s56, s48, s30
	v_lshl_add_u64 v[214:215], s[0:1], 0, v[186:187]
	s_mov_b32 m0, s56
	ds_read_b128 v[160:163], v209 offset:16384
	ds_read_b128 v[164:167], v209 offset:17408
	ds_read_b128 v[168:171], v209 offset:18432
	ds_read_b128 v[172:175], v209 offset:19456
	ds_read_b128 v[176:179], v209 offset:20480
	ds_read_b128 v[180:183], v209 offset:21504
	ds_read_b128 v[200:203], v209 offset:22528
	ds_read_b128 v[210:213], v209 offset:23552
	global_load_lds_dwordx4 v[214:215], off
	s_add_i32 m0, s56, 0x2000
	s_add_u32 s56, s0, 0xb0000
	v_lshl_add_u64 v[216:217], s[0:1], 0, v[190:191]
	s_addc_u32 s57, s1, 0
	s_add_i32 s82, s49, s30
	global_load_lds_dwordx4 v[216:217], off
	v_lshl_add_u64 v[218:219], s[56:57], 0, v[186:187]
	s_mov_b32 m0, s82
	v_lshl_add_u64 v[220:221], s[74:75], 0, v[188:189]
	global_load_lds_dwordx4 v[218:219], off
	v_lshl_add_u64 v[218:219], s[56:57], 0, v[190:191]
	s_add_i32 m0, s82, 0x2000
	s_nop 0
	global_load_lds_dwordx4 v[218:219], off
	v_lshl_add_u64 v[218:219], s[74:75], 0, v[184:185]
	s_mov_b32 m0, s31
	s_nop 0
	global_load_lds_dwordx4 v[218:219], off
	s_mov_b32 m0, s34
	s_nop 0
	global_load_lds_dwordx4 v[220:221], off
	s_waitcnt vmcnt(8)
	s_waitcnt lgkmcnt(0)
	s_barrier
; #define PG8_STAGE(bufoff, gbase, voff) do { _Pragma("unroll") for (int _i = 0; _i < 2; ++_i) \
;         __builtin_amdgcn_global_load_lds((const unsigned*)((const char*)(gbase) + (voff)[_i]), (PG8_LAS unsigned*)(lds + (bufoff) + ldsw + _i * 8192), 16, 0, 0); } while (0)
; #define PG8_LDA(dst, b, h) do { _Pragma("unroll") for (int m = 0; m < 4; ++m) _Pragma("unroll") for (int k = 0; k < 2; ++k) dst[m][k] = *(const PG8_LAS bf16x8*)(lds + PG8_SA(b, h) + aoff + m * 2048 + k * 1024); } while (0)
; #define PG8_LDB(dst, b, h) do { _Pragma("unroll") for (int n = 0; n < 2; ++n) _Pragma("unroll") for (int k = 0; k < 2; ++k) dst[n][k] = *(const PG8_LAS bf16x8*)(lds + PG8_SB(b, h) + boff + n * 2048 + k * 1024); } while (0)
; #define PG8_MMA(ai, bj, At, Bt) do { __builtin_amdgcn_s_setprio(1); _Pragma("unroll") for (int m = 0; m < 4; ++m) _Pragma("unroll") for (int n = 0; n < 2; ++n) _Pragma("unroll") for (int k = 0; k < 2; ++k) \
;         acc[ai][bj][m][n] = __builtin_amdgcn_mfma_f32_16x16x32_bf16(Bt[n][k], At[m][k], acc[ai][bj][m][n], 0, 0, 0); __builtin_amdgcn_s_setprio(0); } while (0)
; #define PG8_WAIT_V(n) asm volatile("s_waitcnt vmcnt(" #n ")" ::: "memory")
; #define PG8_WAIT_L(n) asm volatile("s_waitcnt lgkmcnt(" #n ")" ::: "memory")
; #define PG8_BAR __builtin_amdgcn_s_barrier()
; #define PG8_SCHED __builtin_amdgcn_sched_barrier(0)
; template <class Epi, class Sched, bool ALIGN_EPI = false, bool SP2 = false>
; __device__ __forceinline__ void gemm_phase(PG8_LAS unsigned char* lds, const Gemm g, const Sched& S, const Epi& E, const int tid_in) {
;     ...
;             PG8_WAIT_V(8); PG8_WAIT_L(0); PG8_BAR; PG8_MMA(1, 0, At, B0); PG8_MMA(1, 1, At, B1); PG8_BAR; PG8_SCHED;
;             PG8_LDB(B0, 1, 0); PG8_LDB(B1, 1, 1); PG8_SCHED; PG8_LDA(At, 1, 0); PG8_STAGE(PG8_SA(0, 1), a2 + hstep, voffA);
;             PG8_WAIT_V(8); PG8_WAIT_L(0); PG8_BAR; PG8_MMA(0, 0, At, B0); PG8_MMA(0, 1, At, B1); PG8_BAR; PG8_SCHED;
	s_setprio 1
	s_waitcnt lgkmcnt(0)
	v_mfma_f32_16x16x32_bf16 v[60:63], v[92:95], v[160:163], 0
	v_mfma_f32_16x16x32_bf16 v[56:59], v[112:115], v[160:163], 0
	v_mfma_f32_16x16x32_bf16 v[44:47], v[92:95], v[168:171], 0
	v_mfma_f32_16x16x32_bf16 v[40:43], v[112:115], v[168:171], 0
	v_mfma_f32_16x16x32_bf16 v[28:31], v[92:95], v[176:179], 0
	v_mfma_f32_16x16x32_bf16 v[24:27], v[112:115], v[176:179], 0
	v_mfma_f32_16x16x32_bf16 v[12:15], v[92:95], v[200:203], 0
	v_mfma_f32_16x16x32_bf16 v[8:11], v[112:115], v[200:203], 0
	v_mfma_f32_16x16x32_bf16 v[60:63], v[100:103], v[164:167], v[60:63]
	v_mfma_f32_16x16x32_bf16 v[56:59], v[124:127], v[164:167], v[56:59]
	v_mfma_f32_16x16x32_bf16 v[44:47], v[100:103], v[172:175], v[44:47]
	v_mfma_f32_16x16x32_bf16 v[40:43], v[124:127], v[172:175], v[40:43]
	v_mfma_f32_16x16x32_bf16 v[28:31], v[100:103], v[180:183], v[28:31]
	v_mfma_f32_16x16x32_bf16 v[24:27], v[124:127], v[180:183], v[24:27]
	v_mfma_f32_16x16x32_bf16 v[12:15], v[100:103], v[210:213], v[12:15]
	v_mfma_f32_16x16x32_bf16 v[8:11], v[124:127], v[210:213], v[8:11]
	s_setprio 0
	s_setprio 1
	v_mfma_f32_16x16x32_bf16 v[52:55], v[136:139], v[160:163], 0
	v_mfma_f32_16x16x32_bf16 v[48:51], v[152:155], v[160:163], 0
	v_mfma_f32_16x16x32_bf16 v[36:39], v[136:139], v[168:171], 0
	v_mfma_f32_16x16x32_bf16 v[32:35], v[152:155], v[168:171], 0
	v_mfma_f32_16x16x32_bf16 v[20:23], v[136:139], v[176:179], 0
	v_mfma_f32_16x16x32_bf16 v[16:19], v[152:155], v[176:179], 0
	v_mfma_f32_16x16x32_bf16 v[4:7], v[136:139], v[200:203], 0
	v_mfma_f32_16x16x32_bf16 v[0:3], v[152:155], v[200:203], 0
	v_mfma_f32_16x16x32_bf16 v[52:55], v[148:151], v[164:167], v[52:55]
	v_mfma_f32_16x16x32_bf16 v[48:51], v[156:159], v[164:167], v[48:51]
	v_mfma_f32_16x16x32_bf16 v[36:39], v[148:151], v[172:175], v[36:39]
	v_mfma_f32_16x16x32_bf16 v[32:35], v[156:159], v[172:175], v[32:35]
	v_mfma_f32_16x16x32_bf16 v[20:23], v[148:151], v[180:183], v[20:23]
	v_mfma_f32_16x16x32_bf16 v[16:19], v[156:159], v[180:183], v[16:19]
	v_mfma_f32_16x16x32_bf16 v[4:7], v[148:151], v[210:213], v[4:7]
	v_mfma_f32_16x16x32_bf16 v[0:3], v[156:159], v[210:213], v[0:3]
	s_setprio 0
	s_barrier
	s_add_i32 s82, 0, 0x18000
	s_add_i32 s83, 0, 0x1c000
	v_add_u32_e32 v124, s82, v205
	v_add_u32_e32 v156, s83, v205
	ds_read_b128 v[92:95], v124
	ds_read_b128 v[100:103], v124 offset:1024
	ds_read_b128 v[112:115], v124 offset:2048
	ds_read_b128 v[124:127], v124 offset:3072
	ds_read_b128 v[136:139], v156
	ds_read_b128 v[148:151], v156 offset:1024
	ds_read_b128 v[152:155], v156 offset:2048
	ds_read_b128 v[156:159], v156 offset:3072
	s_add_u32 s56, s74, 0xb0000
	s_addc_u32 s57, s75, 0
	s_mov_b32 m0, s35
	v_lshl_add_u64 v[222:223], s[56:57], 0, v[184:185]
	ds_read_b128 v[160:163], v209 offset:32768
	ds_read_b128 v[164:167], v209 offset:33792
	ds_read_b128 v[168:171], v209 offset:34816
	ds_read_b128 v[172:175], v209 offset:35840
	ds_read_b128 v[176:179], v209 offset:36864
	ds_read_b128 v[180:183], v209 offset:37888
	ds_read_b128 v[200:203], v209 offset:38912
	ds_read_b128 v[210:213], v209 offset:39936
	global_load_lds_dwordx4 v[222:223], off
	v_lshl_add_u64 v[222:223], s[56:57], 0, v[188:189]
	s_mov_b32 m0, s36
	s_nop 0
	global_load_lds_dwordx4 v[222:223], off
	s_waitcnt vmcnt(8)
	s_waitcnt lgkmcnt(0)
	s_barrier
	s_setprio 1
	s_waitcnt lgkmcnt(0)
	v_mfma_f32_16x16x32_bf16 v[144:147], v[92:95], v[160:163], v[144:147]
	v_mfma_f32_16x16x32_bf16 v[140:143], v[112:115], v[160:163], v[140:143]
	v_mfma_f32_16x16x32_bf16 v[120:123], v[92:95], v[168:171], v[120:123]
	v_mfma_f32_16x16x32_bf16 v[116:119], v[112:115], v[168:171], v[116:119]
	v_mfma_f32_16x16x32_bf16 v[96:99], v[92:95], v[176:179], v[96:99]
	v_mfma_f32_16x16x32_bf16 v[88:91], v[112:115], v[176:179], v[88:91]
	v_mfma_f32_16x16x32_bf16 v[76:79], v[92:95], v[200:203], v[76:79]
	v_mfma_f32_16x16x32_bf16 v[72:75], v[112:115], v[200:203], v[72:75]
	v_mfma_f32_16x16x32_bf16 v[144:147], v[100:103], v[164:167], v[144:147]
	v_mfma_f32_16x16x32_bf16 v[140:143], v[124:127], v[164:167], v[140:143]
	v_mfma_f32_16x16x32_bf16 v[120:123], v[100:103], v[172:175], v[120:123]
	v_mfma_f32_16x16x32_bf16 v[116:119], v[124:127], v[172:175], v[116:119]
	v_mfma_f32_16x16x32_bf16 v[96:99], v[100:103], v[180:183], v[96:99]
	v_mfma_f32_16x16x32_bf16 v[88:91], v[124:127], v[180:183], v[88:91]
	v_mfma_f32_16x16x32_bf16 v[76:79], v[100:103], v[210:213], v[76:79]
	v_mfma_f32_16x16x32_bf16 v[72:75], v[124:127], v[210:213], v[72:75]
	s_setprio 0
	s_setprio 1
	v_mfma_f32_16x16x32_bf16 v[132:135], v[136:139], v[160:163], v[132:135]
	v_mfma_f32_16x16x32_bf16 v[128:131], v[152:155], v[160:163], v[128:131]
	v_mfma_f32_16x16x32_bf16 v[108:111], v[136:139], v[168:171], v[108:111]
	v_mfma_f32_16x16x32_bf16 v[104:107], v[152:155], v[168:171], v[104:107]
	v_mfma_f32_16x16x32_bf16 v[84:87], v[136:139], v[176:179], v[84:87]
	v_mfma_f32_16x16x32_bf16 v[80:83], v[152:155], v[176:179], v[80:83]
	v_mfma_f32_16x16x32_bf16 v[68:71], v[136:139], v[200:203], v[68:71]
	v_mfma_f32_16x16x32_bf16 v[64:67], v[152:155], v[200:203], v[64:67]
	v_mfma_f32_16x16x32_bf16 v[132:135], v[148:151], v[164:167], v[132:135]
	v_mfma_f32_16x16x32_bf16 v[128:131], v[156:159], v[164:167], v[128:131]
	v_mfma_f32_16x16x32_bf16 v[108:111], v[148:151], v[172:175], v[108:111]
	v_mfma_f32_16x16x32_bf16 v[104:107], v[156:159], v[172:175], v[104:107]
	v_mfma_f32_16x16x32_bf16 v[84:87], v[148:151], v[180:183], v[84:87]
	v_mfma_f32_16x16x32_bf16 v[80:83], v[156:159], v[180:183], v[80:83]
	v_mfma_f32_16x16x32_bf16 v[68:71], v[148:151], v[210:213], v[68:71]
	v_mfma_f32_16x16x32_bf16 v[64:67], v[156:159], v[210:213], v[64:67]
	s_setprio 0
	s_barrier
; #define PG8_STAGE(bufoff, gbase, voff) do { _Pragma("unroll") for (int _i = 0; _i < 2; ++_i) \
;         __builtin_amdgcn_global_load_lds((const unsigned*)((const char*)(gbase) + (voff)[_i]), (PG8_LAS unsigned*)(lds + (bufoff) + ldsw + _i * 8192), 16, 0, 0); } while (0)
; #define PG8_LDA(dst, b, h) do { _Pragma("unroll") for (int m = 0; m < 4; ++m) _Pragma("unroll") for (int k = 0; k < 2; ++k) dst[m][k] = *(const PG8_LAS bf16x8*)(lds + PG8_SA(b, h) + aoff + m * 2048 + k * 1024); } while (0)
; #define PG8_MMA(ai, bj, At, Bt) do { __builtin_amdgcn_s_setprio(1); _Pragma("unroll") for (int m = 0; m < 4; ++m) _Pragma("unroll") for (int n = 0; n < 2; ++n) _Pragma("unroll") for (int k = 0; k < 2; ++k) \
;         acc[ai][bj][m][n] = __builtin_amdgcn_mfma_f32_16x16x32_bf16(Bt[n][k], At[m][k], acc[ai][bj][m][n], 0, 0, 0); __builtin_amdgcn_s_setprio(0); } while (0)
; #define PG8_WAIT_V(n) asm volatile("s_waitcnt vmcnt(" #n ")" ::: "memory")
; #define PG8_WAIT_L(n) asm volatile("s_waitcnt lgkmcnt(" #n ")" ::: "memory")
; #define PG8_BAR __builtin_amdgcn_s_barrier()
; #define PG8_SCHED __builtin_amdgcn_sched_barrier(0)
; template <class Epi, class Sched, bool ALIGN_EPI = false, bool SP2 = false>
; __device__ __forceinline__ void gemm_phase(PG8_LAS unsigned char* lds, const Gemm g, const Sched& S, const Epi& E, const int tid_in) {
;     ...
;             PG8_LDA(At, 1, 1); PG8_STAGE(PG8_SB(1, 0), b3, voffB); PG8_STAGE(PG8_SB(1, 1), b3 + hstep, voffB); PG8_STAGE(PG8_SA(1, 0), a3, voffA);
;             PG8_WAIT_V(8); PG8_WAIT_L(0); PG8_BAR; PG8_MMA(1, 0, At, B0); PG8_MMA(1, 1, At, B1); PG8_BAR; PG8_SCHED;
	s_add_i32 s56, s82, s30
	v_lshl_add_u64 v[214:215], v[214:215], 0, s[46:47]
	s_mov_b32 m0, s56
	ds_read_b128 v[160:163], v209 offset:49152
	ds_read_b128 v[164:167], v209 offset:50176
	ds_read_b128 v[168:171], v209 offset:51200
	ds_read_b128 v[172:175], v209 offset:52224
	ds_read_b128 v[176:179], v209 offset:53248
	ds_read_b128 v[180:183], v209 offset:54272
	ds_read_b128 v[200:203], v209 offset:55296
	ds_read_b128 v[210:213], v209 offset:56320
	global_load_lds_dwordx4 v[214:215], off
	s_add_i32 m0, s56, 0x2000
	s_add_u32 s0, s0, 0xb0080
	v_lshl_add_u64 v[214:215], v[216:217], 0, s[46:47]
	s_addc_u32 s1, s1, 0
	s_add_i32 s56, s83, s30
	global_load_lds_dwordx4 v[214:215], off
	v_lshl_add_u64 v[214:215], s[0:1], 0, v[186:187]
	s_mov_b32 m0, s56
	s_nop 0
	global_load_lds_dwordx4 v[214:215], off
	v_lshl_add_u64 v[214:215], s[0:1], 0, v[190:191]
	s_add_i32 m0, s56, 0x2000
	s_nop 0
	global_load_lds_dwordx4 v[214:215], off
	v_lshl_add_u64 v[214:215], v[218:219], 0, s[46:47]
	s_mov_b32 m0, s38
	s_nop 0
	global_load_lds_dwordx4 v[214:215], off
	v_lshl_add_u64 v[214:215], v[220:221], 0, s[46:47]
	s_mov_b32 m0, s39
	s_nop 0
	global_load_lds_dwordx4 v[214:215], off
	s_waitcnt vmcnt(8)
	s_waitcnt lgkmcnt(0)
	s_barrier
	s_setprio 1
	s_waitcnt lgkmcnt(0)
	v_mfma_f32_16x16x32_bf16 v[60:63], v[92:95], v[160:163], v[60:63]
	v_mfma_f32_16x16x32_bf16 v[56:59], v[112:115], v[160:163], v[56:59]
	v_mfma_f32_16x16x32_bf16 v[44:47], v[92:95], v[168:171], v[44:47]
	v_mfma_f32_16x16x32_bf16 v[40:43], v[112:115], v[168:171], v[40:43]
	v_mfma_f32_16x16x32_bf16 v[28:31], v[92:95], v[176:179], v[28:31]
	v_mfma_f32_16x16x32_bf16 v[24:27], v[112:115], v[176:179], v[24:27]
	v_mfma_f32_16x16x32_bf16 v[12:15], v[92:95], v[200:203], v[12:15]
	v_mfma_f32_16x16x32_bf16 v[8:11], v[112:115], v[200:203], v[8:11]
	v_mfma_f32_16x16x32_bf16 v[60:63], v[100:103], v[164:167], v[60:63]
	v_mfma_f32_16x16x32_bf16 v[56:59], v[124:127], v[164:167], v[56:59]
	v_mfma_f32_16x16x32_bf16 v[44:47], v[100:103], v[172:175], v[44:47]
	v_mfma_f32_16x16x32_bf16 v[40:43], v[124:127], v[172:175], v[40:43]
	v_mfma_f32_16x16x32_bf16 v[28:31], v[100:103], v[180:183], v[28:31]
	v_mfma_f32_16x16x32_bf16 v[24:27], v[124:127], v[180:183], v[24:27]
	v_mfma_f32_16x16x32_bf16 v[12:15], v[100:103], v[210:213], v[12:15]
	v_mfma_f32_16x16x32_bf16 v[8:11], v[124:127], v[210:213], v[8:11]
	s_setprio 0
	s_setprio 1
	v_mfma_f32_16x16x32_bf16 v[52:55], v[136:139], v[160:163], v[52:55]
	v_mfma_f32_16x16x32_bf16 v[48:51], v[152:155], v[160:163], v[48:51]
	v_mfma_f32_16x16x32_bf16 v[36:39], v[136:139], v[168:171], v[36:39]
	v_mfma_f32_16x16x32_bf16 v[32:35], v[152:155], v[168:171], v[32:35]
	v_mfma_f32_16x16x32_bf16 v[20:23], v[136:139], v[176:179], v[20:23]
	v_mfma_f32_16x16x32_bf16 v[16:19], v[152:155], v[176:179], v[16:19]
	v_mfma_f32_16x16x32_bf16 v[4:7], v[136:139], v[200:203], v[4:7]
	v_mfma_f32_16x16x32_bf16 v[0:3], v[152:155], v[200:203], v[0:3]
	v_mfma_f32_16x16x32_bf16 v[52:55], v[148:151], v[164:167], v[52:55]
	v_mfma_f32_16x16x32_bf16 v[48:51], v[156:159], v[164:167], v[48:51]
	v_mfma_f32_16x16x32_bf16 v[36:39], v[148:151], v[172:175], v[36:39]
	v_mfma_f32_16x16x32_bf16 v[32:35], v[156:159], v[172:175], v[32:35]
	v_mfma_f32_16x16x32_bf16 v[20:23], v[148:151], v[180:183], v[20:23]
	v_mfma_f32_16x16x32_bf16 v[16:19], v[156:159], v[180:183], v[16:19]
	v_mfma_f32_16x16x32_bf16 v[4:7], v[148:151], v[210:213], v[4:7]
	v_mfma_f32_16x16x32_bf16 v[0:3], v[156:159], v[210:213], v[0:3]
	s_setprio 0
	s_barrier
	s_add_i32 s81, s81, 2
	s_add_u32 s76, s76, 0x100
	s_addc_u32 s77, s77, 0
	s_cmp_gt_u32 s81, 41
	s_mov_b64 s[56:57], s[78:79]
	s_cbranch_scc0 .LBB0_1282
	s_branch .Lmy_kdone_4

; #define PG8_BAR __builtin_amdgcn_s_barrier()
; template <class Epi, class Sched, bool ALIGN_EPI = false, bool SP2 = false>
; __device__ __forceinline__ void gemm_phase(PG8_LAS unsigned char* lds, const Gemm g, const Sched& S, const Epi& E, const int tid_in) {
;     ...
;         if constexpr (ALIGN_EPI) { if (wr == 0) PG8_BAR; }
.Lmy_kdone_4:
	s_and_b64 vcc, exec, s[52:53]
	s_cbranch_vccz .LBB0_1285
	s_barrier

; #define PG8_STAGE(bufoff, gbase, voff) do { _Pragma("unroll") for (int _i = 0; _i < 2; ++_i) \
;         __builtin_amdgcn_global_load_lds((const unsigned*)((const char*)(gbase) + (voff)[_i]), (PG8_LAS unsigned*)(lds + (bufoff) + ldsw + _i * 8192), 16, 0, 0); } while (0)
; #define PG8_LDA(dst, b, h) do { _Pragma("unroll") for (int m = 0; m < 4; ++m) _Pragma("unroll") for (int k = 0; k < 2; ++k) dst[m][k] = *(const PG8_LAS bf16x8*)(lds + PG8_SA(b, h) + aoff + m * 2048 + k * 1024); } while (0)
; #define PG8_LDB(dst, b, h) do { _Pragma("unroll") for (int n = 0; n < 2; ++n) _Pragma("unroll") for (int k = 0; k < 2; ++k) dst[n][k] = *(const PG8_LAS bf16x8*)(lds + PG8_SB(b, h) + boff + n * 2048 + k * 1024); } while (0)
; #define PG8_MMA(ai, bj, At, Bt) do { __builtin_amdgcn_s_setprio(1); _Pragma("unroll") for (int m = 0; m < 4; ++m) _Pragma("unroll") for (int n = 0; n < 2; ++n) _Pragma("unroll") for (int k = 0; k < 2; ++k) \
;         acc[ai][bj][m][n] = __builtin_amdgcn_mfma_f32_16x16x32_bf16(Bt[n][k], At[m][k], acc[ai][bj][m][n], 0, 0, 0); __builtin_amdgcn_s_setprio(0); } while (0)
; #define PG8_WAIT_V(n) asm volatile("s_waitcnt vmcnt(" #n ")" ::: "memory")
; template <class Epi, class Sched, bool ALIGN_EPI = false, bool SP2 = false>
; __device__ __forceinline__ void gemm_phase(PG8_LAS unsigned char* lds, const Gemm g, const Sched& S, const Epi& E, const int tid_in) {
;     ...
;         const char* nA = has_next ? (const char*)g.A + (size_t)nxt.pm * tstep : cA; const char* nB = has_next ? (const char*)g.Bt + (size_t)nxt.pn * tstep : cB;
;         for (int t = 0; t < nt; t += 2) {
;             const bool last = (t == nt - 2);
;             const char* a1 = cA + (size_t)(t + 1) * kstep;
;             const char* a2 = last ? nA : cA + (size_t)(t + 2) * kstep; const char* b2 = last ? nB : cB + (size_t)(t + 2) * kstep;
;             const char* a3 = a2 + kstep; const char* b3 = b2 + kstep;
;             if (last && has_next) S.a_ready(nxt);
;             if constexpr (SP2) {
;             PG8_LDB(B0, 0, 0); PG8_LDB(B1, 0, 1); PG8_SCHED; PG8_LDA(At, 0, 0); PG8_STAGE(PG8_SA(1, 1), a1 + hstep, voffA);
;             PG8_WAIT_V(8); PG8_WAIT_L(0); PG8_BAR; PG8_MMA(0, 0, At, B0); PG8_MMA(0, 1, At, B1); PG8_BAR; PG8_SCHED;
;             PG8_LDA(At, 0, 1); PG8_STAGE(PG8_SB(0, 0), b2, voffB); PG8_STAGE(PG8_SB(0, 1), b2 + hstep, voffB); PG8_STAGE(PG8_SA(0, 0), a2, voffA);
.LBB0_1794:
	s_ashr_i32 s57, s56, 31
	s_lshl_b64 s[10:11], s[56:57], 19
	s_add_u32 s66, s5, s10
	s_addc_u32 s67, s30, s11
	s_and_b64 s[10:11], s[6:7], exec
	s_cselect_b32 s9, s67, s1
	s_cselect_b32 s14, s66, s0
	s_ashr_i32 s55, s54, 31
	s_lshl_b64 s[10:11], s[54:55], 19
	s_add_u32 s68, s3, s10
	s_addc_u32 s69, s4, s11
	s_and_b64 s[10:11], s[6:7], exec
	s_cselect_b32 s15, s69, s13
	s_cselect_b32 s16, s68, s12
	s_add_u32 s10, s0, 0x40080
	s_addc_u32 s11, s1, 0
	s_add_u32 s55, s12, 0x100
	v_mov_b32_e32 v0, 0
	s_addc_u32 s57, s13, 0
	s_mov_b32 s65, -2
	ds_read_b128 v[128:131], v204
	ds_read_b128 v[132:135], v204 offset:1024
	s_waitcnt lgkmcnt(0)
	ds_read_b128 v[156:159], v204 offset:2048
	ds_read_b128 v[160:163], v204 offset:3072
	ds_read_b128 v[164:167], v205
	ds_read_b128 v[168:171], v205 offset:1024
	ds_read_b128 v[172:175], v205 offset:2048
	ds_read_b128 v[176:179], v205 offset:3072
	s_add_u32 s0, s10, 0xfffc0080
	s_addc_u32 s1, s11, -1
	s_cmp_eq_u32 s65, 12
	s_cselect_b32 s13, s9, s1
	s_cselect_b32 s12, s14, s0
	s_cselect_b32 s1, s15, s57
	s_cselect_b32 s0, s16, s55
	v_lshl_add_u64 v[192:193], s[10:11], 0, v[148:149]
	s_add_i32 m0, s31, 0xc000
	ds_read_b128 v[180:183], v206
	ds_read_b128 v[184:187], v206 offset:1024
	ds_read_b128 v[188:191], v206 offset:2048
	ds_read_b128 v[210:213], v206 offset:3072
	ds_read_b128 v[214:217], v206 offset:4096
	ds_read_b128 v[218:221], v206 offset:5120
	ds_read_b128 v[222:225], v206 offset:6144
	ds_read_b128 v[226:229], v206 offset:7168
	global_load_lds_dwordx4 v[192:193], off
	v_lshl_add_u64 v[192:193], s[10:11], 0, v[150:151]
	s_add_i32 m0, s31, 0xe000
	s_nop 0
	global_load_lds_dwordx4 v[192:193], off
	s_waitcnt vmcnt(8)
	s_waitcnt lgkmcnt(0)
	s_barrier
	s_setprio 1
	s_waitcnt lgkmcnt(0)
	v_mfma_f32_16x16x32_bf16 v[124:127], v[128:131], v[180:183], 0
	v_mfma_f32_16x16x32_bf16 v[120:123], v[156:159], v[180:183], 0
	v_mfma_f32_16x16x32_bf16 v[108:111], v[128:131], v[188:191], 0
	v_mfma_f32_16x16x32_bf16 v[104:107], v[156:159], v[188:191], 0
	v_mfma_f32_16x16x32_bf16 v[92:95], v[128:131], v[214:217], 0
	v_mfma_f32_16x16x32_bf16 v[88:91], v[156:159], v[214:217], 0
	v_mfma_f32_16x16x32_bf16 v[76:79], v[128:131], v[222:225], 0
	v_mfma_f32_16x16x32_bf16 v[72:75], v[156:159], v[222:225], 0
	v_mfma_f32_16x16x32_bf16 v[124:127], v[132:135], v[184:187], v[124:127]
	v_mfma_f32_16x16x32_bf16 v[120:123], v[160:163], v[184:187], v[120:123]
	v_mfma_f32_16x16x32_bf16 v[108:111], v[132:135], v[210:213], v[108:111]
	v_mfma_f32_16x16x32_bf16 v[104:107], v[160:163], v[210:213], v[104:107]
	v_mfma_f32_16x16x32_bf16 v[92:95], v[132:135], v[218:221], v[92:95]
	v_mfma_f32_16x16x32_bf16 v[88:91], v[160:163], v[218:221], v[88:91]
	v_mfma_f32_16x16x32_bf16 v[76:79], v[132:135], v[226:229], v[76:79]
	v_mfma_f32_16x16x32_bf16 v[72:75], v[160:163], v[226:229], v[72:75]
	s_setprio 0
	s_setprio 1
	v_mfma_f32_16x16x32_bf16 v[116:119], v[164:167], v[180:183], 0
	v_mfma_f32_16x16x32_bf16 v[112:115], v[172:175], v[180:183], 0
	v_mfma_f32_16x16x32_bf16 v[100:103], v[164:167], v[188:191], 0
	v_mfma_f32_16x16x32_bf16 v[96:99], v[172:175], v[188:191], 0
	v_mfma_f32_16x16x32_bf16 v[84:87], v[164:167], v[214:217], 0
	v_mfma_f32_16x16x32_bf16 v[80:83], v[172:175], v[214:217], 0
	v_mfma_f32_16x16x32_bf16 v[68:71], v[164:167], v[222:225], 0
	v_mfma_f32_16x16x32_bf16 v[64:67], v[172:175], v[222:225], 0
	v_mfma_f32_16x16x32_bf16 v[116:119], v[168:171], v[184:187], v[116:119]
	v_mfma_f32_16x16x32_bf16 v[112:115], v[176:179], v[184:187], v[112:115]
	v_mfma_f32_16x16x32_bf16 v[100:103], v[168:171], v[210:213], v[100:103]
	v_mfma_f32_16x16x32_bf16 v[96:99], v[176:179], v[210:213], v[96:99]
	v_mfma_f32_16x16x32_bf16 v[84:87], v[168:171], v[218:221], v[84:87]
	v_mfma_f32_16x16x32_bf16 v[80:83], v[176:179], v[218:221], v[80:83]
	v_mfma_f32_16x16x32_bf16 v[68:71], v[168:171], v[226:229], v[68:71]
	v_mfma_f32_16x16x32_bf16 v[64:67], v[176:179], v[226:229], v[64:67]
	s_setprio 0
	s_barrier
	s_add_i32 s74, s49, s2
	v_lshl_add_u64 v[192:193], s[0:1], 0, v[136:137]
	s_mov_b32 m0, s74
	ds_read_b128 v[180:183], v206 offset:16384
	ds_read_b128 v[184:187], v206 offset:17408
	ds_read_b128 v[188:191], v206 offset:18432
	ds_read_b128 v[210:213], v206 offset:19456
	ds_read_b128 v[214:217], v206 offset:20480
	ds_read_b128 v[218:221], v206 offset:21504
	ds_read_b128 v[222:225], v206 offset:22528
	ds_read_b128 v[226:229], v206 offset:23552
	global_load_lds_dwordx4 v[192:193], off
	s_add_i32 m0, s74, 0x2000
	s_add_u32 s74, s0, 0x40000
	v_lshl_add_u64 v[230:231], s[0:1], 0, v[138:139]
	s_addc_u32 s75, s1, 0
	s_add_i32 s76, s50, s2
	global_load_lds_dwordx4 v[230:231], off
	v_lshl_add_u64 v[232:233], s[74:75], 0, v[136:137]
	s_mov_b32 m0, s76
	v_lshl_add_u64 v[234:235], s[12:13], 0, v[138:139]
	global_load_lds_dwordx4 v[232:233], off
	v_lshl_add_u64 v[232:233], s[74:75], 0, v[138:139]
	s_add_i32 m0, s76, 0x2000
	s_nop 0
	global_load_lds_dwordx4 v[232:233], off
	v_lshl_add_u64 v[232:233], s[12:13], 0, v[136:137]
	s_mov_b32 m0, s31
	s_nop 0
	global_load_lds_dwordx4 v[232:233], off
	s_mov_b32 m0, s34
	s_nop 0
	global_load_lds_dwordx4 v[234:235], off
	s_waitcnt vmcnt(8)
	s_waitcnt lgkmcnt(0)
	s_barrier
; #define PG8_STAGE(bufoff, gbase, voff) do { _Pragma("unroll") for (int _i = 0; _i < 2; ++_i) \
;         __builtin_amdgcn_global_load_lds((const unsigned*)((const char*)(gbase) + (voff)[_i]), (PG8_LAS unsigned*)(lds + (bufoff) + ldsw + _i * 8192), 16, 0, 0); } while (0)
; #define PG8_LDA(dst, b, h) do { _Pragma("unroll") for (int m = 0; m < 4; ++m) _Pragma("unroll") for (int k = 0; k < 2; ++k) dst[m][k] = *(const PG8_LAS bf16x8*)(lds + PG8_SA(b, h) + aoff + m * 2048 + k * 1024); } while (0)
; #define PG8_LDB(dst, b, h) do { _Pragma("unroll") for (int n = 0; n < 2; ++n) _Pragma("unroll") for (int k = 0; k < 2; ++k) dst[n][k] = *(const PG8_LAS bf16x8*)(lds + PG8_SB(b, h) + boff + n * 2048 + k * 1024); } while (0)
; #define PG8_MMA(ai, bj, At, Bt) do { __builtin_amdgcn_s_setprio(1); _Pragma("unroll") for (int m = 0; m < 4; ++m) _Pragma("unroll") for (int n = 0; n < 2; ++n) _Pragma("unroll") for (int k = 0; k < 2; ++k) \
;         acc[ai][bj][m][n] = __builtin_amdgcn_mfma_f32_16x16x32_bf16(Bt[n][k], At[m][k], acc[ai][bj][m][n], 0, 0, 0); __builtin_amdgcn_s_setprio(0); } while (0)
; #define PG8_WAIT_V(n) asm volatile("s_waitcnt vmcnt(" #n ")" ::: "memory")
; #define PG8_WAIT_L(n) asm volatile("s_waitcnt lgkmcnt(" #n ")" ::: "memory")
; #define PG8_BAR __builtin_amdgcn_s_barrier()
; #define PG8_SCHED __builtin_amdgcn_sched_barrier(0)
; template <class Epi, class Sched, bool ALIGN_EPI = false, bool SP2 = false>
; __device__ __forceinline__ void gemm_phase(PG8_LAS unsigned char* lds, const Gemm g, const Sched& S, const Epi& E, const int tid_in) {
;     ...
;             PG8_WAIT_V(8); PG8_WAIT_L(0); PG8_BAR; PG8_MMA(1, 0, At, B0); PG8_MMA(1, 1, At, B1); PG8_BAR; PG8_SCHED;
;             PG8_LDB(B0, 1, 0); PG8_LDB(B1, 1, 1); PG8_SCHED; PG8_LDA(At, 1, 0); PG8_STAGE(PG8_SA(0, 1), a2 + hstep, voffA);
;             PG8_WAIT_V(8); PG8_WAIT_L(0); PG8_BAR; PG8_MMA(0, 0, At, B0); PG8_MMA(0, 1, At, B1); PG8_BAR; PG8_SCHED;
	s_setprio 1
	s_waitcnt lgkmcnt(0)
	v_mfma_f32_16x16x32_bf16 v[60:63], v[128:131], v[180:183], 0
	v_mfma_f32_16x16x32_bf16 v[56:59], v[156:159], v[180:183], 0
	v_mfma_f32_16x16x32_bf16 v[44:47], v[128:131], v[188:191], 0
	v_mfma_f32_16x16x32_bf16 v[40:43], v[156:159], v[188:191], 0
	v_mfma_f32_16x16x32_bf16 v[28:31], v[128:131], v[214:217], 0
	v_mfma_f32_16x16x32_bf16 v[24:27], v[156:159], v[214:217], 0
	v_mfma_f32_16x16x32_bf16 v[12:15], v[128:131], v[222:225], 0
	v_mfma_f32_16x16x32_bf16 v[8:11], v[156:159], v[222:225], 0
	v_mfma_f32_16x16x32_bf16 v[60:63], v[132:135], v[184:187], v[60:63]
	v_mfma_f32_16x16x32_bf16 v[56:59], v[160:163], v[184:187], v[56:59]
	v_mfma_f32_16x16x32_bf16 v[44:47], v[132:135], v[210:213], v[44:47]
	v_mfma_f32_16x16x32_bf16 v[40:43], v[160:163], v[210:213], v[40:43]
	v_mfma_f32_16x16x32_bf16 v[28:31], v[132:135], v[218:221], v[28:31]
	v_mfma_f32_16x16x32_bf16 v[24:27], v[160:163], v[218:221], v[24:27]
	v_mfma_f32_16x16x32_bf16 v[12:15], v[132:135], v[226:229], v[12:15]
	v_mfma_f32_16x16x32_bf16 v[8:11], v[160:163], v[226:229], v[8:11]
	s_setprio 0
	s_setprio 1
	v_mfma_f32_16x16x32_bf16 v[52:55], v[164:167], v[180:183], 0
	v_mfma_f32_16x16x32_bf16 v[48:51], v[172:175], v[180:183], 0
	v_mfma_f32_16x16x32_bf16 v[36:39], v[164:167], v[188:191], 0
	v_mfma_f32_16x16x32_bf16 v[32:35], v[172:175], v[188:191], 0
	v_mfma_f32_16x16x32_bf16 v[20:23], v[164:167], v[214:217], 0
	v_mfma_f32_16x16x32_bf16 v[16:19], v[172:175], v[214:217], 0
	v_mfma_f32_16x16x32_bf16 v[4:7], v[164:167], v[222:225], 0
	v_mfma_f32_16x16x32_bf16 v[0:3], v[172:175], v[222:225], 0
	v_mfma_f32_16x16x32_bf16 v[52:55], v[168:171], v[184:187], v[52:55]
	v_mfma_f32_16x16x32_bf16 v[48:51], v[176:179], v[184:187], v[48:51]
	v_mfma_f32_16x16x32_bf16 v[36:39], v[168:171], v[210:213], v[36:39]
	v_mfma_f32_16x16x32_bf16 v[32:35], v[176:179], v[210:213], v[32:35]
	v_mfma_f32_16x16x32_bf16 v[20:23], v[168:171], v[218:221], v[20:23]
	v_mfma_f32_16x16x32_bf16 v[16:19], v[176:179], v[218:221], v[16:19]
	v_mfma_f32_16x16x32_bf16 v[4:7], v[168:171], v[226:229], v[4:7]
	v_mfma_f32_16x16x32_bf16 v[0:3], v[176:179], v[226:229], v[0:3]
	s_setprio 0
	s_barrier
	s_add_i32 s74, 0, 0x18000
	v_add_u32_e32 v140, s74, v195
	s_add_i32 s75, 0, 0x1c000
	ds_read_b128 v[128:131], v140
	ds_read_b128 v[132:135], v140 offset:1024
	ds_read_b128 v[156:159], v140 offset:2048
	ds_read_b128 v[160:163], v140 offset:3072
	v_add_u32_e32 v140, s75, v195
	ds_read_b128 v[164:167], v140
	ds_read_b128 v[168:171], v140 offset:1024
	ds_read_b128 v[172:175], v140 offset:2048
	ds_read_b128 v[176:179], v140 offset:3072
	s_add_u32 s12, s12, 0x40000
	s_addc_u32 s13, s13, 0
	s_mov_b32 m0, s35
	v_lshl_add_u64 v[236:237], s[12:13], 0, v[136:137]
	ds_read_b128 v[180:183], v206 offset:32768
	ds_read_b128 v[184:187], v206 offset:33792
	ds_read_b128 v[188:191], v206 offset:34816
	ds_read_b128 v[210:213], v206 offset:35840
	ds_read_b128 v[214:217], v206 offset:36864
	ds_read_b128 v[218:221], v206 offset:37888
	ds_read_b128 v[222:225], v206 offset:38912
	ds_read_b128 v[226:229], v206 offset:39936
	global_load_lds_dwordx4 v[236:237], off
	v_lshl_add_u64 v[236:237], s[12:13], 0, v[138:139]
	s_mov_b32 m0, s36
	s_nop 0
	global_load_lds_dwordx4 v[236:237], off
	s_waitcnt vmcnt(8)
	s_waitcnt lgkmcnt(0)
	s_barrier
	s_setprio 1
	s_waitcnt lgkmcnt(0)
	v_mfma_f32_16x16x32_bf16 v[124:127], v[128:131], v[180:183], v[124:127]
	v_mfma_f32_16x16x32_bf16 v[120:123], v[156:159], v[180:183], v[120:123]
	v_mfma_f32_16x16x32_bf16 v[108:111], v[128:131], v[188:191], v[108:111]
	v_mfma_f32_16x16x32_bf16 v[104:107], v[156:159], v[188:191], v[104:107]
	v_mfma_f32_16x16x32_bf16 v[92:95], v[128:131], v[214:217], v[92:95]
	v_mfma_f32_16x16x32_bf16 v[88:91], v[156:159], v[214:217], v[88:91]
	v_mfma_f32_16x16x32_bf16 v[76:79], v[128:131], v[222:225], v[76:79]
	v_mfma_f32_16x16x32_bf16 v[72:75], v[156:159], v[222:225], v[72:75]
	v_mfma_f32_16x16x32_bf16 v[124:127], v[132:135], v[184:187], v[124:127]
	v_mfma_f32_16x16x32_bf16 v[120:123], v[160:163], v[184:187], v[120:123]
	v_mfma_f32_16x16x32_bf16 v[108:111], v[132:135], v[210:213], v[108:111]
	v_mfma_f32_16x16x32_bf16 v[104:107], v[160:163], v[210:213], v[104:107]
	v_mfma_f32_16x16x32_bf16 v[92:95], v[132:135], v[218:221], v[92:95]
	v_mfma_f32_16x16x32_bf16 v[88:91], v[160:163], v[218:221], v[88:91]
	v_mfma_f32_16x16x32_bf16 v[76:79], v[132:135], v[226:229], v[76:79]
	v_mfma_f32_16x16x32_bf16 v[72:75], v[160:163], v[226:229], v[72:75]
	s_setprio 0
	s_setprio 1
	v_mfma_f32_16x16x32_bf16 v[116:119], v[164:167], v[180:183], v[116:119]
	v_mfma_f32_16x16x32_bf16 v[112:115], v[172:175], v[180:183], v[112:115]
	v_mfma_f32_16x16x32_bf16 v[100:103], v[164:167], v[188:191], v[100:103]
	v_mfma_f32_16x16x32_bf16 v[96:99], v[172:175], v[188:191], v[96:99]
	v_mfma_f32_16x16x32_bf16 v[84:87], v[164:167], v[214:217], v[84:87]
	v_mfma_f32_16x16x32_bf16 v[80:83], v[172:175], v[214:217], v[80:83]
	v_mfma_f32_16x16x32_bf16 v[68:71], v[164:167], v[222:225], v[68:71]
	v_mfma_f32_16x16x32_bf16 v[64:67], v[172:175], v[222:225], v[64:67]
	v_mfma_f32_16x16x32_bf16 v[116:119], v[168:171], v[184:187], v[116:119]
	v_mfma_f32_16x16x32_bf16 v[112:115], v[176:179], v[184:187], v[112:115]
	v_mfma_f32_16x16x32_bf16 v[100:103], v[168:171], v[210:213], v[100:103]
	v_mfma_f32_16x16x32_bf16 v[96:99], v[176:179], v[210:213], v[96:99]
	v_mfma_f32_16x16x32_bf16 v[84:87], v[168:171], v[218:221], v[84:87]
	v_mfma_f32_16x16x32_bf16 v[80:83], v[176:179], v[218:221], v[80:83]
	v_mfma_f32_16x16x32_bf16 v[68:71], v[168:171], v[226:229], v[68:71]
	v_mfma_f32_16x16x32_bf16 v[64:67], v[176:179], v[226:229], v[64:67]
	s_setprio 0
	s_barrier
; #define PG8_STAGE(bufoff, gbase, voff) do { _Pragma("unroll") for (int _i = 0; _i < 2; ++_i) \
;         __builtin_amdgcn_global_load_lds((const unsigned*)((const char*)(gbase) + (voff)[_i]), (PG8_LAS unsigned*)(lds + (bufoff) + ldsw + _i * 8192), 16, 0, 0); } while (0)
; #define PG8_LDA(dst, b, h) do { _Pragma("unroll") for (int m = 0; m < 4; ++m) _Pragma("unroll") for (int k = 0; k < 2; ++k) dst[m][k] = *(const PG8_LAS bf16x8*)(lds + PG8_SA(b, h) + aoff + m * 2048 + k * 1024); } while (0)
; #define PG8_MMA(ai, bj, At, Bt) do { __builtin_amdgcn_s_setprio(1); _Pragma("unroll") for (int m = 0; m < 4; ++m) _Pragma("unroll") for (int n = 0; n < 2; ++n) _Pragma("unroll") for (int k = 0; k < 2; ++k) \
;         acc[ai][bj][m][n] = __builtin_amdgcn_mfma_f32_16x16x32_bf16(Bt[n][k], At[m][k], acc[ai][bj][m][n], 0, 0, 0); __builtin_amdgcn_s_setprio(0); } while (0)
; #define PG8_WAIT_V(n) asm volatile("s_waitcnt vmcnt(" #n ")" ::: "memory")
; #define PG8_WAIT_L(n) asm volatile("s_waitcnt lgkmcnt(" #n ")" ::: "memory")
; #define PG8_BAR __builtin_amdgcn_s_barrier()
; #define PG8_SCHED __builtin_amdgcn_sched_barrier(0)
; template <class Epi, class Sched, bool ALIGN_EPI = false, bool SP2 = false>
; __device__ __forceinline__ void gemm_phase(PG8_LAS unsigned char* lds, const Gemm g, const Sched& S, const Epi& E, const int tid_in) {
;     ...
;             PG8_LDA(At, 1, 1); PG8_STAGE(PG8_SB(1, 0), b3, voffB); PG8_STAGE(PG8_SB(1, 1), b3 + hstep, voffB); PG8_STAGE(PG8_SA(1, 0), a3, voffA);
;             PG8_WAIT_V(8); PG8_WAIT_L(0); PG8_BAR; PG8_MMA(1, 0, At, B0); PG8_MMA(1, 1, At, B1); PG8_BAR; PG8_SCHED;
	s_add_i32 s12, s74, s2
	v_lshl_add_u64 v[192:193], v[192:193], 0, s[26:27]
	s_mov_b32 m0, s12
	ds_read_b128 v[180:183], v206 offset:49152
	ds_read_b128 v[184:187], v206 offset:50176
	ds_read_b128 v[188:191], v206 offset:51200
	ds_read_b128 v[210:213], v206 offset:52224
	ds_read_b128 v[214:217], v206 offset:53248
	ds_read_b128 v[218:221], v206 offset:54272
	ds_read_b128 v[222:225], v206 offset:55296
	ds_read_b128 v[226:229], v206 offset:56320
	global_load_lds_dwordx4 v[192:193], off
	s_add_i32 m0, s12, 0x2000
	s_add_u32 s0, s0, 0x40080
	v_lshl_add_u64 v[192:193], v[230:231], 0, s[26:27]
	s_addc_u32 s1, s1, 0
	s_add_i32 s12, s75, s2
	global_load_lds_dwordx4 v[192:193], off
	v_lshl_add_u64 v[192:193], s[0:1], 0, v[136:137]
	s_mov_b32 m0, s12
	s_nop 0
	global_load_lds_dwordx4 v[192:193], off
	v_lshl_add_u64 v[192:193], s[0:1], 0, v[138:139]
	s_add_i32 m0, s12, 0x2000
	s_nop 0
	global_load_lds_dwordx4 v[192:193], off
	v_lshl_add_u64 v[192:193], v[232:233], 0, s[26:27]
	s_mov_b32 m0, s96
	s_nop 0
	global_load_lds_dwordx4 v[192:193], off
	v_lshl_add_u64 v[192:193], v[234:235], 0, s[26:27]
	s_mov_b32 m0, s97
	s_nop 0
	global_load_lds_dwordx4 v[192:193], off
	s_waitcnt vmcnt(8)
	s_waitcnt lgkmcnt(0)
	s_barrier
	s_setprio 1
	s_waitcnt lgkmcnt(0)
	v_mfma_f32_16x16x32_bf16 v[60:63], v[128:131], v[180:183], v[60:63]
	v_mfma_f32_16x16x32_bf16 v[56:59], v[156:159], v[180:183], v[56:59]
	v_mfma_f32_16x16x32_bf16 v[44:47], v[128:131], v[188:191], v[44:47]
	v_mfma_f32_16x16x32_bf16 v[40:43], v[156:159], v[188:191], v[40:43]
	v_mfma_f32_16x16x32_bf16 v[28:31], v[128:131], v[214:217], v[28:31]
	v_mfma_f32_16x16x32_bf16 v[24:27], v[156:159], v[214:217], v[24:27]
	v_mfma_f32_16x16x32_bf16 v[12:15], v[128:131], v[222:225], v[12:15]
	v_mfma_f32_16x16x32_bf16 v[8:11], v[156:159], v[222:225], v[8:11]
	v_mfma_f32_16x16x32_bf16 v[60:63], v[132:135], v[184:187], v[60:63]
	v_mfma_f32_16x16x32_bf16 v[56:59], v[160:163], v[184:187], v[56:59]
	v_mfma_f32_16x16x32_bf16 v[44:47], v[132:135], v[210:213], v[44:47]
	v_mfma_f32_16x16x32_bf16 v[40:43], v[160:163], v[210:213], v[40:43]
	v_mfma_f32_16x16x32_bf16 v[28:31], v[132:135], v[218:221], v[28:31]
	v_mfma_f32_16x16x32_bf16 v[24:27], v[160:163], v[218:221], v[24:27]
	v_mfma_f32_16x16x32_bf16 v[12:15], v[132:135], v[226:229], v[12:15]
	v_mfma_f32_16x16x32_bf16 v[8:11], v[160:163], v[226:229], v[8:11]
	s_setprio 0
	s_setprio 1
	v_mfma_f32_16x16x32_bf16 v[52:55], v[164:167], v[180:183], v[52:55]
	v_mfma_f32_16x16x32_bf16 v[48:51], v[172:175], v[180:183], v[48:51]
	v_mfma_f32_16x16x32_bf16 v[36:39], v[164:167], v[188:191], v[36:39]
	v_mfma_f32_16x16x32_bf16 v[32:35], v[172:175], v[188:191], v[32:35]
	v_mfma_f32_16x16x32_bf16 v[20:23], v[164:167], v[214:217], v[20:23]
	v_mfma_f32_16x16x32_bf16 v[16:19], v[172:175], v[214:217], v[16:19]
	v_mfma_f32_16x16x32_bf16 v[4:7], v[164:167], v[222:225], v[4:7]
	v_mfma_f32_16x16x32_bf16 v[0:3], v[172:175], v[222:225], v[0:3]
	v_mfma_f32_16x16x32_bf16 v[52:55], v[168:171], v[184:187], v[52:55]
	v_mfma_f32_16x16x32_bf16 v[48:51], v[176:179], v[184:187], v[48:51]
	v_mfma_f32_16x16x32_bf16 v[36:39], v[168:171], v[210:213], v[36:39]
	v_mfma_f32_16x16x32_bf16 v[32:35], v[176:179], v[210:213], v[32:35]
	v_mfma_f32_16x16x32_bf16 v[20:23], v[168:171], v[218:221], v[20:23]
	v_mfma_f32_16x16x32_bf16 v[16:19], v[176:179], v[218:221], v[16:19]
	v_mfma_f32_16x16x32_bf16 v[4:7], v[168:171], v[226:229], v[4:7]
	v_mfma_f32_16x16x32_bf16 v[0:3], v[176:179], v[226:229], v[0:3]
	s_setprio 0
	s_barrier
	s_add_i32 s65, s65, 2
	s_add_u32 s10, s10, 0x100
	s_addc_u32 s11, s11, 0
	s_add_u32 s55, s55, 0x100
	s_addc_u32 s57, s57, 0
	s_cmp_gt_u32 s65, 13
	s_cbranch_scc0 .LBB0_1795
	s_branch .Lmy_kdone_5

; #define PG8_STAGE(bufoff, gbase, voff) do { _Pragma("unroll") for (int _i = 0; _i < 2; ++_i) \
;         __builtin_amdgcn_global_load_lds((const unsigned*)((const char*)(gbase) + (voff)[_i]), (PG8_LAS unsigned*)(lds + (bufoff) + ldsw + _i * 8192), 16, 0, 0); } while (0)
; #define PG8_LDA(dst, b, h) do { _Pragma("unroll") for (int m = 0; m < 4; ++m) _Pragma("unroll") for (int k = 0; k < 2; ++k) dst[m][k] = *(const PG8_LAS bf16x8*)(lds + PG8_SA(b, h) + aoff + m * 2048 + k * 1024); } while (0)
; #define PG8_LDB(dst, b, h) do { _Pragma("unroll") for (int n = 0; n < 2; ++n) _Pragma("unroll") for (int k = 0; k < 2; ++k) dst[n][k] = *(const PG8_LAS bf16x8*)(lds + PG8_SB(b, h) + boff + n * 2048 + k * 1024); } while (0)
; #define PG8_MMA(ai, bj, At, Bt) do { __builtin_amdgcn_s_setprio(1); _Pragma("unroll") for (int m = 0; m < 4; ++m) _Pragma("unroll") for (int n = 0; n < 2; ++n) _Pragma("unroll") for (int k = 0; k < 2; ++k) \
;         acc[ai][bj][m][n] = __builtin_amdgcn_mfma_f32_16x16x32_bf16(Bt[n][k], At[m][k], acc[ai][bj][m][n], 0, 0, 0); __builtin_amdgcn_s_setprio(0); } while (0)
; #define PG8_WAIT_V(n) asm volatile("s_waitcnt vmcnt(" #n ")" ::: "memory")
; template <class Epi, class Sched, bool ALIGN_EPI = false, bool SP2 = false>
; __device__ __forceinline__ void gemm_phase(PG8_LAS unsigned char* lds, const Gemm g, const Sched& S, const Epi& E, const int tid_in) {
;     ...
;         const char* nA = has_next ? (const char*)g.A + (size_t)nxt.pm * tstep : cA; const char* nB = has_next ? (const char*)g.Bt + (size_t)nxt.pn * tstep : cB;
;         for (int t = 0; t < nt; t += 2) {
;             const bool last = (t == nt - 2);
;             const char* a1 = cA + (size_t)(t + 1) * kstep;
;             const char* a2 = last ? nA : cA + (size_t)(t + 2) * kstep; const char* b2 = last ? nB : cB + (size_t)(t + 2) * kstep;
;             const char* a3 = a2 + kstep; const char* b3 = b2 + kstep;
;             if (last && has_next) S.a_ready(nxt);
;             if constexpr (SP2) {
;             PG8_LDB(B0, 0, 0); PG8_LDB(B1, 0, 1); PG8_SCHED; PG8_LDA(At, 0, 0); PG8_STAGE(PG8_SA(1, 1), a1 + hstep, voffA);
;             PG8_WAIT_V(8); PG8_WAIT_L(0); PG8_BAR; PG8_MMA(0, 0, At, B0); PG8_MMA(0, 1, At, B1); PG8_BAR; PG8_SCHED;
;             PG8_LDA(At, 0, 1); PG8_STAGE(PG8_SB(0, 0), b2, voffB); PG8_STAGE(PG8_SB(0, 1), b2 + hstep, voffB); PG8_STAGE(PG8_SA(0, 0), a2, voffA);
.LBB0_2953:
	s_ashr_i32 s55, s54, 31
	s_lshl_b64 s[56:57], s[54:55], 19
	s_add_u32 s56, s16, s56
	s_addc_u32 s57, s17, s57
	s_and_b64 s[58:59], s[8:9], exec
	s_cselect_b32 s55, s57, s63
	s_cselect_b32 s61, s56, s62
	s_ashr_i32 s53, s52, 31
	s_lshl_b64 s[58:59], s[52:53], 19
	s_add_u32 s58, s10, s58
	s_addc_u32 s59, s11, s59
	s_and_b64 s[64:65], s[8:9], exec
	s_cselect_b32 s53, s59, s1
	s_cselect_b32 s74, s58, s0
	s_add_u32 s62, s62, 0x40080
	s_addc_u32 s63, s63, 0
	s_add_u32 s75, s0, 0x100
	v_mov_b32_e32 v0, 0
	s_addc_u32 s76, s1, 0
	s_mov_b32 s77, -2
	ds_read_b128 v[92:95], v207
	ds_read_b128 v[100:103], v207 offset:1024
	ds_read_b128 v[112:115], v207 offset:2048
	ds_read_b128 v[124:127], v207 offset:3072
	ds_read_b128 v[136:139], v208
	ds_read_b128 v[148:151], v208 offset:1024
	ds_read_b128 v[152:155], v208 offset:2048
	ds_read_b128 v[156:159], v208 offset:3072
	s_add_u32 s0, s62, 0xfffc0080
	s_addc_u32 s1, s63, -1
	s_cmp_eq_u32 s77, 12
	s_cselect_b32 s65, s55, s1
	s_cselect_b32 s64, s61, s0
	s_cselect_b32 s1, s53, s76
	s_cselect_b32 s0, s74, s75
	v_lshl_add_u64 v[214:215], s[62:63], 0, v[192:193]
	s_add_i32 m0, s4, 0xc000
	ds_read_b128 v[160:163], v209
	ds_read_b128 v[164:167], v209 offset:1024
	ds_read_b128 v[168:171], v209 offset:2048
	ds_read_b128 v[172:175], v209 offset:3072
	ds_read_b128 v[176:179], v209 offset:4096
	ds_read_b128 v[180:183], v209 offset:5120
	ds_read_b128 v[200:203], v209 offset:6144
	ds_read_b128 v[210:213], v209 offset:7168
	global_load_lds_dwordx4 v[214:215], off
	v_lshl_add_u64 v[214:215], s[62:63], 0, v[194:195]
	s_add_i32 m0, s4, 0xe000
	s_nop 0
	global_load_lds_dwordx4 v[214:215], off
	s_waitcnt vmcnt(8)
	s_waitcnt lgkmcnt(0)
	s_barrier
	s_setprio 1
	s_waitcnt lgkmcnt(0)
	v_mfma_f32_16x16x32_bf16 v[144:147], v[92:95], v[160:163], 0
	v_mfma_f32_16x16x32_bf16 v[140:143], v[112:115], v[160:163], 0
	v_mfma_f32_16x16x32_bf16 v[120:123], v[92:95], v[168:171], 0
	v_mfma_f32_16x16x32_bf16 v[116:119], v[112:115], v[168:171], 0
	v_mfma_f32_16x16x32_bf16 v[96:99], v[92:95], v[176:179], 0
	v_mfma_f32_16x16x32_bf16 v[88:91], v[112:115], v[176:179], 0
	v_mfma_f32_16x16x32_bf16 v[76:79], v[92:95], v[200:203], 0
	v_mfma_f32_16x16x32_bf16 v[72:75], v[112:115], v[200:203], 0
	v_mfma_f32_16x16x32_bf16 v[144:147], v[100:103], v[164:167], v[144:147]
	v_mfma_f32_16x16x32_bf16 v[140:143], v[124:127], v[164:167], v[140:143]
	v_mfma_f32_16x16x32_bf16 v[120:123], v[100:103], v[172:175], v[120:123]
	v_mfma_f32_16x16x32_bf16 v[116:119], v[124:127], v[172:175], v[116:119]
	v_mfma_f32_16x16x32_bf16 v[96:99], v[100:103], v[180:183], v[96:99]
	v_mfma_f32_16x16x32_bf16 v[88:91], v[124:127], v[180:183], v[88:91]
	v_mfma_f32_16x16x32_bf16 v[76:79], v[100:103], v[210:213], v[76:79]
	v_mfma_f32_16x16x32_bf16 v[72:75], v[124:127], v[210:213], v[72:75]
	s_setprio 0
	s_setprio 1
	v_mfma_f32_16x16x32_bf16 v[132:135], v[136:139], v[160:163], 0
	v_mfma_f32_16x16x32_bf16 v[128:131], v[152:155], v[160:163], 0
	v_mfma_f32_16x16x32_bf16 v[108:111], v[136:139], v[168:171], 0
	v_mfma_f32_16x16x32_bf16 v[104:107], v[152:155], v[168:171], 0
	v_mfma_f32_16x16x32_bf16 v[84:87], v[136:139], v[176:179], 0
	v_mfma_f32_16x16x32_bf16 v[80:83], v[152:155], v[176:179], 0
	v_mfma_f32_16x16x32_bf16 v[68:71], v[136:139], v[200:203], 0
	v_mfma_f32_16x16x32_bf16 v[64:67], v[152:155], v[200:203], 0
	v_mfma_f32_16x16x32_bf16 v[132:135], v[148:151], v[164:167], v[132:135]
	v_mfma_f32_16x16x32_bf16 v[128:131], v[156:159], v[164:167], v[128:131]
	v_mfma_f32_16x16x32_bf16 v[108:111], v[148:151], v[172:175], v[108:111]
	v_mfma_f32_16x16x32_bf16 v[104:107], v[156:159], v[172:175], v[104:107]
	v_mfma_f32_16x16x32_bf16 v[84:87], v[148:151], v[180:183], v[84:87]
	v_mfma_f32_16x16x32_bf16 v[80:83], v[156:159], v[180:183], v[80:83]
	v_mfma_f32_16x16x32_bf16 v[68:71], v[148:151], v[210:213], v[68:71]
	v_mfma_f32_16x16x32_bf16 v[64:67], v[156:159], v[210:213], v[64:67]
	s_setprio 0
	s_barrier
	s_add_i32 s78, s3, s2
	v_lshl_add_u64 v[214:215], s[0:1], 0, v[186:187]
	s_mov_b32 m0, s78
	ds_read_b128 v[160:163], v209 offset:16384
	ds_read_b128 v[164:167], v209 offset:17408
	ds_read_b128 v[168:171], v209 offset:18432
	ds_read_b128 v[172:175], v209 offset:19456
	ds_read_b128 v[176:179], v209 offset:20480
	ds_read_b128 v[180:183], v209 offset:21504
	ds_read_b128 v[200:203], v209 offset:22528
	ds_read_b128 v[210:213], v209 offset:23552
	global_load_lds_dwordx4 v[214:215], off
	s_add_i32 m0, s78, 0x2000
	s_add_u32 s78, s0, 0x40000
	v_lshl_add_u64 v[216:217], s[0:1], 0, v[190:191]
	s_addc_u32 s79, s1, 0
	s_add_i32 s80, s41, s2
	global_load_lds_dwordx4 v[216:217], off
	v_lshl_add_u64 v[218:219], s[78:79], 0, v[186:187]
	s_mov_b32 m0, s80
	v_lshl_add_u64 v[220:221], s[64:65], 0, v[188:189]
	global_load_lds_dwordx4 v[218:219], off
	v_lshl_add_u64 v[218:219], s[78:79], 0, v[190:191]
	s_add_i32 m0, s80, 0x2000
	s_nop 0
	global_load_lds_dwordx4 v[218:219], off
	v_lshl_add_u64 v[218:219], s[64:65], 0, v[184:185]
	s_mov_b32 m0, s4
	s_nop 0
	global_load_lds_dwordx4 v[218:219], off
	s_mov_b32 m0, s5
	s_nop 0
	global_load_lds_dwordx4 v[220:221], off
	s_waitcnt vmcnt(8)
	s_waitcnt lgkmcnt(0)
	s_barrier
; #define PG8_STAGE(bufoff, gbase, voff) do { _Pragma("unroll") for (int _i = 0; _i < 2; ++_i) \
;         __builtin_amdgcn_global_load_lds((const unsigned*)((const char*)(gbase) + (voff)[_i]), (PG8_LAS unsigned*)(lds + (bufoff) + ldsw + _i * 8192), 16, 0, 0); } while (0)
; #define PG8_LDA(dst, b, h) do { _Pragma("unroll") for (int m = 0; m < 4; ++m) _Pragma("unroll") for (int k = 0; k < 2; ++k) dst[m][k] = *(const PG8_LAS bf16x8*)(lds + PG8_SA(b, h) + aoff + m * 2048 + k * 1024); } while (0)
; #define PG8_LDB(dst, b, h) do { _Pragma("unroll") for (int n = 0; n < 2; ++n) _Pragma("unroll") for (int k = 0; k < 2; ++k) dst[n][k] = *(const PG8_LAS bf16x8*)(lds + PG8_SB(b, h) + boff + n * 2048 + k * 1024); } while (0)
; #define PG8_MMA(ai, bj, At, Bt) do { __builtin_amdgcn_s_setprio(1); _Pragma("unroll") for (int m = 0; m < 4; ++m) _Pragma("unroll") for (int n = 0; n < 2; ++n) _Pragma("unroll") for (int k = 0; k < 2; ++k) \
;         acc[ai][bj][m][n] = __builtin_amdgcn_mfma_f32_16x16x32_bf16(Bt[n][k], At[m][k], acc[ai][bj][m][n], 0, 0, 0); __builtin_amdgcn_s_setprio(0); } while (0)
; #define PG8_WAIT_V(n) asm volatile("s_waitcnt vmcnt(" #n ")" ::: "memory")
; #define PG8_WAIT_L(n) asm volatile("s_waitcnt lgkmcnt(" #n ")" ::: "memory")
; #define PG8_BAR __builtin_amdgcn_s_barrier()
; #define PG8_SCHED __builtin_amdgcn_sched_barrier(0)
; template <class Epi, class Sched, bool ALIGN_EPI = false, bool SP2 = false>
; __device__ __forceinline__ void gemm_phase(PG8_LAS unsigned char* lds, const Gemm g, const Sched& S, const Epi& E, const int tid_in) {
;     ...
;             PG8_WAIT_V(8); PG8_WAIT_L(0); PG8_BAR; PG8_MMA(1, 0, At, B0); PG8_MMA(1, 1, At, B1); PG8_BAR; PG8_SCHED;
;             PG8_LDB(B0, 1, 0); PG8_LDB(B1, 1, 1); PG8_SCHED; PG8_LDA(At, 1, 0); PG8_STAGE(PG8_SA(0, 1), a2 + hstep, voffA);
;             PG8_WAIT_V(8); PG8_WAIT_L(0); PG8_BAR; PG8_MMA(0, 0, At, B0); PG8_MMA(0, 1, At, B1); PG8_BAR; PG8_SCHED;
	s_setprio 1
	s_waitcnt lgkmcnt(0)
	v_mfma_f32_16x16x32_bf16 v[60:63], v[92:95], v[160:163], 0
	v_mfma_f32_16x16x32_bf16 v[56:59], v[112:115], v[160:163], 0
	v_mfma_f32_16x16x32_bf16 v[44:47], v[92:95], v[168:171], 0
	v_mfma_f32_16x16x32_bf16 v[40:43], v[112:115], v[168:171], 0
	v_mfma_f32_16x16x32_bf16 v[28:31], v[92:95], v[176:179], 0
	v_mfma_f32_16x16x32_bf16 v[24:27], v[112:115], v[176:179], 0
	v_mfma_f32_16x16x32_bf16 v[12:15], v[92:95], v[200:203], 0
	v_mfma_f32_16x16x32_bf16 v[8:11], v[112:115], v[200:203], 0
	v_mfma_f32_16x16x32_bf16 v[60:63], v[100:103], v[164:167], v[60:63]
	v_mfma_f32_16x16x32_bf16 v[56:59], v[124:127], v[164:167], v[56:59]
	v_mfma_f32_16x16x32_bf16 v[44:47], v[100:103], v[172:175], v[44:47]
	v_mfma_f32_16x16x32_bf16 v[40:43], v[124:127], v[172:175], v[40:43]
	v_mfma_f32_16x16x32_bf16 v[28:31], v[100:103], v[180:183], v[28:31]
	v_mfma_f32_16x16x32_bf16 v[24:27], v[124:127], v[180:183], v[24:27]
	v_mfma_f32_16x16x32_bf16 v[12:15], v[100:103], v[210:213], v[12:15]
	v_mfma_f32_16x16x32_bf16 v[8:11], v[124:127], v[210:213], v[8:11]
	s_setprio 0
	s_setprio 1
	v_mfma_f32_16x16x32_bf16 v[52:55], v[136:139], v[160:163], 0
	v_mfma_f32_16x16x32_bf16 v[48:51], v[152:155], v[160:163], 0
	v_mfma_f32_16x16x32_bf16 v[36:39], v[136:139], v[168:171], 0
	v_mfma_f32_16x16x32_bf16 v[32:35], v[152:155], v[168:171], 0
	v_mfma_f32_16x16x32_bf16 v[20:23], v[136:139], v[176:179], 0
	v_mfma_f32_16x16x32_bf16 v[16:19], v[152:155], v[176:179], 0
	v_mfma_f32_16x16x32_bf16 v[4:7], v[136:139], v[200:203], 0
	v_mfma_f32_16x16x32_bf16 v[0:3], v[152:155], v[200:203], 0
	v_mfma_f32_16x16x32_bf16 v[52:55], v[148:151], v[164:167], v[52:55]
	v_mfma_f32_16x16x32_bf16 v[48:51], v[156:159], v[164:167], v[48:51]
	v_mfma_f32_16x16x32_bf16 v[36:39], v[148:151], v[172:175], v[36:39]
	v_mfma_f32_16x16x32_bf16 v[32:35], v[156:159], v[172:175], v[32:35]
	v_mfma_f32_16x16x32_bf16 v[20:23], v[148:151], v[180:183], v[20:23]
	v_mfma_f32_16x16x32_bf16 v[16:19], v[156:159], v[180:183], v[16:19]
	v_mfma_f32_16x16x32_bf16 v[4:7], v[148:151], v[210:213], v[4:7]
	v_mfma_f32_16x16x32_bf16 v[0:3], v[156:159], v[210:213], v[0:3]
	s_setprio 0
	s_barrier
	s_add_i32 s78, 0, 0x18000
	s_add_i32 s79, 0, 0x1c000
	v_add_u32_e32 v124, s78, v205
	v_add_u32_e32 v156, s79, v205
	ds_read_b128 v[92:95], v124
	ds_read_b128 v[100:103], v124 offset:1024
	ds_read_b128 v[112:115], v124 offset:2048
	ds_read_b128 v[124:127], v124 offset:3072
	ds_read_b128 v[136:139], v156
	ds_read_b128 v[148:151], v156 offset:1024
	ds_read_b128 v[152:155], v156 offset:2048
	ds_read_b128 v[156:159], v156 offset:3072
	s_add_u32 s64, s64, 0x40000
	s_addc_u32 s65, s65, 0
	s_mov_b32 m0, s30
	v_lshl_add_u64 v[222:223], s[64:65], 0, v[184:185]
	ds_read_b128 v[160:163], v209 offset:32768
	ds_read_b128 v[164:167], v209 offset:33792
	ds_read_b128 v[168:171], v209 offset:34816
	ds_read_b128 v[172:175], v209 offset:35840
	ds_read_b128 v[176:179], v209 offset:36864
	ds_read_b128 v[180:183], v209 offset:37888
	ds_read_b128 v[200:203], v209 offset:38912
	ds_read_b128 v[210:213], v209 offset:39936
	global_load_lds_dwordx4 v[222:223], off
	v_lshl_add_u64 v[222:223], s[64:65], 0, v[188:189]
	s_mov_b32 m0, s31
	s_nop 0
	global_load_lds_dwordx4 v[222:223], off
	s_waitcnt vmcnt(8)
	s_waitcnt lgkmcnt(0)
	s_barrier
	s_setprio 1
	s_waitcnt lgkmcnt(0)
	v_mfma_f32_16x16x32_bf16 v[144:147], v[92:95], v[160:163], v[144:147]
	v_mfma_f32_16x16x32_bf16 v[140:143], v[112:115], v[160:163], v[140:143]
	v_mfma_f32_16x16x32_bf16 v[120:123], v[92:95], v[168:171], v[120:123]
	v_mfma_f32_16x16x32_bf16 v[116:119], v[112:115], v[168:171], v[116:119]
	v_mfma_f32_16x16x32_bf16 v[96:99], v[92:95], v[176:179], v[96:99]
	v_mfma_f32_16x16x32_bf16 v[88:91], v[112:115], v[176:179], v[88:91]
	v_mfma_f32_16x16x32_bf16 v[76:79], v[92:95], v[200:203], v[76:79]
	v_mfma_f32_16x16x32_bf16 v[72:75], v[112:115], v[200:203], v[72:75]
	v_mfma_f32_16x16x32_bf16 v[144:147], v[100:103], v[164:167], v[144:147]
	v_mfma_f32_16x16x32_bf16 v[140:143], v[124:127], v[164:167], v[140:143]
	v_mfma_f32_16x16x32_bf16 v[120:123], v[100:103], v[172:175], v[120:123]
	v_mfma_f32_16x16x32_bf16 v[116:119], v[124:127], v[172:175], v[116:119]
	v_mfma_f32_16x16x32_bf16 v[96:99], v[100:103], v[180:183], v[96:99]
	v_mfma_f32_16x16x32_bf16 v[88:91], v[124:127], v[180:183], v[88:91]
	v_mfma_f32_16x16x32_bf16 v[76:79], v[100:103], v[210:213], v[76:79]
	v_mfma_f32_16x16x32_bf16 v[72:75], v[124:127], v[210:213], v[72:75]
	s_setprio 0
	s_setprio 1
	v_mfma_f32_16x16x32_bf16 v[132:135], v[136:139], v[160:163], v[132:135]
	v_mfma_f32_16x16x32_bf16 v[128:131], v[152:155], v[160:163], v[128:131]
	v_mfma_f32_16x16x32_bf16 v[108:111], v[136:139], v[168:171], v[108:111]
	v_mfma_f32_16x16x32_bf16 v[104:107], v[152:155], v[168:171], v[104:107]
	v_mfma_f32_16x16x32_bf16 v[84:87], v[136:139], v[176:179], v[84:87]
	v_mfma_f32_16x16x32_bf16 v[80:83], v[152:155], v[176:179], v[80:83]
	v_mfma_f32_16x16x32_bf16 v[68:71], v[136:139], v[200:203], v[68:71]
	v_mfma_f32_16x16x32_bf16 v[64:67], v[152:155], v[200:203], v[64:67]
	v_mfma_f32_16x16x32_bf16 v[132:135], v[148:151], v[164:167], v[132:135]
	v_mfma_f32_16x16x32_bf16 v[128:131], v[156:159], v[164:167], v[128:131]
	v_mfma_f32_16x16x32_bf16 v[108:111], v[148:151], v[172:175], v[108:111]
	v_mfma_f32_16x16x32_bf16 v[104:107], v[156:159], v[172:175], v[104:107]
	v_mfma_f32_16x16x32_bf16 v[84:87], v[148:151], v[180:183], v[84:87]
	v_mfma_f32_16x16x32_bf16 v[80:83], v[156:159], v[180:183], v[80:83]
	v_mfma_f32_16x16x32_bf16 v[68:71], v[148:151], v[210:213], v[68:71]
	v_mfma_f32_16x16x32_bf16 v[64:67], v[156:159], v[210:213], v[64:67]
	s_setprio 0
	s_barrier
; #define PG8_STAGE(bufoff, gbase, voff) do { _Pragma("unroll") for (int _i = 0; _i < 2; ++_i) \
;         __builtin_amdgcn_global_load_lds((const unsigned*)((const char*)(gbase) + (voff)[_i]), (PG8_LAS unsigned*)(lds + (bufoff) + ldsw + _i * 8192), 16, 0, 0); } while (0)
; #define PG8_LDA(dst, b, h) do { _Pragma("unroll") for (int m = 0; m < 4; ++m) _Pragma("unroll") for (int k = 0; k < 2; ++k) dst[m][k] = *(const PG8_LAS bf16x8*)(lds + PG8_SA(b, h) + aoff + m * 2048 + k * 1024); } while (0)
; #define PG8_MMA(ai, bj, At, Bt) do { __builtin_amdgcn_s_setprio(1); _Pragma("unroll") for (int m = 0; m < 4; ++m) _Pragma("unroll") for (int n = 0; n < 2; ++n) _Pragma("unroll") for (int k = 0; k < 2; ++k) \
;         acc[ai][bj][m][n] = __builtin_amdgcn_mfma_f32_16x16x32_bf16(Bt[n][k], At[m][k], acc[ai][bj][m][n], 0, 0, 0); __builtin_amdgcn_s_setprio(0); } while (0)
; #define PG8_WAIT_V(n) asm volatile("s_waitcnt vmcnt(" #n ")" ::: "memory")
; #define PG8_WAIT_L(n) asm volatile("s_waitcnt lgkmcnt(" #n ")" ::: "memory")
; #define PG8_BAR __builtin_amdgcn_s_barrier()
; #define PG8_SCHED __builtin_amdgcn_sched_barrier(0)
; template <class Epi, class Sched, bool ALIGN_EPI = false, bool SP2 = false>
; __device__ __forceinline__ void gemm_phase(PG8_LAS unsigned char* lds, const Gemm g, const Sched& S, const Epi& E, const int tid_in) {
;     ...
;             PG8_LDA(At, 1, 1); PG8_STAGE(PG8_SB(1, 0), b3, voffB); PG8_STAGE(PG8_SB(1, 1), b3 + hstep, voffB); PG8_STAGE(PG8_SA(1, 0), a3, voffA);
;             PG8_WAIT_V(8); PG8_WAIT_L(0); PG8_BAR; PG8_MMA(1, 0, At, B0); PG8_MMA(1, 1, At, B1); PG8_BAR; PG8_SCHED;
	s_add_i32 s64, s78, s2
	v_lshl_add_u64 v[214:215], v[214:215], 0, s[22:23]
	s_mov_b32 m0, s64
	ds_read_b128 v[160:163], v209 offset:49152
	ds_read_b128 v[164:167], v209 offset:50176
	ds_read_b128 v[168:171], v209 offset:51200
	ds_read_b128 v[172:175], v209 offset:52224
	ds_read_b128 v[176:179], v209 offset:53248
	ds_read_b128 v[180:183], v209 offset:54272
	ds_read_b128 v[200:203], v209 offset:55296
	ds_read_b128 v[210:213], v209 offset:56320
	global_load_lds_dwordx4 v[214:215], off
	s_add_i32 m0, s64, 0x2000
	s_add_u32 s0, s0, 0x40080
	v_lshl_add_u64 v[214:215], v[216:217], 0, s[22:23]
	s_addc_u32 s1, s1, 0
	s_add_i32 s64, s79, s2
	global_load_lds_dwordx4 v[214:215], off
	v_lshl_add_u64 v[214:215], s[0:1], 0, v[186:187]
	s_mov_b32 m0, s64
	s_nop 0
	global_load_lds_dwordx4 v[214:215], off
	v_lshl_add_u64 v[214:215], s[0:1], 0, v[190:191]
	s_add_i32 m0, s64, 0x2000
	s_nop 0
	global_load_lds_dwordx4 v[214:215], off
	v_lshl_add_u64 v[214:215], v[218:219], 0, s[22:23]
	s_mov_b32 m0, s35
	s_nop 0
	global_load_lds_dwordx4 v[214:215], off
	v_lshl_add_u64 v[214:215], v[220:221], 0, s[22:23]
	s_mov_b32 m0, s36
	s_nop 0
	global_load_lds_dwordx4 v[214:215], off
	s_waitcnt vmcnt(8)
	s_waitcnt lgkmcnt(0)
	s_barrier
	s_setprio 1
	s_waitcnt lgkmcnt(0)
	v_mfma_f32_16x16x32_bf16 v[60:63], v[92:95], v[160:163], v[60:63]
	v_mfma_f32_16x16x32_bf16 v[56:59], v[112:115], v[160:163], v[56:59]
	v_mfma_f32_16x16x32_bf16 v[44:47], v[92:95], v[168:171], v[44:47]
	v_mfma_f32_16x16x32_bf16 v[40:43], v[112:115], v[168:171], v[40:43]
	v_mfma_f32_16x16x32_bf16 v[28:31], v[92:95], v[176:179], v[28:31]
	v_mfma_f32_16x16x32_bf16 v[24:27], v[112:115], v[176:179], v[24:27]
	v_mfma_f32_16x16x32_bf16 v[12:15], v[92:95], v[200:203], v[12:15]
	v_mfma_f32_16x16x32_bf16 v[8:11], v[112:115], v[200:203], v[8:11]
	v_mfma_f32_16x16x32_bf16 v[60:63], v[100:103], v[164:167], v[60:63]
	v_mfma_f32_16x16x32_bf16 v[56:59], v[124:127], v[164:167], v[56:59]
	v_mfma_f32_16x16x32_bf16 v[44:47], v[100:103], v[172:175], v[44:47]
	v_mfma_f32_16x16x32_bf16 v[40:43], v[124:127], v[172:175], v[40:43]
	v_mfma_f32_16x16x32_bf16 v[28:31], v[100:103], v[180:183], v[28:31]
	v_mfma_f32_16x16x32_bf16 v[24:27], v[124:127], v[180:183], v[24:27]
	v_mfma_f32_16x16x32_bf16 v[12:15], v[100:103], v[210:213], v[12:15]
	v_mfma_f32_16x16x32_bf16 v[8:11], v[124:127], v[210:213], v[8:11]
	s_setprio 0
	s_setprio 1
	v_mfma_f32_16x16x32_bf16 v[52:55], v[136:139], v[160:163], v[52:55]
	v_mfma_f32_16x16x32_bf16 v[48:51], v[152:155], v[160:163], v[48:51]
	v_mfma_f32_16x16x32_bf16 v[36:39], v[136:139], v[168:171], v[36:39]
	v_mfma_f32_16x16x32_bf16 v[32:35], v[152:155], v[168:171], v[32:35]
	v_mfma_f32_16x16x32_bf16 v[20:23], v[136:139], v[176:179], v[20:23]
	v_mfma_f32_16x16x32_bf16 v[16:19], v[152:155], v[176:179], v[16:19]
	v_mfma_f32_16x16x32_bf16 v[4:7], v[136:139], v[200:203], v[4:7]
	v_mfma_f32_16x16x32_bf16 v[0:3], v[152:155], v[200:203], v[0:3]
	v_mfma_f32_16x16x32_bf16 v[52:55], v[148:151], v[164:167], v[52:55]
	v_mfma_f32_16x16x32_bf16 v[48:51], v[156:159], v[164:167], v[48:51]
	v_mfma_f32_16x16x32_bf16 v[36:39], v[148:151], v[172:175], v[36:39]
	v_mfma_f32_16x16x32_bf16 v[32:35], v[156:159], v[172:175], v[32:35]
	v_mfma_f32_16x16x32_bf16 v[20:23], v[148:151], v[180:183], v[20:23]
	v_mfma_f32_16x16x32_bf16 v[16:19], v[156:159], v[180:183], v[16:19]
	v_mfma_f32_16x16x32_bf16 v[4:7], v[148:151], v[210:213], v[4:7]
	v_mfma_f32_16x16x32_bf16 v[0:3], v[156:159], v[210:213], v[0:3]
	s_setprio 0
	s_barrier
	s_add_i32 s77, s77, 2
	s_add_u32 s62, s62, 0x100
	s_addc_u32 s63, s63, 0
	s_add_u32 s75, s75, 0x100
	s_addc_u32 s76, s76, 0
	s_cmp_gt_u32 s77, 13
	s_cbranch_scc0 .LBB0_2954
	s_branch .Lmy_kdone_6

; #define PG8_BAR __builtin_amdgcn_s_barrier()
; template <class Epi, class Sched, bool ALIGN_EPI = false, bool SP2 = false>
; __device__ __forceinline__ void gemm_phase(PG8_LAS unsigned char* lds, const Gemm g, const Sched& S, const Epi& E, const int tid_in) {
;     ...
;         if constexpr (ALIGN_EPI) { if (wr == 0) PG8_BAR; }
.Lmy_kdone_6:
	s_and_b64 vcc, exec, s[24:25]
	s_cbranch_vccz .LBB0_2957
	s_barrier

; #define PG8_STAGE(bufoff, gbase, voff) do { _Pragma("unroll") for (int _i = 0; _i < 2; ++_i) \
;         __builtin_amdgcn_global_load_lds((const unsigned*)((const char*)(gbase) + (voff)[_i]), (PG8_LAS unsigned*)(lds + (bufoff) + ldsw + _i * 8192), 16, 0, 0); } while (0)
; #define PG8_LDA(dst, b, h) do { _Pragma("unroll") for (int m = 0; m < 4; ++m) _Pragma("unroll") for (int k = 0; k < 2; ++k) dst[m][k] = *(const PG8_LAS bf16x8*)(lds + PG8_SA(b, h) + aoff + m * 2048 + k * 1024); } while (0)
; #define PG8_LDB(dst, b, h) do { _Pragma("unroll") for (int n = 0; n < 2; ++n) _Pragma("unroll") for (int k = 0; k < 2; ++k) dst[n][k] = *(const PG8_LAS bf16x8*)(lds + PG8_SB(b, h) + boff + n * 2048 + k * 1024); } while (0)
; #define PG8_MMA(ai, bj, At, Bt) do { __builtin_amdgcn_s_setprio(1); _Pragma("unroll") for (int m = 0; m < 4; ++m) _Pragma("unroll") for (int n = 0; n < 2; ++n) _Pragma("unroll") for (int k = 0; k < 2; ++k) \
;         acc[ai][bj][m][n] = __builtin_amdgcn_mfma_f32_16x16x32_bf16(Bt[n][k], At[m][k], acc[ai][bj][m][n], 0, 0, 0); __builtin_amdgcn_s_setprio(0); } while (0)
; #define PG8_WAIT_V(n) asm volatile("s_waitcnt vmcnt(" #n ")" ::: "memory")
; template <class Epi, class Sched, bool ALIGN_EPI = false, bool SP2 = false>
; __device__ __forceinline__ void gemm_phase(PG8_LAS unsigned char* lds, const Gemm g, const Sched& S, const Epi& E, const int tid_in) {
;     ...
;         const char* nA = has_next ? (const char*)g.A + (size_t)nxt.pm * tstep : cA; const char* nB = has_next ? (const char*)g.Bt + (size_t)nxt.pn * tstep : cB;
;         for (int t = 0; t < nt; t += 2) {
;             const bool last = (t == nt - 2);
;             const char* a1 = cA + (size_t)(t + 1) * kstep;
;             const char* a2 = last ? nA : cA + (size_t)(t + 2) * kstep; const char* b2 = last ? nB : cB + (size_t)(t + 2) * kstep;
;             const char* a3 = a2 + kstep; const char* b3 = b2 + kstep;
;             if (last && has_next) S.a_ready(nxt);
;             if constexpr (SP2) {
;             PG8_LDB(B0, 0, 0); PG8_LDB(B1, 0, 1); PG8_SCHED; PG8_LDA(At, 0, 0); PG8_STAGE(PG8_SA(1, 1), a1 + hstep, voffA);
;             PG8_WAIT_V(8); PG8_WAIT_L(0); PG8_BAR; PG8_MMA(0, 0, At, B0); PG8_MMA(0, 1, At, B1); PG8_BAR; PG8_SCHED;
;             PG8_LDA(At, 0, 1); PG8_STAGE(PG8_SB(0, 0), b2, voffB); PG8_STAGE(PG8_SB(0, 1), b2 + hstep, voffB); PG8_STAGE(PG8_SA(0, 0), a2, voffA);
.LBB0_3052:
	s_ashr_i32 s25, s24, 31
	s_lshl_b64 s[26:27], s[24:25], 19
	s_add_u32 s26, s30, s26
	s_addc_u32 s27, s31, s27
	s_and_b64 s[28:29], s[6:7], exec
	s_cselect_b32 s25, s27, s11
	s_cselect_b32 s49, s26, s10
	s_ashr_i32 s23, s22, 31
	s_lshl_b64 s[28:29], s[22:23], 19
	s_add_u32 s28, s4, s28
	s_addc_u32 s29, s5, s29
	s_and_b64 s[38:39], s[6:7], exec
	s_cselect_b32 s23, s29, s1
	s_cselect_b32 s50, s28, s0
	s_add_u32 s10, s10, 0x40080
	s_addc_u32 s11, s11, 0
	s_add_u32 s51, s0, 0x100
	v_mov_b32_e32 v0, 0
	s_addc_u32 s52, s1, 0
	s_mov_b32 s53, -2
	ds_read_b128 v[160:163], v154
	ds_read_b128 v[164:167], v154 offset:1024
	ds_read_b128 v[168:171], v154 offset:2048
	ds_read_b128 v[172:175], v154 offset:3072
	ds_read_b128 v[176:179], v155
	ds_read_b128 v[180:183], v155 offset:1024
	ds_read_b128 v[184:187], v155 offset:2048
	ds_read_b128 v[188:191], v155 offset:3072
	s_add_u32 s0, s10, 0xfffc0080
	s_addc_u32 s1, s11, -1
	s_cmp_eq_u32 s53, 12
	s_cselect_b32 s39, s25, s1
	s_cselect_b32 s38, s49, s0
	s_cselect_b32 s1, s23, s52
	s_cselect_b32 s0, s50, s51
	v_lshl_add_u64 v[144:145], s[10:11], 0, v[136:137]
	s_add_i32 m0, s35, 0xc000
	ds_read_b128 v[192:195], v156
	ds_read_b128 v[196:199], v156 offset:1024
	ds_read_b128 v[200:203], v156 offset:2048
	ds_read_b128 v[204:207], v156 offset:3072
	ds_read_b128 v[208:211], v156 offset:4096
	ds_read_b128 v[212:215], v156 offset:5120
	ds_read_b128 v[216:219], v156 offset:6144
	ds_read_b128 v[220:223], v156 offset:7168
	global_load_lds_dwordx4 v[144:145], off
	v_lshl_add_u64 v[144:145], s[10:11], 0, v[138:139]
	s_add_i32 m0, s35, 0xe000
	s_nop 0
	global_load_lds_dwordx4 v[144:145], off
	s_waitcnt vmcnt(8)
	s_waitcnt lgkmcnt(0)
	s_barrier
	s_setprio 1
	s_waitcnt lgkmcnt(0)
	v_mfma_f32_16x16x32_bf16 v[124:127], v[160:163], v[192:195], 0
	v_mfma_f32_16x16x32_bf16 v[116:119], v[168:171], v[192:195], 0
	v_mfma_f32_16x16x32_bf16 v[108:111], v[160:163], v[200:203], 0
	v_mfma_f32_16x16x32_bf16 v[100:103], v[168:171], v[200:203], 0
	v_mfma_f32_16x16x32_bf16 v[92:95], v[160:163], v[208:211], 0
	v_mfma_f32_16x16x32_bf16 v[84:87], v[168:171], v[208:211], 0
	v_mfma_f32_16x16x32_bf16 v[76:79], v[160:163], v[216:219], 0
	v_mfma_f32_16x16x32_bf16 v[68:71], v[168:171], v[216:219], 0
	v_mfma_f32_16x16x32_bf16 v[124:127], v[164:167], v[196:199], v[124:127]
	v_mfma_f32_16x16x32_bf16 v[116:119], v[172:175], v[196:199], v[116:119]
	v_mfma_f32_16x16x32_bf16 v[108:111], v[164:167], v[204:207], v[108:111]
	v_mfma_f32_16x16x32_bf16 v[100:103], v[172:175], v[204:207], v[100:103]
	v_mfma_f32_16x16x32_bf16 v[92:95], v[164:167], v[212:215], v[92:95]
	v_mfma_f32_16x16x32_bf16 v[84:87], v[172:175], v[212:215], v[84:87]
	v_mfma_f32_16x16x32_bf16 v[76:79], v[164:167], v[220:223], v[76:79]
	v_mfma_f32_16x16x32_bf16 v[68:71], v[172:175], v[220:223], v[68:71]
	s_setprio 0
	s_setprio 1
	v_mfma_f32_16x16x32_bf16 v[120:123], v[176:179], v[192:195], 0
	v_mfma_f32_16x16x32_bf16 v[112:115], v[184:187], v[192:195], 0
	v_mfma_f32_16x16x32_bf16 v[104:107], v[176:179], v[200:203], 0
	v_mfma_f32_16x16x32_bf16 v[96:99], v[184:187], v[200:203], 0
	v_mfma_f32_16x16x32_bf16 v[88:91], v[176:179], v[208:211], 0
	v_mfma_f32_16x16x32_bf16 v[80:83], v[184:187], v[208:211], 0
	v_mfma_f32_16x16x32_bf16 v[72:75], v[176:179], v[216:219], 0
	v_mfma_f32_16x16x32_bf16 v[64:67], v[184:187], v[216:219], 0
	v_mfma_f32_16x16x32_bf16 v[120:123], v[180:183], v[196:199], v[120:123]
	v_mfma_f32_16x16x32_bf16 v[112:115], v[188:191], v[196:199], v[112:115]
	v_mfma_f32_16x16x32_bf16 v[104:107], v[180:183], v[204:207], v[104:107]
	v_mfma_f32_16x16x32_bf16 v[96:99], v[188:191], v[204:207], v[96:99]
	v_mfma_f32_16x16x32_bf16 v[88:91], v[180:183], v[212:215], v[88:91]
	v_mfma_f32_16x16x32_bf16 v[80:83], v[188:191], v[212:215], v[80:83]
	v_mfma_f32_16x16x32_bf16 v[72:75], v[180:183], v[220:223], v[72:75]
	v_mfma_f32_16x16x32_bf16 v[64:67], v[188:191], v[220:223], v[64:67]
	s_setprio 0
	s_barrier
	s_add_i32 s54, s3, s34
	v_lshl_add_u64 v[144:145], s[0:1], 0, v[130:131]
	s_mov_b32 m0, s54
	ds_read_b128 v[192:195], v156 offset:16384
	ds_read_b128 v[196:199], v156 offset:17408
	ds_read_b128 v[200:203], v156 offset:18432
	ds_read_b128 v[204:207], v156 offset:19456
	ds_read_b128 v[208:211], v156 offset:20480
	ds_read_b128 v[212:215], v156 offset:21504
	ds_read_b128 v[216:219], v156 offset:22528
	ds_read_b128 v[220:223], v156 offset:23552
	global_load_lds_dwordx4 v[144:145], off
	s_add_i32 m0, s54, 0x2000
	s_add_u32 s54, s0, 0x40000
	v_lshl_add_u64 v[224:225], s[0:1], 0, v[134:135]
	s_addc_u32 s55, s1, 0
	s_add_i32 s56, s46, s34
	global_load_lds_dwordx4 v[224:225], off
	v_lshl_add_u64 v[226:227], s[54:55], 0, v[130:131]
	s_mov_b32 m0, s56
	v_lshl_add_u64 v[228:229], s[38:39], 0, v[132:133]
	global_load_lds_dwordx4 v[226:227], off
	v_lshl_add_u64 v[226:227], s[54:55], 0, v[134:135]
	s_add_i32 m0, s56, 0x2000
	s_nop 0
	global_load_lds_dwordx4 v[226:227], off
	v_lshl_add_u64 v[226:227], s[38:39], 0, v[128:129]
	s_mov_b32 m0, s35
	s_nop 0
	global_load_lds_dwordx4 v[226:227], off
	s_mov_b32 m0, s36
	s_nop 0
	global_load_lds_dwordx4 v[228:229], off
	s_waitcnt vmcnt(8)
	s_waitcnt lgkmcnt(0)
	s_barrier
; #define PG8_STAGE(bufoff, gbase, voff) do { _Pragma("unroll") for (int _i = 0; _i < 2; ++_i) \
;         __builtin_amdgcn_global_load_lds((const unsigned*)((const char*)(gbase) + (voff)[_i]), (PG8_LAS unsigned*)(lds + (bufoff) + ldsw + _i * 8192), 16, 0, 0); } while (0)
; #define PG8_LDA(dst, b, h) do { _Pragma("unroll") for (int m = 0; m < 4; ++m) _Pragma("unroll") for (int k = 0; k < 2; ++k) dst[m][k] = *(const PG8_LAS bf16x8*)(lds + PG8_SA(b, h) + aoff + m * 2048 + k * 1024); } while (0)
; #define PG8_LDB(dst, b, h) do { _Pragma("unroll") for (int n = 0; n < 2; ++n) _Pragma("unroll") for (int k = 0; k < 2; ++k) dst[n][k] = *(const PG8_LAS bf16x8*)(lds + PG8_SB(b, h) + boff + n * 2048 + k * 1024); } while (0)
; #define PG8_MMA(ai, bj, At, Bt) do { __builtin_amdgcn_s_setprio(1); _Pragma("unroll") for (int m = 0; m < 4; ++m) _Pragma("unroll") for (int n = 0; n < 2; ++n) _Pragma("unroll") for (int k = 0; k < 2; ++k) \
;         acc[ai][bj][m][n] = __builtin_amdgcn_mfma_f32_16x16x32_bf16(Bt[n][k], At[m][k], acc[ai][bj][m][n], 0, 0, 0); __builtin_amdgcn_s_setprio(0); } while (0)
; #define PG8_WAIT_V(n) asm volatile("s_waitcnt vmcnt(" #n ")" ::: "memory")
; #define PG8_WAIT_L(n) asm volatile("s_waitcnt lgkmcnt(" #n ")" ::: "memory")
; #define PG8_BAR __builtin_amdgcn_s_barrier()
; #define PG8_SCHED __builtin_amdgcn_sched_barrier(0)
; template <class Epi, class Sched, bool ALIGN_EPI = false, bool SP2 = false>
; __device__ __forceinline__ void gemm_phase(PG8_LAS unsigned char* lds, const Gemm g, const Sched& S, const Epi& E, const int tid_in) {
;     ...
;             PG8_WAIT_V(8); PG8_WAIT_L(0); PG8_BAR; PG8_MMA(1, 0, At, B0); PG8_MMA(1, 1, At, B1); PG8_BAR; PG8_SCHED;
;             PG8_LDB(B0, 1, 0); PG8_LDB(B1, 1, 1); PG8_SCHED; PG8_LDA(At, 1, 0); PG8_STAGE(PG8_SA(0, 1), a2 + hstep, voffA);
;             PG8_WAIT_V(8); PG8_WAIT_L(0); PG8_BAR; PG8_MMA(0, 0, At, B0); PG8_MMA(0, 1, At, B1); PG8_BAR; PG8_SCHED;
	s_setprio 1
	s_waitcnt lgkmcnt(0)
	v_mfma_f32_16x16x32_bf16 v[60:63], v[160:163], v[192:195], 0
	v_mfma_f32_16x16x32_bf16 v[52:55], v[168:171], v[192:195], 0
	v_mfma_f32_16x16x32_bf16 v[44:47], v[160:163], v[200:203], 0
	v_mfma_f32_16x16x32_bf16 v[36:39], v[168:171], v[200:203], 0
	v_mfma_f32_16x16x32_bf16 v[28:31], v[160:163], v[208:211], 0
	v_mfma_f32_16x16x32_bf16 v[20:23], v[168:171], v[208:211], 0
	v_mfma_f32_16x16x32_bf16 v[12:15], v[160:163], v[216:219], 0
	v_mfma_f32_16x16x32_bf16 v[4:7], v[168:171], v[216:219], 0
	v_mfma_f32_16x16x32_bf16 v[60:63], v[164:167], v[196:199], v[60:63]
	v_mfma_f32_16x16x32_bf16 v[52:55], v[172:175], v[196:199], v[52:55]
	v_mfma_f32_16x16x32_bf16 v[44:47], v[164:167], v[204:207], v[44:47]
	v_mfma_f32_16x16x32_bf16 v[36:39], v[172:175], v[204:207], v[36:39]
	v_mfma_f32_16x16x32_bf16 v[28:31], v[164:167], v[212:215], v[28:31]
	v_mfma_f32_16x16x32_bf16 v[20:23], v[172:175], v[212:215], v[20:23]
	v_mfma_f32_16x16x32_bf16 v[12:15], v[164:167], v[220:223], v[12:15]
	v_mfma_f32_16x16x32_bf16 v[4:7], v[172:175], v[220:223], v[4:7]
	s_setprio 0
	s_setprio 1
	v_mfma_f32_16x16x32_bf16 v[56:59], v[176:179], v[192:195], 0
	v_mfma_f32_16x16x32_bf16 v[48:51], v[184:187], v[192:195], 0
	v_mfma_f32_16x16x32_bf16 v[40:43], v[176:179], v[200:203], 0
	v_mfma_f32_16x16x32_bf16 v[32:35], v[184:187], v[200:203], 0
	v_mfma_f32_16x16x32_bf16 v[24:27], v[176:179], v[208:211], 0
	v_mfma_f32_16x16x32_bf16 v[16:19], v[184:187], v[208:211], 0
	v_mfma_f32_16x16x32_bf16 v[8:11], v[176:179], v[216:219], 0
	v_mfma_f32_16x16x32_bf16 v[0:3], v[184:187], v[216:219], 0
	v_mfma_f32_16x16x32_bf16 v[56:59], v[180:183], v[196:199], v[56:59]
	v_mfma_f32_16x16x32_bf16 v[48:51], v[188:191], v[196:199], v[48:51]
	v_mfma_f32_16x16x32_bf16 v[40:43], v[180:183], v[204:207], v[40:43]
	v_mfma_f32_16x16x32_bf16 v[32:35], v[188:191], v[204:207], v[32:35]
	v_mfma_f32_16x16x32_bf16 v[24:27], v[180:183], v[212:215], v[24:27]
	v_mfma_f32_16x16x32_bf16 v[16:19], v[188:191], v[212:215], v[16:19]
	v_mfma_f32_16x16x32_bf16 v[8:11], v[180:183], v[220:223], v[8:11]
	v_mfma_f32_16x16x32_bf16 v[0:3], v[188:191], v[220:223], v[0:3]
	s_setprio 0
	s_barrier
	s_add_i32 s54, 0, 0x18000
	v_add_u32_e32 v159, s54, v148
	s_add_i32 s55, 0, 0x1c000
	ds_read_b128 v[160:163], v159
	ds_read_b128 v[164:167], v159 offset:1024
	ds_read_b128 v[168:171], v159 offset:2048
	ds_read_b128 v[172:175], v159 offset:3072
	v_add_u32_e32 v159, s55, v148
	ds_read_b128 v[176:179], v159
	ds_read_b128 v[180:183], v159 offset:1024
	ds_read_b128 v[184:187], v159 offset:2048
	ds_read_b128 v[188:191], v159 offset:3072
	s_add_u32 s38, s38, 0x40000
	s_addc_u32 s39, s39, 0
	s_mov_b32 m0, s37
	v_lshl_add_u64 v[230:231], s[38:39], 0, v[128:129]
	ds_read_b128 v[192:195], v156 offset:32768
	ds_read_b128 v[196:199], v156 offset:33792
	ds_read_b128 v[200:203], v156 offset:34816
	ds_read_b128 v[204:207], v156 offset:35840
	ds_read_b128 v[208:211], v156 offset:36864
	ds_read_b128 v[212:215], v156 offset:37888
	ds_read_b128 v[216:219], v156 offset:38912
	ds_read_b128 v[220:223], v156 offset:39936
	global_load_lds_dwordx4 v[230:231], off
	v_lshl_add_u64 v[230:231], s[38:39], 0, v[132:133]
	s_mov_b32 m0, s40
	s_nop 0
	global_load_lds_dwordx4 v[230:231], off
	s_waitcnt vmcnt(8)
	s_waitcnt lgkmcnt(0)
	s_barrier
	s_setprio 1
	s_waitcnt lgkmcnt(0)
	v_mfma_f32_16x16x32_bf16 v[124:127], v[160:163], v[192:195], v[124:127]
	v_mfma_f32_16x16x32_bf16 v[116:119], v[168:171], v[192:195], v[116:119]
	v_mfma_f32_16x16x32_bf16 v[108:111], v[160:163], v[200:203], v[108:111]
	v_mfma_f32_16x16x32_bf16 v[100:103], v[168:171], v[200:203], v[100:103]
	v_mfma_f32_16x16x32_bf16 v[92:95], v[160:163], v[208:211], v[92:95]
	v_mfma_f32_16x16x32_bf16 v[84:87], v[168:171], v[208:211], v[84:87]
	v_mfma_f32_16x16x32_bf16 v[76:79], v[160:163], v[216:219], v[76:79]
	v_mfma_f32_16x16x32_bf16 v[68:71], v[168:171], v[216:219], v[68:71]
	v_mfma_f32_16x16x32_bf16 v[124:127], v[164:167], v[196:199], v[124:127]
	v_mfma_f32_16x16x32_bf16 v[116:119], v[172:175], v[196:199], v[116:119]
	v_mfma_f32_16x16x32_bf16 v[108:111], v[164:167], v[204:207], v[108:111]
	v_mfma_f32_16x16x32_bf16 v[100:103], v[172:175], v[204:207], v[100:103]
	v_mfma_f32_16x16x32_bf16 v[92:95], v[164:167], v[212:215], v[92:95]
	v_mfma_f32_16x16x32_bf16 v[84:87], v[172:175], v[212:215], v[84:87]
	v_mfma_f32_16x16x32_bf16 v[76:79], v[164:167], v[220:223], v[76:79]
	v_mfma_f32_16x16x32_bf16 v[68:71], v[172:175], v[220:223], v[68:71]
	s_setprio 0
	s_setprio 1
	v_mfma_f32_16x16x32_bf16 v[120:123], v[176:179], v[192:195], v[120:123]
	v_mfma_f32_16x16x32_bf16 v[112:115], v[184:187], v[192:195], v[112:115]
	v_mfma_f32_16x16x32_bf16 v[104:107], v[176:179], v[200:203], v[104:107]
	v_mfma_f32_16x16x32_bf16 v[96:99], v[184:187], v[200:203], v[96:99]
	v_mfma_f32_16x16x32_bf16 v[88:91], v[176:179], v[208:211], v[88:91]
	v_mfma_f32_16x16x32_bf16 v[80:83], v[184:187], v[208:211], v[80:83]
	v_mfma_f32_16x16x32_bf16 v[72:75], v[176:179], v[216:219], v[72:75]
	v_mfma_f32_16x16x32_bf16 v[64:67], v[184:187], v[216:219], v[64:67]
	v_mfma_f32_16x16x32_bf16 v[120:123], v[180:183], v[196:199], v[120:123]
	v_mfma_f32_16x16x32_bf16 v[112:115], v[188:191], v[196:199], v[112:115]
	v_mfma_f32_16x16x32_bf16 v[104:107], v[180:183], v[204:207], v[104:107]
	v_mfma_f32_16x16x32_bf16 v[96:99], v[188:191], v[204:207], v[96:99]
	v_mfma_f32_16x16x32_bf16 v[88:91], v[180:183], v[212:215], v[88:91]
	v_mfma_f32_16x16x32_bf16 v[80:83], v[188:191], v[212:215], v[80:83]
	v_mfma_f32_16x16x32_bf16 v[72:75], v[180:183], v[220:223], v[72:75]
	v_mfma_f32_16x16x32_bf16 v[64:67], v[188:191], v[220:223], v[64:67]
	s_setprio 0
	s_barrier
; #define PG8_STAGE(bufoff, gbase, voff) do { _Pragma("unroll") for (int _i = 0; _i < 2; ++_i) \
;         __builtin_amdgcn_global_load_lds((const unsigned*)((const char*)(gbase) + (voff)[_i]), (PG8_LAS unsigned*)(lds + (bufoff) + ldsw + _i * 8192), 16, 0, 0); } while (0)
; #define PG8_LDA(dst, b, h) do { _Pragma("unroll") for (int m = 0; m < 4; ++m) _Pragma("unroll") for (int k = 0; k < 2; ++k) dst[m][k] = *(const PG8_LAS bf16x8*)(lds + PG8_SA(b, h) + aoff + m * 2048 + k * 1024); } while (0)
; #define PG8_MMA(ai, bj, At, Bt) do { __builtin_amdgcn_s_setprio(1); _Pragma("unroll") for (int m = 0; m < 4; ++m) _Pragma("unroll") for (int n = 0; n < 2; ++n) _Pragma("unroll") for (int k = 0; k < 2; ++k) \
;         acc[ai][bj][m][n] = __builtin_amdgcn_mfma_f32_16x16x32_bf16(Bt[n][k], At[m][k], acc[ai][bj][m][n], 0, 0, 0); __builtin_amdgcn_s_setprio(0); } while (0)
; #define PG8_WAIT_V(n) asm volatile("s_waitcnt vmcnt(" #n ")" ::: "memory")
; #define PG8_WAIT_L(n) asm volatile("s_waitcnt lgkmcnt(" #n ")" ::: "memory")
; #define PG8_BAR __builtin_amdgcn_s_barrier()
; #define PG8_SCHED __builtin_amdgcn_sched_barrier(0)
; template <class Epi, class Sched, bool ALIGN_EPI = false, bool SP2 = false>
; __device__ __forceinline__ void gemm_phase(PG8_LAS unsigned char* lds, const Gemm g, const Sched& S, const Epi& E, const int tid_in) {
;     ...
;             PG8_LDA(At, 1, 1); PG8_STAGE(PG8_SB(1, 0), b3, voffB); PG8_STAGE(PG8_SB(1, 1), b3 + hstep, voffB); PG8_STAGE(PG8_SA(1, 0), a3, voffA);
;             PG8_WAIT_V(8); PG8_WAIT_L(0); PG8_BAR; PG8_MMA(1, 0, At, B0); PG8_MMA(1, 1, At, B1); PG8_BAR; PG8_SCHED;
	s_add_i32 s38, s54, s34
	v_lshl_add_u64 v[144:145], v[144:145], 0, s[18:19]
	s_mov_b32 m0, s38
	ds_read_b128 v[192:195], v156 offset:49152
	ds_read_b128 v[196:199], v156 offset:50176
	ds_read_b128 v[200:203], v156 offset:51200
	ds_read_b128 v[204:207], v156 offset:52224
	ds_read_b128 v[208:211], v156 offset:53248
	ds_read_b128 v[212:215], v156 offset:54272
	ds_read_b128 v[216:219], v156 offset:55296
	ds_read_b128 v[220:223], v156 offset:56320
	global_load_lds_dwordx4 v[144:145], off
	s_add_i32 m0, s38, 0x2000
	s_add_u32 s0, s0, 0x40080
	v_lshl_add_u64 v[144:145], v[224:225], 0, s[18:19]
	s_addc_u32 s1, s1, 0
	s_add_i32 s38, s55, s34
	global_load_lds_dwordx4 v[144:145], off
	v_lshl_add_u64 v[144:145], s[0:1], 0, v[130:131]
	s_mov_b32 m0, s38
	s_nop 0
	global_load_lds_dwordx4 v[144:145], off
	v_lshl_add_u64 v[144:145], s[0:1], 0, v[134:135]
	s_add_i32 m0, s38, 0x2000
	s_nop 0
	global_load_lds_dwordx4 v[144:145], off
	v_lshl_add_u64 v[144:145], v[226:227], 0, s[18:19]
	s_mov_b32 m0, s43
	s_nop 0
	global_load_lds_dwordx4 v[144:145], off
	v_lshl_add_u64 v[144:145], v[228:229], 0, s[18:19]
	s_mov_b32 m0, s44
	s_nop 0
	global_load_lds_dwordx4 v[144:145], off
	s_waitcnt vmcnt(8)
	s_waitcnt lgkmcnt(0)
	s_barrier
	s_setprio 1
	s_waitcnt lgkmcnt(0)
	v_mfma_f32_16x16x32_bf16 v[60:63], v[160:163], v[192:195], v[60:63]
	v_mfma_f32_16x16x32_bf16 v[52:55], v[168:171], v[192:195], v[52:55]
	v_mfma_f32_16x16x32_bf16 v[44:47], v[160:163], v[200:203], v[44:47]
	v_mfma_f32_16x16x32_bf16 v[36:39], v[168:171], v[200:203], v[36:39]
	v_mfma_f32_16x16x32_bf16 v[28:31], v[160:163], v[208:211], v[28:31]
	v_mfma_f32_16x16x32_bf16 v[20:23], v[168:171], v[208:211], v[20:23]
	v_mfma_f32_16x16x32_bf16 v[12:15], v[160:163], v[216:219], v[12:15]
	v_mfma_f32_16x16x32_bf16 v[4:7], v[168:171], v[216:219], v[4:7]
	v_mfma_f32_16x16x32_bf16 v[60:63], v[164:167], v[196:199], v[60:63]
	v_mfma_f32_16x16x32_bf16 v[52:55], v[172:175], v[196:199], v[52:55]
	v_mfma_f32_16x16x32_bf16 v[44:47], v[164:167], v[204:207], v[44:47]
	v_mfma_f32_16x16x32_bf16 v[36:39], v[172:175], v[204:207], v[36:39]
	v_mfma_f32_16x16x32_bf16 v[28:31], v[164:167], v[212:215], v[28:31]
	v_mfma_f32_16x16x32_bf16 v[20:23], v[172:175], v[212:215], v[20:23]
	v_mfma_f32_16x16x32_bf16 v[12:15], v[164:167], v[220:223], v[12:15]
	v_mfma_f32_16x16x32_bf16 v[4:7], v[172:175], v[220:223], v[4:7]
	s_setprio 0
	s_setprio 1
	v_mfma_f32_16x16x32_bf16 v[56:59], v[176:179], v[192:195], v[56:59]
	v_mfma_f32_16x16x32_bf16 v[48:51], v[184:187], v[192:195], v[48:51]
	v_mfma_f32_16x16x32_bf16 v[40:43], v[176:179], v[200:203], v[40:43]
	v_mfma_f32_16x16x32_bf16 v[32:35], v[184:187], v[200:203], v[32:35]
	v_mfma_f32_16x16x32_bf16 v[24:27], v[176:179], v[208:211], v[24:27]
	v_mfma_f32_16x16x32_bf16 v[16:19], v[184:187], v[208:211], v[16:19]
	v_mfma_f32_16x16x32_bf16 v[8:11], v[176:179], v[216:219], v[8:11]
	v_mfma_f32_16x16x32_bf16 v[0:3], v[184:187], v[216:219], v[0:3]
	v_mfma_f32_16x16x32_bf16 v[56:59], v[180:183], v[196:199], v[56:59]
	v_mfma_f32_16x16x32_bf16 v[48:51], v[188:191], v[196:199], v[48:51]
	v_mfma_f32_16x16x32_bf16 v[40:43], v[180:183], v[204:207], v[40:43]
	v_mfma_f32_16x16x32_bf16 v[32:35], v[188:191], v[204:207], v[32:35]
	v_mfma_f32_16x16x32_bf16 v[24:27], v[180:183], v[212:215], v[24:27]
	v_mfma_f32_16x16x32_bf16 v[16:19], v[188:191], v[212:215], v[16:19]
	v_mfma_f32_16x16x32_bf16 v[8:11], v[180:183], v[220:223], v[8:11]
	v_mfma_f32_16x16x32_bf16 v[0:3], v[188:191], v[220:223], v[0:3]
	s_setprio 0
	s_barrier
	s_add_i32 s53, s53, 2
	s_add_u32 s10, s10, 0x100
	s_addc_u32 s11, s11, 0
	s_add_u32 s51, s51, 0x100
	s_addc_u32 s52, s52, 0
	s_cmp_gt_u32 s53, 13
	s_cbranch_scc0 .LBB0_3053
	s_branch .Lmy_kdone_7

; #define PG8_BAR __builtin_amdgcn_s_barrier()
; template <class Epi, class Sched, bool ALIGN_EPI = false, bool SP2 = false>
; __device__ __forceinline__ void gemm_phase(PG8_LAS unsigned char* lds, const Gemm g, const Sched& S, const Epi& E, const int tid_in) {
;     ...
;         if constexpr (ALIGN_EPI) { if (wr == 0) PG8_BAR; }
.Lmy_kdone_7:
	s_and_b64 vcc, exec, s[20:21]
	s_cbranch_vccz .LBB0_3056
	s_barrier

; #define PG8_STAGE(bufoff, gbase, voff) do { _Pragma("unroll") for (int _i = 0; _i < 2; ++_i) \
;         __builtin_amdgcn_global_load_lds((const unsigned*)((const char*)(gbase) + (voff)[_i]), (PG8_LAS unsigned*)(lds + (bufoff) + ldsw + _i * 8192), 16, 0, 0); } while (0)
; #define PG8_LDA(dst, b, h) do { _Pragma("unroll") for (int m = 0; m < 4; ++m) _Pragma("unroll") for (int k = 0; k < 2; ++k) dst[m][k] = *(const PG8_LAS bf16x8*)(lds + PG8_SA(b, h) + aoff + m * 2048 + k * 1024); } while (0)
; #define PG8_LDB(dst, b, h) do { _Pragma("unroll") for (int n = 0; n < 2; ++n) _Pragma("unroll") for (int k = 0; k < 2; ++k) dst[n][k] = *(const PG8_LAS bf16x8*)(lds + PG8_SB(b, h) + boff + n * 2048 + k * 1024); } while (0)
; #define PG8_MMA(ai, bj, At, Bt) do { __builtin_amdgcn_s_setprio(1); _Pragma("unroll") for (int m = 0; m < 4; ++m) _Pragma("unroll") for (int n = 0; n < 2; ++n) _Pragma("unroll") for (int k = 0; k < 2; ++k) \
;         acc[ai][bj][m][n] = __builtin_amdgcn_mfma_f32_16x16x32_bf16(Bt[n][k], At[m][k], acc[ai][bj][m][n], 0, 0, 0); __builtin_amdgcn_s_setprio(0); } while (0)
; #define PG8_WAIT_V(n) asm volatile("s_waitcnt vmcnt(" #n ")" ::: "memory")
; #define PG8_WAIT_L(n) asm volatile("s_waitcnt lgkmcnt(" #n ")" ::: "memory")
; #define PG8_BAR __builtin_amdgcn_s_barrier()
; template <class Epi, class Sched, bool ALIGN_EPI = false, bool SP2 = false>
; __device__ __forceinline__ void gemm_phase(PG8_LAS unsigned char* lds, const Gemm g, const Sched& S, const Epi& E, const int tid_in) {
;     ...
;         for (int t = 0; t < nt; t += 2) {
;             const bool last = (t == nt - 2);
;             const char* a1 = cA + (size_t)(t + 1) * kstep;
;             const char* a2 = last ? nA : cA + (size_t)(t + 2) * kstep; const char* b2 = last ? nB : cB + (size_t)(t + 2) * kstep;
;             const char* a3 = a2 + kstep; const char* b3 = b2 + kstep;
;             if (last && has_next) S.a_ready(nxt);
;             if constexpr (SP2) {
;             PG8_LDB(B0, 0, 0); PG8_LDB(B1, 0, 1); PG8_SCHED; PG8_LDA(At, 0, 0); PG8_STAGE(PG8_SA(1, 1), a1 + hstep, voffA);
;             PG8_WAIT_V(8); PG8_WAIT_L(0); PG8_BAR; PG8_MMA(0, 0, At, B0); PG8_MMA(0, 1, At, B1); PG8_BAR; PG8_SCHED;
;             PG8_LDA(At, 0, 1); PG8_STAGE(PG8_SB(0, 0), b2, voffB); PG8_STAGE(PG8_SB(0, 1), b2 + hstep, voffB); PG8_STAGE(PG8_SA(0, 0), a2, voffA);
.LBB0_3134:
	s_add_u32 s81, s0, 0x100
	v_mov_b32_e32 v0, 0
	s_addc_u32 s82, s1, 0
	s_mov_b32 s83, -2
	ds_read_b128 v[92:95], v207
	ds_read_b128 v[100:103], v207 offset:1024
	ds_read_b128 v[112:115], v207 offset:2048
	ds_read_b128 v[124:127], v207 offset:3072
	ds_read_b128 v[136:139], v208
	ds_read_b128 v[148:151], v208 offset:1024
	ds_read_b128 v[152:155], v208 offset:2048
	ds_read_b128 v[156:159], v208 offset:3072
	s_add_u32 s62, s60, 0x100
	s_addc_u32 s63, s61, 0
	s_cmp_eq_u32 s83, 40
	s_cselect_b32 s65, s9, s63
	s_cselect_b32 s64, s8, s62
	s_cselect_b32 s1, s59, s82
	s_cselect_b32 s0, s58, s81
	v_lshl_add_u64 v[214:215], s[60:61], 0, v[192:193]
	s_add_i32 m0, s4, 0xc000
	ds_read_b128 v[160:163], v209
	ds_read_b128 v[164:167], v209 offset:1024
	ds_read_b128 v[168:171], v209 offset:2048
	ds_read_b128 v[172:175], v209 offset:3072
	ds_read_b128 v[176:179], v209 offset:4096
	ds_read_b128 v[180:183], v209 offset:5120
	ds_read_b128 v[200:203], v209 offset:6144
	ds_read_b128 v[210:213], v209 offset:7168
	global_load_lds_dwordx4 v[214:215], off
	v_lshl_add_u64 v[214:215], s[60:61], 0, v[194:195]
	s_add_i32 m0, s4, 0xe000
	s_nop 0
	global_load_lds_dwordx4 v[214:215], off
	s_waitcnt vmcnt(8)
	s_waitcnt lgkmcnt(0)
	s_barrier
	s_setprio 1
	s_waitcnt lgkmcnt(0)
	v_mfma_f32_16x16x32_bf16 v[144:147], v[92:95], v[160:163], 0
	v_mfma_f32_16x16x32_bf16 v[140:143], v[112:115], v[160:163], 0
	v_mfma_f32_16x16x32_bf16 v[120:123], v[92:95], v[168:171], 0
	v_mfma_f32_16x16x32_bf16 v[116:119], v[112:115], v[168:171], 0
	v_mfma_f32_16x16x32_bf16 v[96:99], v[92:95], v[176:179], 0
	v_mfma_f32_16x16x32_bf16 v[88:91], v[112:115], v[176:179], 0
	v_mfma_f32_16x16x32_bf16 v[76:79], v[92:95], v[200:203], 0
	v_mfma_f32_16x16x32_bf16 v[72:75], v[112:115], v[200:203], 0
	v_mfma_f32_16x16x32_bf16 v[144:147], v[100:103], v[164:167], v[144:147]
	v_mfma_f32_16x16x32_bf16 v[140:143], v[124:127], v[164:167], v[140:143]
	v_mfma_f32_16x16x32_bf16 v[120:123], v[100:103], v[172:175], v[120:123]
	v_mfma_f32_16x16x32_bf16 v[116:119], v[124:127], v[172:175], v[116:119]
	v_mfma_f32_16x16x32_bf16 v[96:99], v[100:103], v[180:183], v[96:99]
	v_mfma_f32_16x16x32_bf16 v[88:91], v[124:127], v[180:183], v[88:91]
	v_mfma_f32_16x16x32_bf16 v[76:79], v[100:103], v[210:213], v[76:79]
	v_mfma_f32_16x16x32_bf16 v[72:75], v[124:127], v[210:213], v[72:75]
	s_setprio 0
	s_setprio 1
	v_mfma_f32_16x16x32_bf16 v[132:135], v[136:139], v[160:163], 0
	v_mfma_f32_16x16x32_bf16 v[128:131], v[152:155], v[160:163], 0
	v_mfma_f32_16x16x32_bf16 v[108:111], v[136:139], v[168:171], 0
	v_mfma_f32_16x16x32_bf16 v[104:107], v[152:155], v[168:171], 0
	v_mfma_f32_16x16x32_bf16 v[84:87], v[136:139], v[176:179], 0
	v_mfma_f32_16x16x32_bf16 v[80:83], v[152:155], v[176:179], 0
	v_mfma_f32_16x16x32_bf16 v[68:71], v[136:139], v[200:203], 0
	v_mfma_f32_16x16x32_bf16 v[64:67], v[152:155], v[200:203], 0
	v_mfma_f32_16x16x32_bf16 v[132:135], v[148:151], v[164:167], v[132:135]
	v_mfma_f32_16x16x32_bf16 v[128:131], v[156:159], v[164:167], v[128:131]
	v_mfma_f32_16x16x32_bf16 v[108:111], v[148:151], v[172:175], v[108:111]
	v_mfma_f32_16x16x32_bf16 v[104:107], v[156:159], v[172:175], v[104:107]
	v_mfma_f32_16x16x32_bf16 v[84:87], v[148:151], v[180:183], v[84:87]
	v_mfma_f32_16x16x32_bf16 v[80:83], v[156:159], v[180:183], v[80:83]
	v_mfma_f32_16x16x32_bf16 v[68:71], v[148:151], v[210:213], v[68:71]
	v_mfma_f32_16x16x32_bf16 v[64:67], v[156:159], v[210:213], v[64:67]
	s_setprio 0
	s_barrier
	s_add_i32 s60, s3, s2
	v_lshl_add_u64 v[214:215], s[0:1], 0, v[186:187]
	s_mov_b32 m0, s60
	ds_read_b128 v[160:163], v209 offset:16384
	ds_read_b128 v[164:167], v209 offset:17408
	ds_read_b128 v[168:171], v209 offset:18432
	ds_read_b128 v[172:175], v209 offset:19456
	ds_read_b128 v[176:179], v209 offset:20480
	ds_read_b128 v[180:183], v209 offset:21504
	ds_read_b128 v[200:203], v209 offset:22528
	ds_read_b128 v[210:213], v209 offset:23552
	global_load_lds_dwordx4 v[214:215], off
	s_add_i32 m0, s60, 0x2000
	s_add_u32 s60, s0, 0xb0000
	v_lshl_add_u64 v[216:217], s[0:1], 0, v[190:191]
	s_addc_u32 s61, s1, 0
	s_add_i32 s84, s69, s2
	global_load_lds_dwordx4 v[216:217], off
	v_lshl_add_u64 v[218:219], s[60:61], 0, v[186:187]
	s_mov_b32 m0, s84
	v_lshl_add_u64 v[220:221], s[64:65], 0, v[188:189]
	global_load_lds_dwordx4 v[218:219], off
	v_lshl_add_u64 v[218:219], s[60:61], 0, v[190:191]
	s_add_i32 m0, s84, 0x2000
	s_nop 0
	global_load_lds_dwordx4 v[218:219], off
	v_lshl_add_u64 v[218:219], s[64:65], 0, v[184:185]
	s_mov_b32 m0, s4
	s_nop 0
	global_load_lds_dwordx4 v[218:219], off
	s_mov_b32 m0, s5
	s_nop 0
	global_load_lds_dwordx4 v[220:221], off
	s_waitcnt vmcnt(8)
	s_waitcnt lgkmcnt(0)
	s_barrier
; #define PG8_STAGE(bufoff, gbase, voff) do { _Pragma("unroll") for (int _i = 0; _i < 2; ++_i) \
;         __builtin_amdgcn_global_load_lds((const unsigned*)((const char*)(gbase) + (voff)[_i]), (PG8_LAS unsigned*)(lds + (bufoff) + ldsw + _i * 8192), 16, 0, 0); } while (0)
; #define PG8_LDA(dst, b, h) do { _Pragma("unroll") for (int m = 0; m < 4; ++m) _Pragma("unroll") for (int k = 0; k < 2; ++k) dst[m][k] = *(const PG8_LAS bf16x8*)(lds + PG8_SA(b, h) + aoff + m * 2048 + k * 1024); } while (0)
; #define PG8_LDB(dst, b, h) do { _Pragma("unroll") for (int n = 0; n < 2; ++n) _Pragma("unroll") for (int k = 0; k < 2; ++k) dst[n][k] = *(const PG8_LAS bf16x8*)(lds + PG8_SB(b, h) + boff + n * 2048 + k * 1024); } while (0)
; #define PG8_MMA(ai, bj, At, Bt) do { __builtin_amdgcn_s_setprio(1); _Pragma("unroll") for (int m = 0; m < 4; ++m) _Pragma("unroll") for (int n = 0; n < 2; ++n) _Pragma("unroll") for (int k = 0; k < 2; ++k) \
;         acc[ai][bj][m][n] = __builtin_amdgcn_mfma_f32_16x16x32_bf16(Bt[n][k], At[m][k], acc[ai][bj][m][n], 0, 0, 0); __builtin_amdgcn_s_setprio(0); } while (0)
; #define PG8_WAIT_V(n) asm volatile("s_waitcnt vmcnt(" #n ")" ::: "memory")
; #define PG8_WAIT_L(n) asm volatile("s_waitcnt lgkmcnt(" #n ")" ::: "memory")
; #define PG8_BAR __builtin_amdgcn_s_barrier()
; #define PG8_SCHED __builtin_amdgcn_sched_barrier(0)
; template <class Epi, class Sched, bool ALIGN_EPI = false, bool SP2 = false>
; __device__ __forceinline__ void gemm_phase(PG8_LAS unsigned char* lds, const Gemm g, const Sched& S, const Epi& E, const int tid_in) {
;     ...
;             PG8_WAIT_V(8); PG8_WAIT_L(0); PG8_BAR; PG8_MMA(1, 0, At, B0); PG8_MMA(1, 1, At, B1); PG8_BAR; PG8_SCHED;
;             PG8_LDB(B0, 1, 0); PG8_LDB(B1, 1, 1); PG8_SCHED; PG8_LDA(At, 1, 0); PG8_STAGE(PG8_SA(0, 1), a2 + hstep, voffA);
;             PG8_WAIT_V(8); PG8_WAIT_L(0); PG8_BAR; PG8_MMA(0, 0, At, B0); PG8_MMA(0, 1, At, B1); PG8_BAR; PG8_SCHED;
	s_setprio 1
	s_waitcnt lgkmcnt(0)
	v_mfma_f32_16x16x32_bf16 v[60:63], v[92:95], v[160:163], 0
	v_mfma_f32_16x16x32_bf16 v[56:59], v[112:115], v[160:163], 0
	v_mfma_f32_16x16x32_bf16 v[44:47], v[92:95], v[168:171], 0
	v_mfma_f32_16x16x32_bf16 v[40:43], v[112:115], v[168:171], 0
	v_mfma_f32_16x16x32_bf16 v[28:31], v[92:95], v[176:179], 0
	v_mfma_f32_16x16x32_bf16 v[24:27], v[112:115], v[176:179], 0
	v_mfma_f32_16x16x32_bf16 v[12:15], v[92:95], v[200:203], 0
	v_mfma_f32_16x16x32_bf16 v[8:11], v[112:115], v[200:203], 0
	v_mfma_f32_16x16x32_bf16 v[60:63], v[100:103], v[164:167], v[60:63]
	v_mfma_f32_16x16x32_bf16 v[56:59], v[124:127], v[164:167], v[56:59]
	v_mfma_f32_16x16x32_bf16 v[44:47], v[100:103], v[172:175], v[44:47]
	v_mfma_f32_16x16x32_bf16 v[40:43], v[124:127], v[172:175], v[40:43]
	v_mfma_f32_16x16x32_bf16 v[28:31], v[100:103], v[180:183], v[28:31]
	v_mfma_f32_16x16x32_bf16 v[24:27], v[124:127], v[180:183], v[24:27]
	v_mfma_f32_16x16x32_bf16 v[12:15], v[100:103], v[210:213], v[12:15]
	v_mfma_f32_16x16x32_bf16 v[8:11], v[124:127], v[210:213], v[8:11]
	s_setprio 0
	s_setprio 1
	v_mfma_f32_16x16x32_bf16 v[52:55], v[136:139], v[160:163], 0
	v_mfma_f32_16x16x32_bf16 v[48:51], v[152:155], v[160:163], 0
	v_mfma_f32_16x16x32_bf16 v[36:39], v[136:139], v[168:171], 0
	v_mfma_f32_16x16x32_bf16 v[32:35], v[152:155], v[168:171], 0
	v_mfma_f32_16x16x32_bf16 v[20:23], v[136:139], v[176:179], 0
	v_mfma_f32_16x16x32_bf16 v[16:19], v[152:155], v[176:179], 0
	v_mfma_f32_16x16x32_bf16 v[4:7], v[136:139], v[200:203], 0
	v_mfma_f32_16x16x32_bf16 v[0:3], v[152:155], v[200:203], 0
	v_mfma_f32_16x16x32_bf16 v[52:55], v[148:151], v[164:167], v[52:55]
	v_mfma_f32_16x16x32_bf16 v[48:51], v[156:159], v[164:167], v[48:51]
	v_mfma_f32_16x16x32_bf16 v[36:39], v[148:151], v[172:175], v[36:39]
	v_mfma_f32_16x16x32_bf16 v[32:35], v[156:159], v[172:175], v[32:35]
	v_mfma_f32_16x16x32_bf16 v[20:23], v[148:151], v[180:183], v[20:23]
	v_mfma_f32_16x16x32_bf16 v[16:19], v[156:159], v[180:183], v[16:19]
	v_mfma_f32_16x16x32_bf16 v[4:7], v[148:151], v[210:213], v[4:7]
	v_mfma_f32_16x16x32_bf16 v[0:3], v[156:159], v[210:213], v[0:3]
	s_setprio 0
	s_barrier
	s_add_i32 s84, 0, 0x18000
	s_add_i32 s85, 0, 0x1c000
	v_add_u32_e32 v124, s84, v205
	v_add_u32_e32 v156, s85, v205
	ds_read_b128 v[92:95], v124
	ds_read_b128 v[100:103], v124 offset:1024
	ds_read_b128 v[112:115], v124 offset:2048
	ds_read_b128 v[124:127], v124 offset:3072
	ds_read_b128 v[136:139], v156
	ds_read_b128 v[148:151], v156 offset:1024
	ds_read_b128 v[152:155], v156 offset:2048
	ds_read_b128 v[156:159], v156 offset:3072
	s_add_u32 s60, s64, 0xb0000
	s_addc_u32 s61, s65, 0
	s_mov_b32 m0, s34
	v_lshl_add_u64 v[222:223], s[60:61], 0, v[184:185]
	ds_read_b128 v[160:163], v209 offset:32768
	ds_read_b128 v[164:167], v209 offset:33792
	ds_read_b128 v[168:171], v209 offset:34816
	ds_read_b128 v[172:175], v209 offset:35840
	ds_read_b128 v[176:179], v209 offset:36864
	ds_read_b128 v[180:183], v209 offset:37888
	ds_read_b128 v[200:203], v209 offset:38912
	ds_read_b128 v[210:213], v209 offset:39936
	global_load_lds_dwordx4 v[222:223], off
	v_lshl_add_u64 v[222:223], s[60:61], 0, v[188:189]
	s_mov_b32 m0, s35
	s_nop 0
	global_load_lds_dwordx4 v[222:223], off
	s_waitcnt vmcnt(8)
	s_waitcnt lgkmcnt(0)
	s_barrier
	s_setprio 1
	s_waitcnt lgkmcnt(0)
	v_mfma_f32_16x16x32_bf16 v[144:147], v[92:95], v[160:163], v[144:147]
	v_mfma_f32_16x16x32_bf16 v[140:143], v[112:115], v[160:163], v[140:143]
	v_mfma_f32_16x16x32_bf16 v[120:123], v[92:95], v[168:171], v[120:123]
	v_mfma_f32_16x16x32_bf16 v[116:119], v[112:115], v[168:171], v[116:119]
	v_mfma_f32_16x16x32_bf16 v[96:99], v[92:95], v[176:179], v[96:99]
	v_mfma_f32_16x16x32_bf16 v[88:91], v[112:115], v[176:179], v[88:91]
	v_mfma_f32_16x16x32_bf16 v[76:79], v[92:95], v[200:203], v[76:79]
	v_mfma_f32_16x16x32_bf16 v[72:75], v[112:115], v[200:203], v[72:75]
	v_mfma_f32_16x16x32_bf16 v[144:147], v[100:103], v[164:167], v[144:147]
	v_mfma_f32_16x16x32_bf16 v[140:143], v[124:127], v[164:167], v[140:143]
	v_mfma_f32_16x16x32_bf16 v[120:123], v[100:103], v[172:175], v[120:123]
	v_mfma_f32_16x16x32_bf16 v[116:119], v[124:127], v[172:175], v[116:119]
	v_mfma_f32_16x16x32_bf16 v[96:99], v[100:103], v[180:183], v[96:99]
	v_mfma_f32_16x16x32_bf16 v[88:91], v[124:127], v[180:183], v[88:91]
	v_mfma_f32_16x16x32_bf16 v[76:79], v[100:103], v[210:213], v[76:79]
	v_mfma_f32_16x16x32_bf16 v[72:75], v[124:127], v[210:213], v[72:75]
	s_setprio 0
	s_setprio 1
	v_mfma_f32_16x16x32_bf16 v[132:135], v[136:139], v[160:163], v[132:135]
	v_mfma_f32_16x16x32_bf16 v[128:131], v[152:155], v[160:163], v[128:131]
	v_mfma_f32_16x16x32_bf16 v[108:111], v[136:139], v[168:171], v[108:111]
	v_mfma_f32_16x16x32_bf16 v[104:107], v[152:155], v[168:171], v[104:107]
	v_mfma_f32_16x16x32_bf16 v[84:87], v[136:139], v[176:179], v[84:87]
	v_mfma_f32_16x16x32_bf16 v[80:83], v[152:155], v[176:179], v[80:83]
	v_mfma_f32_16x16x32_bf16 v[68:71], v[136:139], v[200:203], v[68:71]
	v_mfma_f32_16x16x32_bf16 v[64:67], v[152:155], v[200:203], v[64:67]
	v_mfma_f32_16x16x32_bf16 v[132:135], v[148:151], v[164:167], v[132:135]
	v_mfma_f32_16x16x32_bf16 v[128:131], v[156:159], v[164:167], v[128:131]
	v_mfma_f32_16x16x32_bf16 v[108:111], v[148:151], v[172:175], v[108:111]
	v_mfma_f32_16x16x32_bf16 v[104:107], v[156:159], v[172:175], v[104:107]
	v_mfma_f32_16x16x32_bf16 v[84:87], v[148:151], v[180:183], v[84:87]
	v_mfma_f32_16x16x32_bf16 v[80:83], v[156:159], v[180:183], v[80:83]
	v_mfma_f32_16x16x32_bf16 v[68:71], v[148:151], v[210:213], v[68:71]
	v_mfma_f32_16x16x32_bf16 v[64:67], v[156:159], v[210:213], v[64:67]
	s_setprio 0
	s_barrier
; #define PG8_STAGE(bufoff, gbase, voff) do { _Pragma("unroll") for (int _i = 0; _i < 2; ++_i) \
;         __builtin_amdgcn_global_load_lds((const unsigned*)((const char*)(gbase) + (voff)[_i]), (PG8_LAS unsigned*)(lds + (bufoff) + ldsw + _i * 8192), 16, 0, 0); } while (0)
; #define PG8_LDA(dst, b, h) do { _Pragma("unroll") for (int m = 0; m < 4; ++m) _Pragma("unroll") for (int k = 0; k < 2; ++k) dst[m][k] = *(const PG8_LAS bf16x8*)(lds + PG8_SA(b, h) + aoff + m * 2048 + k * 1024); } while (0)
; #define PG8_MMA(ai, bj, At, Bt) do { __builtin_amdgcn_s_setprio(1); _Pragma("unroll") for (int m = 0; m < 4; ++m) _Pragma("unroll") for (int n = 0; n < 2; ++n) _Pragma("unroll") for (int k = 0; k < 2; ++k) \
;         acc[ai][bj][m][n] = __builtin_amdgcn_mfma_f32_16x16x32_bf16(Bt[n][k], At[m][k], acc[ai][bj][m][n], 0, 0, 0); __builtin_amdgcn_s_setprio(0); } while (0)
; #define PG8_WAIT_V(n) asm volatile("s_waitcnt vmcnt(" #n ")" ::: "memory")
; #define PG8_WAIT_L(n) asm volatile("s_waitcnt lgkmcnt(" #n ")" ::: "memory")
; #define PG8_BAR __builtin_amdgcn_s_barrier()
; #define PG8_SCHED __builtin_amdgcn_sched_barrier(0)
; template <class Epi, class Sched, bool ALIGN_EPI = false, bool SP2 = false>
; __device__ __forceinline__ void gemm_phase(PG8_LAS unsigned char* lds, const Gemm g, const Sched& S, const Epi& E, const int tid_in) {
;     ...
;             PG8_LDA(At, 1, 1); PG8_STAGE(PG8_SB(1, 0), b3, voffB); PG8_STAGE(PG8_SB(1, 1), b3 + hstep, voffB); PG8_STAGE(PG8_SA(1, 0), a3, voffA);
;             PG8_WAIT_V(8); PG8_WAIT_L(0); PG8_BAR; PG8_MMA(1, 0, At, B0); PG8_MMA(1, 1, At, B1); PG8_BAR; PG8_SCHED;
	s_add_i32 s60, s84, s2
	v_lshl_add_u64 v[214:215], v[214:215], 0, s[26:27]
	s_mov_b32 m0, s60
	ds_read_b128 v[160:163], v209 offset:49152
	ds_read_b128 v[164:167], v209 offset:50176
	ds_read_b128 v[168:171], v209 offset:51200
	ds_read_b128 v[172:175], v209 offset:52224
	ds_read_b128 v[176:179], v209 offset:53248
	ds_read_b128 v[180:183], v209 offset:54272
	ds_read_b128 v[200:203], v209 offset:55296
	ds_read_b128 v[210:213], v209 offset:56320
	global_load_lds_dwordx4 v[214:215], off
	s_add_i32 m0, s60, 0x2000
	s_add_u32 s0, s0, 0xb0080
	v_lshl_add_u64 v[214:215], v[216:217], 0, s[26:27]
	s_addc_u32 s1, s1, 0
	s_add_i32 s60, s85, s2
	global_load_lds_dwordx4 v[214:215], off
	v_lshl_add_u64 v[214:215], s[0:1], 0, v[186:187]
	s_mov_b32 m0, s60
	s_nop 0
	global_load_lds_dwordx4 v[214:215], off
	v_lshl_add_u64 v[214:215], s[0:1], 0, v[190:191]
	s_add_i32 m0, s60, 0x2000
	s_nop 0
	global_load_lds_dwordx4 v[214:215], off
	v_lshl_add_u64 v[214:215], v[218:219], 0, s[26:27]
	s_mov_b32 m0, s37
	s_nop 0
	global_load_lds_dwordx4 v[214:215], off
	v_lshl_add_u64 v[214:215], v[220:221], 0, s[26:27]
	s_mov_b32 m0, s66
	s_nop 0
	global_load_lds_dwordx4 v[214:215], off
	s_waitcnt vmcnt(8)
	s_waitcnt lgkmcnt(0)
	s_barrier
	s_setprio 1
	s_waitcnt lgkmcnt(0)
	v_mfma_f32_16x16x32_bf16 v[60:63], v[92:95], v[160:163], v[60:63]
	v_mfma_f32_16x16x32_bf16 v[56:59], v[112:115], v[160:163], v[56:59]
	v_mfma_f32_16x16x32_bf16 v[44:47], v[92:95], v[168:171], v[44:47]
	v_mfma_f32_16x16x32_bf16 v[40:43], v[112:115], v[168:171], v[40:43]
	v_mfma_f32_16x16x32_bf16 v[28:31], v[92:95], v[176:179], v[28:31]
	v_mfma_f32_16x16x32_bf16 v[24:27], v[112:115], v[176:179], v[24:27]
	v_mfma_f32_16x16x32_bf16 v[12:15], v[92:95], v[200:203], v[12:15]
	v_mfma_f32_16x16x32_bf16 v[8:11], v[112:115], v[200:203], v[8:11]
	v_mfma_f32_16x16x32_bf16 v[60:63], v[100:103], v[164:167], v[60:63]
	v_mfma_f32_16x16x32_bf16 v[56:59], v[124:127], v[164:167], v[56:59]
	v_mfma_f32_16x16x32_bf16 v[44:47], v[100:103], v[172:175], v[44:47]
	v_mfma_f32_16x16x32_bf16 v[40:43], v[124:127], v[172:175], v[40:43]
	v_mfma_f32_16x16x32_bf16 v[28:31], v[100:103], v[180:183], v[28:31]
	v_mfma_f32_16x16x32_bf16 v[24:27], v[124:127], v[180:183], v[24:27]
	v_mfma_f32_16x16x32_bf16 v[12:15], v[100:103], v[210:213], v[12:15]
	v_mfma_f32_16x16x32_bf16 v[8:11], v[124:127], v[210:213], v[8:11]
	s_setprio 0
	s_setprio 1
	v_mfma_f32_16x16x32_bf16 v[52:55], v[136:139], v[160:163], v[52:55]
	v_mfma_f32_16x16x32_bf16 v[48:51], v[152:155], v[160:163], v[48:51]
	v_mfma_f32_16x16x32_bf16 v[36:39], v[136:139], v[168:171], v[36:39]
	v_mfma_f32_16x16x32_bf16 v[32:35], v[152:155], v[168:171], v[32:35]
	v_mfma_f32_16x16x32_bf16 v[20:23], v[136:139], v[176:179], v[20:23]
	v_mfma_f32_16x16x32_bf16 v[16:19], v[152:155], v[176:179], v[16:19]
	v_mfma_f32_16x16x32_bf16 v[4:7], v[136:139], v[200:203], v[4:7]
	v_mfma_f32_16x16x32_bf16 v[0:3], v[152:155], v[200:203], v[0:3]
	v_mfma_f32_16x16x32_bf16 v[52:55], v[148:151], v[164:167], v[52:55]
	v_mfma_f32_16x16x32_bf16 v[48:51], v[156:159], v[164:167], v[48:51]
	v_mfma_f32_16x16x32_bf16 v[36:39], v[148:151], v[172:175], v[36:39]
	v_mfma_f32_16x16x32_bf16 v[32:35], v[156:159], v[172:175], v[32:35]
	v_mfma_f32_16x16x32_bf16 v[20:23], v[148:151], v[180:183], v[20:23]
	v_mfma_f32_16x16x32_bf16 v[16:19], v[156:159], v[180:183], v[16:19]
	v_mfma_f32_16x16x32_bf16 v[4:7], v[148:151], v[210:213], v[4:7]
	v_mfma_f32_16x16x32_bf16 v[0:3], v[156:159], v[210:213], v[0:3]
	s_setprio 0
	s_barrier
	s_add_i32 s83, s83, 2
	s_add_u32 s81, s81, 0x100
	s_addc_u32 s82, s82, 0
	s_cmp_gt_u32 s83, 41
	s_mov_b64 s[60:61], s[62:63]
	s_cbranch_scc0 .LBB0_3135
	s_branch .Lmy_kdone_8

; __device__ __forceinline__ float bflo(unsigned w) { return __uint_as_float(w << 16); }
; __device__ __forceinline__ float bfhi(unsigned w) { return __uint_as_float(w & 0xffff0000u); }
; #define PHASE_IDS() const int tid_p = fresh_tid(wave_s); const int lane_p = tid_p & 63, wave_p = __builtin_amdgcn_readfirstlane(tid_p >> 6), gw_p = vcu * NWAVES + wave_p; (void)lane_p; (void)gw_p
; __global__ void __launch_bounds__(NWAVES * 64, 2) nsa_fwd(Args args) {
;     ...
;     { WS_PTRS(); PHASE_IDS();
;     for (int row = gw_p; row < MR; row += NGW) {
;         const float rs = pg8::row_rs(SS, row); const u32x2* xr = (const u32x2*)(XB + (size_t)row * D) + lane_p; const f32x4* gr = (const f32x4*)norm_final + lane_p;
;         f32x4* o = (f32x4*)(row < NP ? out + OFF_Y + (size_t)row * D : out + OFF_YS + (size_t)(row - NP) * D) + lane_p;
; #pragma unroll
;         for (int j = 0; j < 4; ++j) { const u32x2 xb = xr[64 * j]; const f32x4 xv = (f32x4){bflo(xb.x), bfhi(xb.x), bflo(xb.y), bfhi(xb.y)}; o[64 * j] = xv * rs * gr[64 * j]; }
;     } }
.LBB0_3223:
	s_mov_b32 s20, s14
	global_load_dwordx4 v[40:43], v[2:3], off
	global_load_dwordx4 v[44:47], v[2:3], off offset:1024
	global_load_dwordx4 v[48:51], v[2:3], off offset:2048
	global_load_dwordx4 v[52:55], v[2:3], off offset:3072
	s_add_u32 s0, s48, s2
	s_addc_u32 s1, s49, s3
	global_load_dwordx4 v[60:63], v0, s[0:1]
	global_load_dwordx4 v[64:67], v0, s[0:1] offset:16
	global_load_dwordx4 v[68:71], v0, s[0:1] offset:32
	global_load_dwordx4 v[72:75], v0, s[0:1] offset:48
	v_lshl_add_u64 v[30:31], s[48:49], 0, v[4:5]
	global_load_dwordx2 v[76:77], v[30:31], off offset:-1024
	global_load_dwordx2 v[78:79], v[30:31], off offset:-512
	global_load_dwordx2 v[80:81], v[30:31], off
	global_load_dwordx2 v[82:83], v[30:31], off offset:512
	s_add_u32 s2, s2, s4
	s_addc_u32 s3, s3, s5
	v_lshl_add_u64 v[4:5], v[4:5], 0, s[6:7]
	s_add_i32 s20, s20, s86
.Lmy_p13_loop:
	s_cmpk_gt_i32 s20, 0x407f
	s_cbranch_scc1 .Lmy_p13_lastA
	s_add_u32 s0, s48, s2
	s_addc_u32 s1, s49, s3
	global_load_dwordx4 v[84:87], v0, s[0:1]
	global_load_dwordx4 v[88:91], v0, s[0:1] offset:16
	global_load_dwordx4 v[92:95], v0, s[0:1] offset:32
	global_load_dwordx4 v[96:99], v0, s[0:1] offset:48
	v_lshl_add_u64 v[30:31], s[48:49], 0, v[4:5]
	global_load_dwordx2 v[100:101], v[30:31], off offset:-1024
	global_load_dwordx2 v[102:103], v[30:31], off offset:-512
	global_load_dwordx2 v[104:105], v[30:31], off
	global_load_dwordx2 v[106:107], v[30:31], off offset:512
	s_add_u32 s2, s2, s4
	s_addc_u32 s3, s3, s5
	v_lshl_add_u64 v[4:5], v[4:5], 0, s[6:7]
	s_add_i32 s20, s20, s86
	s_waitcnt vmcnt(8)
	s_add_i32 s10, s14, 0xffffc000
	s_lshl_b64 s[0:1], s[10:11], 12
	s_add_u32 s0, s15, s0
	s_addc_u32 s1, s16, s1
	s_cmpk_lt_i32 s14, 0x4000
	s_cselect_b32 s13, s18, s1
	s_cselect_b32 s12, s17, s0
	v_add_f32_e32 v108, v60, v61
	v_add_f32_e32 v109, v62, v63
	v_add_f32_e32 v110, v64, v65
	v_add_f32_e32 v111, v66, v67
	v_add_f32_e32 v112, v68, v69
	v_add_f32_e32 v113, v70, v71
	v_add_f32_e32 v114, v72, v73
	v_add_f32_e32 v115, v74, v75
	v_add_f32_e32 v108, v108, v109
	v_add_f32_e32 v110, v110, v111
	v_add_f32_e32 v112, v112, v113
	v_add_f32_e32 v114, v114, v115
	v_add_f32_e32 v108, v108, v110
	v_add_f32_e32 v108, v108, v112
	v_add_f32_e32 v9, v108, v114
	v_fmamk_f32 v9, v9, 0x3a800000, v6
	v_mul_f32_e32 v14, 0x4f800000, v9
	v_cmp_gt_f32_e32 vcc, s19, v9
	s_nop 1
	v_cndmask_b32_e32 v9, v9, v14, vcc
	v_sqrt_f32_e32 v14, v9
	s_nop 0
	v_add_u32_e32 v15, -1, v14
	v_add_u32_e32 v18, 1, v14
	v_fma_f32 v19, -v15, v14, v9
	v_fma_f32 v20, -v18, v14, v9
	v_cmp_ge_f32_e64 s[0:1], 0, v19
	s_nop 1
	v_cndmask_b32_e64 v14, v14, v15, s[0:1]
	v_cmp_lt_f32_e64 s[0:1], 0, v20
	s_nop 1
	v_cndmask_b32_e64 v14, v14, v18, s[0:1]
	v_mul_f32_e32 v15, 0x37800000, v14
	v_cndmask_b32_e32 v14, v14, v15, vcc
	v_cmp_class_f32_e32 vcc, v9, v7
	s_nop 1
	v_cndmask_b32_e32 v9, v14, v9, vcc
	v_div_scale_f32 v14, s[0:1], v9, v9, 1.0
	v_rcp_f32_e32 v18, v14
	v_div_scale_f32 v15, vcc, 1.0, v9, 1.0
	v_fma_f32 v19, -v14, v18, 1.0
	v_fmac_f32_e32 v18, v19, v18
	v_mul_f32_e32 v19, v15, v18
	v_fma_f32 v20, -v14, v19, v15
	v_fmac_f32_e32 v19, v20, v18
	v_fma_f32 v14, -v14, v19, v15
	s_nop 1
	v_div_fmas_f32 v14, v14, v18, v19
	v_div_fixup_f32 v14, v14, v9, 1.0
	v_lshlrev_b32_e32 v116, 16, v76
	v_and_b32_e32 v117, 0xffff0000, v76
	v_lshlrev_b32_e32 v118, 16, v77
	v_and_b32_e32 v119, 0xffff0000, v77
	v_mul_f32_e32 v116, v116, v14
	v_mul_f32_e32 v117, v117, v14
	v_mul_f32_e32 v118, v118, v14
	v_mul_f32_e32 v119, v119, v14
	v_mul_f32_e32 v120, v116, v40
	v_mul_f32_e32 v121, v117, v41
	v_mul_f32_e32 v122, v118, v42
	v_mul_f32_e32 v123, v119, v43
	global_store_dwordx4 v8, v[120:123], s[12:13]
	v_lshlrev_b32_e32 v116, 16, v78
	v_and_b32_e32 v117, 0xffff0000, v78
	v_lshlrev_b32_e32 v118, 16, v79
	v_and_b32_e32 v119, 0xffff0000, v79
	v_mul_f32_e32 v116, v116, v14
	v_mul_f32_e32 v117, v117, v14
	v_mul_f32_e32 v118, v118, v14
	v_mul_f32_e32 v119, v119, v14
	v_mul_f32_e32 v120, v116, v44
	v_mul_f32_e32 v121, v117, v45
	v_mul_f32_e32 v122, v118, v46
	v_mul_f32_e32 v123, v119, v47
	global_store_dwordx4 v8, v[120:123], s[12:13] offset:1024
	v_lshlrev_b32_e32 v116, 16, v80
	v_and_b32_e32 v117, 0xffff0000, v80
	v_lshlrev_b32_e32 v118, 16, v81
	v_and_b32_e32 v119, 0xffff0000, v81
	v_mul_f32_e32 v116, v116, v14
	v_mul_f32_e32 v117, v117, v14
	v_mul_f32_e32 v118, v118, v14
	v_mul_f32_e32 v119, v119, v14
	v_mul_f32_e32 v120, v116, v48
	v_mul_f32_e32 v121, v117, v49
	v_mul_f32_e32 v122, v118, v50
	v_mul_f32_e32 v123, v119, v51
	global_store_dwordx4 v8, v[120:123], s[12:13] offset:2048
	v_lshlrev_b32_e32 v116, 16, v82
	v_and_b32_e32 v117, 0xffff0000, v82
	v_lshlrev_b32_e32 v118, 16, v83
	v_and_b32_e32 v119, 0xffff0000, v83
	v_mul_f32_e32 v116, v116, v14
	v_mul_f32_e32 v117, v117, v14
	v_mul_f32_e32 v118, v118, v14
	v_mul_f32_e32 v119, v119, v14
	v_mul_f32_e32 v120, v116, v52
	v_mul_f32_e32 v121, v117, v53
	v_mul_f32_e32 v122, v118, v54
	v_mul_f32_e32 v123, v119, v55
	global_store_dwordx4 v8, v[120:123], s[12:13] offset:3072
	s_add_i32 s14, s14, s86
	s_add_u32 s17, s17, s8
	s_addc_u32 s18, s18, s9
	s_cmpk_gt_i32 s20, 0x407f
	s_cbranch_scc1 .Lmy_p13_lastB
; __device__ __forceinline__ float bflo(unsigned w) { return __uint_as_float(w << 16); }
; __device__ __forceinline__ float bfhi(unsigned w) { return __uint_as_float(w & 0xffff0000u); }
; __global__ void __launch_bounds__(NWAVES * 64, 2) nsa_fwd(Args args) {
;     ...
;     for (int row = gw_p; row < MR; row += NGW) {
;         const float rs = pg8::row_rs(SS, row); const u32x2* xr = (const u32x2*)(XB + (size_t)row * D) + lane_p; const f32x4* gr = (const f32x4*)norm_final + lane_p;
;         f32x4* o = (f32x4*)(row < NP ? out + OFF_Y + (size_t)row * D : out + OFF_YS + (size_t)(row - NP) * D) + lane_p;
; #pragma unroll
;         for (int j = 0; j < 4; ++j) { const u32x2 xb = xr[64 * j]; const f32x4 xv = (f32x4){bflo(xb.x), bfhi(xb.x), bflo(xb.y), bfhi(xb.y)}; o[64 * j] = xv * rs * gr[64 * j]; }
;     } }
	s_add_u32 s0, s48, s2
	s_addc_u32 s1, s49, s3
	global_load_dwordx4 v[60:63], v0, s[0:1]
	global_load_dwordx4 v[64:67], v0, s[0:1] offset:16
	global_load_dwordx4 v[68:71], v0, s[0:1] offset:32
	global_load_dwordx4 v[72:75], v0, s[0:1] offset:48
	v_lshl_add_u64 v[30:31], s[48:49], 0, v[4:5]
	global_load_dwordx2 v[76:77], v[30:31], off offset:-1024
	global_load_dwordx2 v[78:79], v[30:31], off offset:-512
	global_load_dwordx2 v[80:81], v[30:31], off
	global_load_dwordx2 v[82:83], v[30:31], off offset:512
	s_add_u32 s2, s2, s4
	s_addc_u32 s3, s3, s5
	v_lshl_add_u64 v[4:5], v[4:5], 0, s[6:7]
	s_add_i32 s20, s20, s86
	s_waitcnt vmcnt(8)
	s_add_i32 s10, s14, 0xffffc000
	s_lshl_b64 s[0:1], s[10:11], 12
	s_add_u32 s0, s15, s0
	s_addc_u32 s1, s16, s1
	s_cmpk_lt_i32 s14, 0x4000
	s_cselect_b32 s13, s18, s1
	s_cselect_b32 s12, s17, s0
	v_add_f32_e32 v108, v84, v85
	v_add_f32_e32 v109, v86, v87
	v_add_f32_e32 v110, v88, v89
	v_add_f32_e32 v111, v90, v91
	v_add_f32_e32 v112, v92, v93
	v_add_f32_e32 v113, v94, v95
	v_add_f32_e32 v114, v96, v97
	v_add_f32_e32 v115, v98, v99
	v_add_f32_e32 v108, v108, v109
	v_add_f32_e32 v110, v110, v111
	v_add_f32_e32 v112, v112, v113
	v_add_f32_e32 v114, v114, v115
	v_add_f32_e32 v108, v108, v110
	v_add_f32_e32 v108, v108, v112
	v_add_f32_e32 v9, v108, v114
	v_fmamk_f32 v9, v9, 0x3a800000, v6
	v_mul_f32_e32 v14, 0x4f800000, v9
	v_cmp_gt_f32_e32 vcc, s19, v9
	s_nop 1
	v_cndmask_b32_e32 v9, v9, v14, vcc
	v_sqrt_f32_e32 v14, v9
	s_nop 0
	v_add_u32_e32 v15, -1, v14
	v_add_u32_e32 v18, 1, v14
	v_fma_f32 v19, -v15, v14, v9
	v_fma_f32 v20, -v18, v14, v9
	v_cmp_ge_f32_e64 s[0:1], 0, v19
	s_nop 1
	v_cndmask_b32_e64 v14, v14, v15, s[0:1]
	v_cmp_lt_f32_e64 s[0:1], 0, v20
	s_nop 1
	v_cndmask_b32_e64 v14, v14, v18, s[0:1]
	v_mul_f32_e32 v15, 0x37800000, v14
	v_cndmask_b32_e32 v14, v14, v15, vcc
	v_cmp_class_f32_e32 vcc, v9, v7
	s_nop 1
	v_cndmask_b32_e32 v9, v14, v9, vcc
	v_div_scale_f32 v14, s[0:1], v9, v9, 1.0
	v_rcp_f32_e32 v18, v14
	v_div_scale_f32 v15, vcc, 1.0, v9, 1.0
	v_fma_f32 v19, -v14, v18, 1.0
	v_fmac_f32_e32 v18, v19, v18
	v_mul_f32_e32 v19, v15, v18
	v_fma_f32 v20, -v14, v19, v15
	v_fmac_f32_e32 v19, v20, v18
	v_fma_f32 v14, -v14, v19, v15
	s_nop 1
	v_div_fmas_f32 v14, v14, v18, v19
	v_div_fixup_f32 v14, v14, v9, 1.0
	v_lshlrev_b32_e32 v116, 16, v100
	v_and_b32_e32 v117, 0xffff0000, v100
	v_lshlrev_b32_e32 v118, 16, v101
	v_and_b32_e32 v119, 0xffff0000, v101
	v_mul_f32_e32 v116, v116, v14
	v_mul_f32_e32 v117, v117, v14
	v_mul_f32_e32 v118, v118, v14
	v_mul_f32_e32 v119, v119, v14
	v_mul_f32_e32 v120, v116, v40
	v_mul_f32_e32 v121, v117, v41
	v_mul_f32_e32 v122, v118, v42
	v_mul_f32_e32 v123, v119, v43
	global_store_dwordx4 v8, v[120:123], s[12:13]
	v_lshlrev_b32_e32 v116, 16, v102
	v_and_b32_e32 v117, 0xffff0000, v102
	v_lshlrev_b32_e32 v118, 16, v103
	v_and_b32_e32 v119, 0xffff0000, v103
	v_mul_f32_e32 v116, v116, v14
	v_mul_f32_e32 v117, v117, v14
	v_mul_f32_e32 v118, v118, v14
	v_mul_f32_e32 v119, v119, v14
	v_mul_f32_e32 v120, v116, v44
	v_mul_f32_e32 v121, v117, v45
	v_mul_f32_e32 v122, v118, v46
	v_mul_f32_e32 v123, v119, v47
	global_store_dwordx4 v8, v[120:123], s[12:13] offset:1024
	v_lshlrev_b32_e32 v116, 16, v104
	v_and_b32_e32 v117, 0xffff0000, v104
	v_lshlrev_b32_e32 v118, 16, v105
	v_and_b32_e32 v119, 0xffff0000, v105
	v_mul_f32_e32 v116, v116, v14
	v_mul_f32_e32 v117, v117, v14
	v_mul_f32_e32 v118, v118, v14
	v_mul_f32_e32 v119, v119, v14
	v_mul_f32_e32 v120, v116, v48
	v_mul_f32_e32 v121, v117, v49
	v_mul_f32_e32 v122, v118, v50
	v_mul_f32_e32 v123, v119, v51
	global_store_dwordx4 v8, v[120:123], s[12:13] offset:2048
	v_lshlrev_b32_e32 v116, 16, v106
	v_and_b32_e32 v117, 0xffff0000, v106
	v_lshlrev_b32_e32 v118, 16, v107
	v_and_b32_e32 v119, 0xffff0000, v107
	v_mul_f32_e32 v116, v116, v14
	v_mul_f32_e32 v117, v117, v14
	v_mul_f32_e32 v118, v118, v14
	v_mul_f32_e32 v119, v119, v14
	v_mul_f32_e32 v120, v116, v52
	v_mul_f32_e32 v121, v117, v53
	v_mul_f32_e32 v122, v118, v54
	v_mul_f32_e32 v123, v119, v55
	global_store_dwordx4 v8, v[120:123], s[12:13] offset:3072
	s_add_i32 s14, s14, s86
	s_add_u32 s17, s17, s8
	s_addc_u32 s18, s18, s9
	s_branch .Lmy_p13_loop
.Lmy_p13_lastA:
	s_waitcnt vmcnt(0)
; __device__ __forceinline__ float bflo(unsigned w) { return __uint_as_float(w << 16); }
; __device__ __forceinline__ float bfhi(unsigned w) { return __uint_as_float(w & 0xffff0000u); }
; __global__ void __launch_bounds__(NWAVES * 64, 2) nsa_fwd(Args args) {
;     ...
;     for (int row = gw_p; row < MR; row += NGW) {
;         const float rs = pg8::row_rs(SS, row); const u32x2* xr = (const u32x2*)(XB + (size_t)row * D) + lane_p; const f32x4* gr = (const f32x4*)norm_final + lane_p;
;         f32x4* o = (f32x4*)(row < NP ? out + OFF_Y + (size_t)row * D : out + OFF_YS + (size_t)(row - NP) * D) + lane_p;
; #pragma unroll
;         for (int j = 0; j < 4; ++j) { const u32x2 xb = xr[64 * j]; const f32x4 xv = (f32x4){bflo(xb.x), bfhi(xb.x), bflo(xb.y), bfhi(xb.y)}; o[64 * j] = xv * rs * gr[64 * j]; }
;     } }
	s_add_i32 s10, s14, 0xffffc000
	s_lshl_b64 s[0:1], s[10:11], 12
	s_add_u32 s0, s15, s0
	s_addc_u32 s1, s16, s1
	s_cmpk_lt_i32 s14, 0x4000
	s_cselect_b32 s13, s18, s1
	s_cselect_b32 s12, s17, s0
	v_add_f32_e32 v108, v60, v61
	v_add_f32_e32 v109, v62, v63
	v_add_f32_e32 v110, v64, v65
	v_add_f32_e32 v111, v66, v67
	v_add_f32_e32 v112, v68, v69
	v_add_f32_e32 v113, v70, v71
	v_add_f32_e32 v114, v72, v73
	v_add_f32_e32 v115, v74, v75
	v_add_f32_e32 v108, v108, v109
	v_add_f32_e32 v110, v110, v111
	v_add_f32_e32 v112, v112, v113
	v_add_f32_e32 v114, v114, v115
	v_add_f32_e32 v108, v108, v110
	v_add_f32_e32 v108, v108, v112
	v_add_f32_e32 v9, v108, v114
	v_fmamk_f32 v9, v9, 0x3a800000, v6
	v_mul_f32_e32 v14, 0x4f800000, v9
	v_cmp_gt_f32_e32 vcc, s19, v9
	s_nop 1
	v_cndmask_b32_e32 v9, v9, v14, vcc
	v_sqrt_f32_e32 v14, v9
	s_nop 0
	v_add_u32_e32 v15, -1, v14
	v_add_u32_e32 v18, 1, v14
	v_fma_f32 v19, -v15, v14, v9
	v_fma_f32 v20, -v18, v14, v9
	v_cmp_ge_f32_e64 s[0:1], 0, v19
	s_nop 1
	v_cndmask_b32_e64 v14, v14, v15, s[0:1]
	v_cmp_lt_f32_e64 s[0:1], 0, v20
	s_nop 1
	v_cndmask_b32_e64 v14, v14, v18, s[0:1]
	v_mul_f32_e32 v15, 0x37800000, v14
	v_cndmask_b32_e32 v14, v14, v15, vcc
	v_cmp_class_f32_e32 vcc, v9, v7
	s_nop 1
	v_cndmask_b32_e32 v9, v14, v9, vcc
	v_div_scale_f32 v14, s[0:1], v9, v9, 1.0
	v_rcp_f32_e32 v18, v14
	v_div_scale_f32 v15, vcc, 1.0, v9, 1.0
	v_fma_f32 v19, -v14, v18, 1.0
	v_fmac_f32_e32 v18, v19, v18
	v_mul_f32_e32 v19, v15, v18
	v_fma_f32 v20, -v14, v19, v15
	v_fmac_f32_e32 v19, v20, v18
	v_fma_f32 v14, -v14, v19, v15
	s_nop 1
	v_div_fmas_f32 v14, v14, v18, v19
	v_div_fixup_f32 v14, v14, v9, 1.0
	v_lshlrev_b32_e32 v116, 16, v76
	v_and_b32_e32 v117, 0xffff0000, v76
	v_lshlrev_b32_e32 v118, 16, v77
	v_and_b32_e32 v119, 0xffff0000, v77
	v_mul_f32_e32 v116, v116, v14
	v_mul_f32_e32 v117, v117, v14
	v_mul_f32_e32 v118, v118, v14
	v_mul_f32_e32 v119, v119, v14
	v_mul_f32_e32 v120, v116, v40
	v_mul_f32_e32 v121, v117, v41
	v_mul_f32_e32 v122, v118, v42
	v_mul_f32_e32 v123, v119, v43
	global_store_dwordx4 v8, v[120:123], s[12:13]
	v_lshlrev_b32_e32 v116, 16, v78
	v_and_b32_e32 v117, 0xffff0000, v78
	v_lshlrev_b32_e32 v118, 16, v79
	v_and_b32_e32 v119, 0xffff0000, v79
	v_mul_f32_e32 v116, v116, v14
	v_mul_f32_e32 v117, v117, v14
	v_mul_f32_e32 v118, v118, v14
	v_mul_f32_e32 v119, v119, v14
	v_mul_f32_e32 v120, v116, v44
	v_mul_f32_e32 v121, v117, v45
	v_mul_f32_e32 v122, v118, v46
	v_mul_f32_e32 v123, v119, v47
	global_store_dwordx4 v8, v[120:123], s[12:13] offset:1024
	v_lshlrev_b32_e32 v116, 16, v80
	v_and_b32_e32 v117, 0xffff0000, v80
	v_lshlrev_b32_e32 v118, 16, v81
	v_and_b32_e32 v119, 0xffff0000, v81
	v_mul_f32_e32 v116, v116, v14
	v_mul_f32_e32 v117, v117, v14
	v_mul_f32_e32 v118, v118, v14
	v_mul_f32_e32 v119, v119, v14
	v_mul_f32_e32 v120, v116, v48
	v_mul_f32_e32 v121, v117, v49
	v_mul_f32_e32 v122, v118, v50
	v_mul_f32_e32 v123, v119, v51
	global_store_dwordx4 v8, v[120:123], s[12:13] offset:2048
	v_lshlrev_b32_e32 v116, 16, v82
	v_and_b32_e32 v117, 0xffff0000, v82
	v_lshlrev_b32_e32 v118, 16, v83
	v_and_b32_e32 v119, 0xffff0000, v83
	v_mul_f32_e32 v116, v116, v14
	v_mul_f32_e32 v117, v117, v14
	v_mul_f32_e32 v118, v118, v14
	v_mul_f32_e32 v119, v119, v14
	v_mul_f32_e32 v120, v116, v52
	v_mul_f32_e32 v121, v117, v53
	v_mul_f32_e32 v122, v118, v54
	v_mul_f32_e32 v123, v119, v55
	global_store_dwordx4 v8, v[120:123], s[12:13] offset:3072
	s_add_i32 s14, s14, s86
	s_add_u32 s17, s17, s8
	s_addc_u32 s18, s18, s9
	s_endpgm
.Lmy_p13_lastB:
	s_waitcnt vmcnt(0)
	s_add_i32 s10, s14, 0xffffc000
	s_lshl_b64 s[0:1], s[10:11], 12
	s_add_u32 s0, s15, s0
	s_addc_u32 s1, s16, s1
	s_cmpk_lt_i32 s14, 0x4000
	s_cselect_b32 s13, s18, s1
	s_cselect_b32 s12, s17, s0
	v_add_f32_e32 v108, v84, v85
	v_add_f32_e32 v109, v86, v87
	v_add_f32_e32 v110, v88, v89
	v_add_f32_e32 v111, v90, v91
	v_add_f32_e32 v112, v92, v93
	v_add_f32_e32 v113, v94, v95
	v_add_f32_e32 v114, v96, v97
	v_add_f32_e32 v115, v98, v99
	v_add_f32_e32 v108, v108, v109
	v_add_f32_e32 v110, v110, v111
	v_add_f32_e32 v112, v112, v113
	v_add_f32_e32 v114, v114, v115
	v_add_f32_e32 v108, v108, v110
	v_add_f32_e32 v108, v108, v112
	v_add_f32_e32 v9, v108, v114
	v_fmamk_f32 v9, v9, 0x3a800000, v6
	v_mul_f32_e32 v14, 0x4f800000, v9
	v_cmp_gt_f32_e32 vcc, s19, v9
	s_nop 1
	v_cndmask_b32_e32 v9, v9, v14, vcc
	v_sqrt_f32_e32 v14, v9
	s_nop 0
	v_add_u32_e32 v15, -1, v14
	v_add_u32_e32 v18, 1, v14
	v_fma_f32 v19, -v15, v14, v9
	v_fma_f32 v20, -v18, v14, v9
	v_cmp_ge_f32_e64 s[0:1], 0, v19
	s_nop 1
	v_cndmask_b32_e64 v14, v14, v15, s[0:1]
	v_cmp_lt_f32_e64 s[0:1], 0, v20
	s_nop 1
	v_cndmask_b32_e64 v14, v14, v18, s[0:1]
	v_mul_f32_e32 v15, 0x37800000, v14
	v_cndmask_b32_e32 v14, v14, v15, vcc
	v_cmp_class_f32_e32 vcc, v9, v7
	s_nop 1
	v_cndmask_b32_e32 v9, v14, v9, vcc
	v_div_scale_f32 v14, s[0:1], v9, v9, 1.0
	v_rcp_f32_e32 v18, v14
	v_div_scale_f32 v15, vcc, 1.0, v9, 1.0
	v_fma_f32 v19, -v14, v18, 1.0
	v_fmac_f32_e32 v18, v19, v18
	v_mul_f32_e32 v19, v15, v18
	v_fma_f32 v20, -v14, v19, v15
	v_fmac_f32_e32 v19, v20, v18
	v_fma_f32 v14, -v14, v19, v15
	s_nop 1
	v_div_fmas_f32 v14, v14, v18, v19
	v_div_fixup_f32 v14, v14, v9, 1.0
	v_lshlrev_b32_e32 v116, 16, v100
	v_and_b32_e32 v117, 0xffff0000, v100
	v_lshlrev_b32_e32 v118, 16, v101
	v_and_b32_e32 v119, 0xffff0000, v101
	v_mul_f32_e32 v116, v116, v14
	v_mul_f32_e32 v117, v117, v14
	v_mul_f32_e32 v118, v118, v14
	v_mul_f32_e32 v119, v119, v14
	v_mul_f32_e32 v120, v116, v40
	v_mul_f32_e32 v121, v117, v41
	v_mul_f32_e32 v122, v118, v42
	v_mul_f32_e32 v123, v119, v43
	global_store_dwordx4 v8, v[120:123], s[12:13]
	v_lshlrev_b32_e32 v116, 16, v102
	v_and_b32_e32 v117, 0xffff0000, v102
	v_lshlrev_b32_e32 v118, 16, v103
	v_and_b32_e32 v119, 0xffff0000, v103
	v_mul_f32_e32 v116, v116, v14
	v_mul_f32_e32 v117, v117, v14
	v_mul_f32_e32 v118, v118, v14
	v_mul_f32_e32 v119, v119, v14
	v_mul_f32_e32 v120, v116, v44
	v_mul_f32_e32 v121, v117, v45
	v_mul_f32_e32 v122, v118, v46
	v_mul_f32_e32 v123, v119, v47
	global_store_dwordx4 v8, v[120:123], s[12:13] offset:1024
	v_lshlrev_b32_e32 v116, 16, v104
	v_and_b32_e32 v117, 0xffff0000, v104
	v_lshlrev_b32_e32 v118, 16, v105
	v_and_b32_e32 v119, 0xffff0000, v105
	v_mul_f32_e32 v116, v116, v14
	v_mul_f32_e32 v117, v117, v14
	v_mul_f32_e32 v118, v118, v14
	v_mul_f32_e32 v119, v119, v14
	v_mul_f32_e32 v120, v116, v48
	v_mul_f32_e32 v121, v117, v49
	v_mul_f32_e32 v122, v118, v50
	v_mul_f32_e32 v123, v119, v51
	global_store_dwordx4 v8, v[120:123], s[12:13] offset:2048
	v_lshlrev_b32_e32 v116, 16, v106
	v_and_b32_e32 v117, 0xffff0000, v106
	v_lshlrev_b32_e32 v118, 16, v107
	v_and_b32_e32 v119, 0xffff0000, v107
	v_mul_f32_e32 v116, v116, v14
	v_mul_f32_e32 v117, v117, v14
	v_mul_f32_e32 v118, v118, v14
	v_mul_f32_e32 v119, v119, v14
	v_mul_f32_e32 v120, v116, v52
	v_mul_f32_e32 v121, v117, v53
	v_mul_f32_e32 v122, v118, v54
	v_mul_f32_e32 v123, v119, v55
	global_store_dwordx4 v8, v[120:123], s[12:13] offset:3072
	s_add_i32 s14, s14, s86
	s_add_u32 s17, s17, s8
	s_addc_u32 s18, s18, s9
	s_endpgm
